# accumulator chains (k0,k1 back to back) in all 64 K-loop MFMA runs incl. QKV, sg_in and the peeled first iterations
# speedup vs baseline: 1.0087x; 1.0004x over previous
.LBB0_303:
	s_ashr_i32 s35, s34, 31
	s_lshl_b64 s[8:9], s[34:35], 20
	s_add_u32 s36, s53, s8
	s_addc_u32 s37, s54, s9
	s_and_b64 s[8:9], s[2:3], exec
	s_cselect_b32 s35, s37, s5
	s_cselect_b32 s52, s36, s4
	s_ashr_i32 s31, s30, 31
	s_lshl_b64 s[8:9], s[30:31], 20
	s_add_u32 s38, s55, s8
	s_addc_u32 s39, s56, s9
	s_and_b64 s[8:9], s[2:3], exec
	s_cselect_b32 s31, s39, s7
	s_cselect_b32 s77, s38, s6
	s_add_u32 s4, s4, 0x80080
	s_addc_u32 s5, s5, 0
	s_add_u32 s78, s6, 0x100
	s_addc_u32 s79, s7, 0
	s_mov_b32 s80, -2
	s_waitcnt lgkmcnt(0)
	ds_read_b128 v[2:5], v234
	ds_read_b128 v[6:9], v234 offset:1024
	ds_read_b128 v[10:13], v234 offset:2048
	ds_read_b128 v[14:17], v234 offset:3072
	ds_read_b128 v[18:21], v235
	ds_read_b128 v[22:25], v235 offset:1024
	ds_read_b128 v[26:29], v235 offset:2048
	ds_read_b128 v[30:33], v235 offset:3072
	s_add_u32 s6, s4, 0xfff80080
	s_addc_u32 s7, s5, -1
	s_cmp_eq_u32 s80, 28
	s_cselect_b32 s9, s35, s7
	s_cselect_b32 s8, s52, s6
	s_cselect_b32 s7, s31, s79
	s_cselect_b32 s6, s77, s78
	v_lshl_add_u64 v[214:215], s[4:5], 0, v[206:207]
	s_add_i32 m0, s43, 0xc000
	ds_read_b128 v[98:101], v236
	ds_read_b128 v[102:105], v236 offset:1024
	ds_read_b128 v[106:109], v236 offset:2048
	ds_read_b128 v[110:113], v236 offset:3072
	ds_read_b128 v[178:181], v236 offset:4096
	ds_read_b128 v[182:185], v236 offset:5120
	ds_read_b128 v[186:189], v236 offset:6144
	ds_read_b128 v[190:193], v236 offset:7168
	global_load_lds_dwordx4 v[214:215], off
	v_lshl_add_u64 v[214:215], s[4:5], 0, v[208:209]
	s_add_i32 m0, s43, 0xe000
	s_nop 0
	global_load_lds_dwordx4 v[214:215], off
	s_waitcnt vmcnt(8)
	s_waitcnt lgkmcnt(0)
	s_barrier
	s_waitcnt lgkmcnt(0)
	v_mfma_i32_16x16x64_i8 v[174:177], v[2:5], v[98:101], 0
	v_mfma_i32_16x16x64_i8 v[174:177], v[6:9], v[102:105], v[174:177]
	v_mfma_i32_16x16x64_i8 v[170:173], v[10:13], v[98:101], 0
	v_mfma_i32_16x16x64_i8 v[170:173], v[14:17], v[102:105], v[170:173]
	v_mfma_i32_16x16x64_i8 v[158:161], v[2:5], v[106:109], 0
	v_mfma_i32_16x16x64_i8 v[158:161], v[6:9], v[110:113], v[158:161]
	v_mfma_i32_16x16x64_i8 v[154:157], v[10:13], v[106:109], 0
	v_mfma_i32_16x16x64_i8 v[154:157], v[14:17], v[110:113], v[154:157]
	v_mfma_i32_16x16x64_i8 v[142:145], v[2:5], v[178:181], 0
	v_mfma_i32_16x16x64_i8 v[142:145], v[6:9], v[182:185], v[142:145]
	v_mfma_i32_16x16x64_i8 v[138:141], v[10:13], v[178:181], 0
	v_mfma_i32_16x16x64_i8 v[138:141], v[14:17], v[182:185], v[138:141]
	v_mfma_i32_16x16x64_i8 v[126:129], v[2:5], v[186:189], 0
	v_mfma_i32_16x16x64_i8 v[126:129], v[6:9], v[190:193], v[126:129]
	v_mfma_i32_16x16x64_i8 v[122:125], v[10:13], v[186:189], 0
	v_mfma_i32_16x16x64_i8 v[122:125], v[14:17], v[190:193], v[122:125]
	v_mfma_i32_16x16x64_i8 v[166:169], v[18:21], v[98:101], 0
	v_mfma_i32_16x16x64_i8 v[166:169], v[22:25], v[102:105], v[166:169]
	v_mfma_i32_16x16x64_i8 v[98:101], v[26:29], v[98:101], 0
	v_mfma_i32_16x16x64_i8 v[98:101], v[30:33], v[102:105], v[98:101]
	v_mfma_i32_16x16x64_i8 v[102:105], v[18:21], v[106:109], 0
	v_mfma_i32_16x16x64_i8 v[102:105], v[22:25], v[110:113], v[102:105]
	v_mfma_i32_16x16x64_i8 v[106:109], v[26:29], v[106:109], 0
	v_mfma_i32_16x16x64_i8 v[106:109], v[30:33], v[110:113], v[106:109]
	v_mfma_i32_16x16x64_i8 v[130:133], v[26:29], v[178:181], 0
	v_mfma_i32_16x16x64_i8 v[130:133], v[30:33], v[182:185], v[130:133]
	v_mfma_i32_16x16x64_i8 v[118:121], v[18:21], v[186:189], 0
	v_mfma_i32_16x16x64_i8 v[118:121], v[22:25], v[190:193], v[118:121]
	v_mfma_i32_16x16x64_i8 v[114:117], v[26:29], v[186:189], 0
	v_mfma_i32_16x16x64_i8 v[114:117], v[30:33], v[190:193], v[114:117]
	v_mfma_i32_16x16x64_i8 v[110:113], v[18:21], v[178:181], 0
	v_mfma_i32_16x16x64_i8 v[110:113], v[22:25], v[182:185], v[110:113]
	s_barrier
	s_add_i32 s81, s70, s41
	v_lshl_add_u64 v[226:227], s[6:7], 0, v[196:197]
	s_mov_b32 m0, s81
	ds_read_b128 v[134:137], v236 offset:16384
	ds_read_b128 v[146:149], v236 offset:17408
	ds_read_b128 v[150:153], v236 offset:18432
	ds_read_b128 v[162:165], v236 offset:19456
	ds_read_b128 v[178:181], v236 offset:20480
	ds_read_b128 v[182:185], v236 offset:21504
	ds_read_b128 v[186:189], v236 offset:22528
	ds_read_b128 v[190:193], v236 offset:23552
	global_load_lds_dwordx4 v[226:227], off
	s_add_i32 m0, s81, 0x2000
	s_add_u32 s82, s6, 0x80000
	v_lshl_add_u64 v[244:245], s[6:7], 0, v[198:199]
	s_addc_u32 s83, s7, 0
	s_add_i32 s81, s71, s41
	global_load_lds_dwordx4 v[244:245], off
	v_lshl_add_u64 v[214:215], s[82:83], 0, v[196:197]
	s_mov_b32 m0, s81
	v_lshl_add_u64 v[246:247], s[8:9], 0, v[196:197]
	global_load_lds_dwordx4 v[214:215], off
	v_lshl_add_u64 v[214:215], s[82:83], 0, v[198:199]
	s_add_i32 m0, s81, 0x2000
	v_lshl_add_u64 v[248:249], s[8:9], 0, v[198:199]
	global_load_lds_dwordx4 v[214:215], off
	s_mov_b32 m0, s43
	s_nop 0
	global_load_lds_dwordx4 v[246:247], off
	s_mov_b32 m0, s57
	s_nop 0
	global_load_lds_dwordx4 v[248:249], off
	s_waitcnt vmcnt(8)
	s_waitcnt lgkmcnt(0)
	s_barrier
	s_waitcnt lgkmcnt(0)
	v_mfma_i32_16x16x64_i8 v[94:97], v[2:5], v[134:137], 0
	v_mfma_i32_16x16x64_i8 v[94:97], v[6:9], v[146:149], v[94:97]
	v_mfma_i32_16x16x64_i8 v[90:93], v[10:13], v[134:137], 0
	v_mfma_i32_16x16x64_i8 v[90:93], v[14:17], v[146:149], v[90:93]
	v_mfma_i32_16x16x64_i8 v[78:81], v[2:5], v[150:153], 0
	v_mfma_i32_16x16x64_i8 v[78:81], v[6:9], v[162:165], v[78:81]
	v_mfma_i32_16x16x64_i8 v[74:77], v[10:13], v[150:153], 0
	v_mfma_i32_16x16x64_i8 v[74:77], v[14:17], v[162:165], v[74:77]
	v_mfma_i32_16x16x64_i8 v[62:65], v[2:5], v[178:181], 0
	v_mfma_i32_16x16x64_i8 v[62:65], v[6:9], v[182:185], v[62:65]
	v_mfma_i32_16x16x64_i8 v[58:61], v[10:13], v[178:181], 0
	v_mfma_i32_16x16x64_i8 v[58:61], v[14:17], v[182:185], v[58:61]
	v_mfma_i32_16x16x64_i8 v[2:5], v[2:5], v[186:189], 0
	v_mfma_i32_16x16x64_i8 v[2:5], v[6:9], v[190:193], v[2:5]
	v_mfma_i32_16x16x64_i8 v[6:9], v[10:13], v[186:189], 0
	v_mfma_i32_16x16x64_i8 v[6:9], v[14:17], v[190:193], v[6:9]
	v_mfma_i32_16x16x64_i8 v[42:45], v[18:21], v[150:153], 0
	v_mfma_i32_16x16x64_i8 v[70:73], v[22:25], v[162:165], v[42:45]
	v_mfma_i32_16x16x64_i8 v[42:45], v[26:29], v[150:153], 0
	v_mfma_i32_16x16x64_i8 v[66:69], v[30:33], v[162:165], v[42:45]
	v_mfma_i32_16x16x64_i8 v[42:45], v[18:21], v[178:181], 0
	v_mfma_i32_16x16x64_i8 v[54:57], v[22:25], v[182:185], v[42:45]
	v_mfma_i32_16x16x64_i8 v[10:13], v[18:21], v[134:137], 0
	v_mfma_i32_16x16x64_i8 v[10:13], v[22:25], v[146:149], v[10:13]
	v_mfma_i32_16x16x64_i8 v[42:45], v[26:29], v[178:181], 0
	v_mfma_i32_16x16x64_i8 v[50:53], v[30:33], v[182:185], v[42:45]
	v_mfma_i32_16x16x64_i8 v[18:21], v[18:21], v[186:189], 0
	v_mfma_i32_16x16x64_i8 v[18:21], v[22:25], v[190:193], v[18:21]
	v_mfma_i32_16x16x64_i8 v[14:17], v[26:29], v[134:137], 0
	v_mfma_i32_16x16x64_i8 v[14:17], v[30:33], v[146:149], v[14:17]
	v_mfma_i32_16x16x64_i8 v[22:25], v[26:29], v[186:189], 0
	v_mfma_i32_16x16x64_i8 v[22:25], v[30:33], v[190:193], v[22:25]
	s_barrier
	s_add_i32 s81, 0, 0x18000
	s_add_i32 s82, 0, 0x1c000
	v_add_u32_e32 v38, s81, v229
	v_add_u32_e32 v42, s82, v229
	ds_read_b128 v[26:29], v38
	ds_read_b128 v[30:33], v38 offset:1024
	ds_read_b128 v[34:37], v38 offset:2048
	ds_read_b128 v[38:41], v38 offset:3072
	ds_read_b128 v[178:181], v42
	ds_read_b128 v[182:185], v42 offset:1024
	ds_read_b128 v[186:189], v42 offset:2048
	ds_read_b128 v[190:193], v42 offset:3072
	s_add_u32 s8, s8, 0x80000
	s_addc_u32 s9, s9, 0
	s_mov_b32 m0, s60
	v_lshl_add_u64 v[134:135], s[8:9], 0, v[196:197]
	ds_read_b128 v[42:45], v236 offset:32768
	ds_read_b128 v[46:49], v236 offset:33792
	ds_read_b128 v[82:85], v236 offset:34816
	ds_read_b128 v[86:89], v236 offset:35840
	ds_read_b128 v[214:217], v236 offset:36864
	ds_read_b128 v[218:221], v236 offset:37888
	ds_read_b128 v[222:225], v236 offset:38912
	ds_read_b128 v[240:243], v236 offset:39936
	global_load_lds_dwordx4 v[134:135], off
	v_lshl_add_u64 v[134:135], s[8:9], 0, v[198:199]
	s_mov_b32 m0, s61
	s_nop 0
	global_load_lds_dwordx4 v[134:135], off
	s_waitcnt vmcnt(8)
	s_waitcnt lgkmcnt(0)
	s_barrier
	s_waitcnt lgkmcnt(0)
	v_mfma_i32_16x16x64_i8 v[134:137], v[26:29], v[42:45], v[174:177]
	v_mfma_i32_16x16x64_i8 v[174:177], v[30:33], v[46:49], v[134:137]
	v_mfma_i32_16x16x64_i8 v[134:137], v[34:37], v[42:45], v[170:173]
	v_mfma_i32_16x16x64_i8 v[170:173], v[38:41], v[46:49], v[134:137]
	v_mfma_i32_16x16x64_i8 v[134:137], v[26:29], v[82:85], v[158:161]
	v_mfma_i32_16x16x64_i8 v[158:161], v[30:33], v[86:89], v[134:137]
	v_mfma_i32_16x16x64_i8 v[134:137], v[34:37], v[82:85], v[154:157]
	v_mfma_i32_16x16x64_i8 v[154:157], v[38:41], v[86:89], v[134:137]
	v_mfma_i32_16x16x64_i8 v[134:137], v[26:29], v[214:217], v[142:145]
	v_mfma_i32_16x16x64_i8 v[142:145], v[30:33], v[218:221], v[134:137]
	v_mfma_i32_16x16x64_i8 v[134:137], v[34:37], v[214:217], v[138:141]
	v_mfma_i32_16x16x64_i8 v[138:141], v[38:41], v[218:221], v[134:137]
	v_mfma_i32_16x16x64_i8 v[126:129], v[26:29], v[222:225], v[126:129]
	v_mfma_i32_16x16x64_i8 v[126:129], v[30:33], v[240:243], v[126:129]
	v_mfma_i32_16x16x64_i8 v[122:125], v[34:37], v[222:225], v[122:125]
	v_mfma_i32_16x16x64_i8 v[122:125], v[38:41], v[240:243], v[122:125]
	v_mfma_i32_16x16x64_i8 v[134:137], v[178:181], v[42:45], v[166:169]
	v_mfma_i32_16x16x64_i8 v[166:169], v[182:185], v[46:49], v[134:137]
	v_mfma_i32_16x16x64_i8 v[42:45], v[186:189], v[42:45], v[98:101]
	v_mfma_i32_16x16x64_i8 v[162:165], v[190:193], v[46:49], v[42:45]
	v_mfma_i32_16x16x64_i8 v[42:45], v[178:181], v[82:85], v[102:105]
	v_mfma_i32_16x16x64_i8 v[150:153], v[182:185], v[86:89], v[42:45]
	v_mfma_i32_16x16x64_i8 v[42:45], v[186:189], v[82:85], v[106:109]
	v_mfma_i32_16x16x64_i8 v[146:149], v[190:193], v[86:89], v[42:45]
	v_mfma_i32_16x16x64_i8 v[42:45], v[178:181], v[214:217], v[110:113]
	v_mfma_i32_16x16x64_i8 v[134:137], v[182:185], v[218:221], v[42:45]
	v_mfma_i32_16x16x64_i8 v[42:45], v[186:189], v[214:217], v[130:133]
	v_mfma_i32_16x16x64_i8 v[130:133], v[190:193], v[218:221], v[42:45]
	v_mfma_i32_16x16x64_i8 v[42:45], v[178:181], v[222:225], v[118:121]
	v_mfma_i32_16x16x64_i8 v[118:121], v[182:185], v[240:243], v[42:45]
	v_mfma_i32_16x16x64_i8 v[42:45], v[186:189], v[222:225], v[114:117]
	v_mfma_i32_16x16x64_i8 v[114:117], v[190:193], v[240:243], v[42:45]
	s_barrier
	s_add_i32 s8, s81, s41
	s_nop 3
	v_lshl_add_u64 v[42:43], v[226:227], 0, s[24:25]
	s_mov_b32 m0, s8
	ds_read_b128 v[82:85], v236 offset:49152
	ds_read_b128 v[98:101], v236 offset:50176
	ds_read_b128 v[102:105], v236 offset:51200
	ds_read_b128 v[106:109], v236 offset:52224
	ds_read_b128 v[110:113], v236 offset:53248
	ds_read_b128 v[214:217], v236 offset:54272
	ds_read_b128 v[218:221], v236 offset:55296
	ds_read_b128 v[222:225], v236 offset:56320
	global_load_lds_dwordx4 v[42:43], off
	s_add_i32 m0, s8, 0x2000
	s_add_u32 s6, s6, 0x80080
	v_lshl_add_u64 v[42:43], v[244:245], 0, s[24:25]
	s_addc_u32 s7, s7, 0
	s_add_i32 s8, s82, s41
	global_load_lds_dwordx4 v[42:43], off
	v_lshl_add_u64 v[42:43], s[6:7], 0, v[196:197]
	s_mov_b32 m0, s8
	s_nop 0
	global_load_lds_dwordx4 v[42:43], off
	v_lshl_add_u64 v[42:43], s[6:7], 0, v[198:199]
	s_add_i32 m0, s8, 0x2000
	s_nop 0
	global_load_lds_dwordx4 v[42:43], off
	v_lshl_add_u64 v[42:43], v[246:247], 0, s[24:25]
	s_mov_b32 m0, s63
	s_nop 0
	global_load_lds_dwordx4 v[42:43], off
	v_lshl_add_u64 v[42:43], v[248:249], 0, s[24:25]
	s_mov_b32 m0, s64
	s_nop 0
	global_load_lds_dwordx4 v[42:43], off
	s_waitcnt vmcnt(8)
	s_waitcnt lgkmcnt(0)
	s_barrier
	s_waitcnt lgkmcnt(0)
	v_mfma_i32_16x16x64_i8 v[42:45], v[26:29], v[82:85], v[94:97]
	v_mfma_i32_16x16x64_i8 v[94:97], v[30:33], v[98:101], v[42:45]
	v_mfma_i32_16x16x64_i8 v[42:45], v[34:37], v[82:85], v[90:93]
	v_mfma_i32_16x16x64_i8 v[90:93], v[38:41], v[98:101], v[42:45]
	v_mfma_i32_16x16x64_i8 v[42:45], v[26:29], v[102:105], v[78:81]
	v_mfma_i32_16x16x64_i8 v[78:81], v[30:33], v[106:109], v[42:45]
	v_mfma_i32_16x16x64_i8 v[42:45], v[34:37], v[102:105], v[74:77]
	v_mfma_i32_16x16x64_i8 v[74:77], v[38:41], v[106:109], v[42:45]
	v_mfma_i32_16x16x64_i8 v[42:45], v[26:29], v[110:113], v[62:65]
	v_mfma_i32_16x16x64_i8 v[62:65], v[30:33], v[214:217], v[42:45]
	v_mfma_i32_16x16x64_i8 v[2:5], v[26:29], v[218:221], v[2:5]
	v_mfma_i32_16x16x64_i8 v[46:49], v[30:33], v[222:225], v[2:5]
	v_mfma_i32_16x16x64_i8 v[42:45], v[34:37], v[110:113], v[58:61]
	v_mfma_i32_16x16x64_i8 v[58:61], v[38:41], v[214:217], v[42:45]
	v_mfma_i32_16x16x64_i8 v[2:5], v[34:37], v[218:221], v[6:9]
	v_mfma_i32_16x16x64_i8 v[42:45], v[38:41], v[222:225], v[2:5]
	v_mfma_i32_16x16x64_i8 v[2:5], v[178:181], v[82:85], v[10:13]
	v_mfma_i32_16x16x64_i8 v[86:89], v[182:185], v[98:101], v[2:5]
	v_mfma_i32_16x16x64_i8 v[2:5], v[186:189], v[82:85], v[14:17]
	v_mfma_i32_16x16x64_i8 v[82:85], v[190:193], v[98:101], v[2:5]
	v_mfma_i32_16x16x64_i8 v[2:5], v[178:181], v[102:105], v[70:73]
	v_mfma_i32_16x16x64_i8 v[70:73], v[182:185], v[106:109], v[2:5]
	v_mfma_i32_16x16x64_i8 v[2:5], v[186:189], v[102:105], v[66:69]
	v_mfma_i32_16x16x64_i8 v[66:69], v[190:193], v[106:109], v[2:5]
	v_mfma_i32_16x16x64_i8 v[2:5], v[178:181], v[110:113], v[54:57]
	v_mfma_i32_16x16x64_i8 v[54:57], v[182:185], v[214:217], v[2:5]
	v_mfma_i32_16x16x64_i8 v[2:5], v[186:189], v[110:113], v[50:53]
	v_mfma_i32_16x16x64_i8 v[50:53], v[190:193], v[214:217], v[2:5]
	v_mfma_i32_16x16x64_i8 v[2:5], v[178:181], v[218:221], v[18:21]
	v_mfma_i32_16x16x64_i8 v[38:41], v[182:185], v[222:225], v[2:5]
	v_mfma_i32_16x16x64_i8 v[2:5], v[186:189], v[218:221], v[22:25]
	v_mfma_i32_16x16x64_i8 v[34:37], v[190:193], v[222:225], v[2:5]
	s_barrier
	s_add_i32 s80, s80, 2
	s_add_u32 s4, s4, 0x100
	s_addc_u32 s5, s5, 0
	s_add_u32 s78, s78, 0x100
	s_addc_u32 s79, s79, 0
	s_cmp_gt_u32 s80, 29
.LBB0_304:
	s_waitcnt lgkmcnt(0)
	ds_read_b128 v[2:5], v234
	ds_read_b128 v[6:9], v234 offset:1024
	ds_read_b128 v[10:13], v234 offset:2048
	ds_read_b128 v[14:17], v234 offset:3072
	ds_read_b128 v[18:21], v235
	ds_read_b128 v[22:25], v235 offset:1024
	ds_read_b128 v[26:29], v235 offset:2048
	ds_read_b128 v[30:33], v235 offset:3072
	s_add_u32 s6, s4, 0xfff80080
	s_addc_u32 s7, s5, -1
	s_cmp_eq_u32 s80, 28
	s_cselect_b32 s9, s35, s7
	s_cselect_b32 s8, s52, s6
	s_cselect_b32 s7, s31, s79
	s_cselect_b32 s6, s77, s78
	v_lshl_add_u64 v[214:215], s[4:5], 0, v[206:207]
	s_add_i32 m0, s43, 0xc000
	ds_read_b128 v[98:101], v236
	ds_read_b128 v[102:105], v236 offset:1024
	ds_read_b128 v[106:109], v236 offset:2048
	ds_read_b128 v[110:113], v236 offset:3072
	ds_read_b128 v[178:181], v236 offset:4096
	ds_read_b128 v[182:185], v236 offset:5120
	ds_read_b128 v[186:189], v236 offset:6144
	ds_read_b128 v[190:193], v236 offset:7168
	global_load_lds_dwordx4 v[214:215], off
	v_lshl_add_u64 v[214:215], s[4:5], 0, v[208:209]
	s_add_i32 m0, s43, 0xe000
	s_nop 0
	global_load_lds_dwordx4 v[214:215], off
	s_waitcnt vmcnt(8)
	s_waitcnt lgkmcnt(0)
	s_barrier
	s_waitcnt lgkmcnt(0)
	v_mfma_i32_16x16x64_i8 v[174:177], v[2:5], v[98:101], v[174:177]
	v_mfma_i32_16x16x64_i8 v[174:177], v[6:9], v[102:105], v[174:177]
	v_mfma_i32_16x16x64_i8 v[170:173], v[10:13], v[98:101], v[170:173]
	v_mfma_i32_16x16x64_i8 v[170:173], v[14:17], v[102:105], v[170:173]
	v_mfma_i32_16x16x64_i8 v[158:161], v[2:5], v[106:109], v[158:161]
	v_mfma_i32_16x16x64_i8 v[158:161], v[6:9], v[110:113], v[158:161]
	v_mfma_i32_16x16x64_i8 v[154:157], v[10:13], v[106:109], v[154:157]
	v_mfma_i32_16x16x64_i8 v[154:157], v[14:17], v[110:113], v[154:157]
	v_mfma_i32_16x16x64_i8 v[142:145], v[2:5], v[178:181], v[142:145]
	v_mfma_i32_16x16x64_i8 v[142:145], v[6:9], v[182:185], v[142:145]
	v_mfma_i32_16x16x64_i8 v[138:141], v[10:13], v[178:181], v[138:141]
	v_mfma_i32_16x16x64_i8 v[138:141], v[14:17], v[182:185], v[138:141]
	v_mfma_i32_16x16x64_i8 v[126:129], v[2:5], v[186:189], v[126:129]
	v_mfma_i32_16x16x64_i8 v[126:129], v[6:9], v[190:193], v[126:129]
	v_mfma_i32_16x16x64_i8 v[122:125], v[10:13], v[186:189], v[122:125]
	v_mfma_i32_16x16x64_i8 v[122:125], v[14:17], v[190:193], v[122:125]
	v_mfma_i32_16x16x64_i8 v[166:169], v[18:21], v[98:101], v[166:169]
	v_mfma_i32_16x16x64_i8 v[166:169], v[22:25], v[102:105], v[166:169]
	v_mfma_i32_16x16x64_i8 v[98:101], v[26:29], v[98:101], v[162:165]
	v_mfma_i32_16x16x64_i8 v[98:101], v[30:33], v[102:105], v[98:101]
	v_mfma_i32_16x16x64_i8 v[102:105], v[18:21], v[106:109], v[150:153]
	v_mfma_i32_16x16x64_i8 v[102:105], v[22:25], v[110:113], v[102:105]
	v_mfma_i32_16x16x64_i8 v[106:109], v[26:29], v[106:109], v[146:149]
	v_mfma_i32_16x16x64_i8 v[106:109], v[30:33], v[110:113], v[106:109]
	v_mfma_i32_16x16x64_i8 v[130:133], v[26:29], v[178:181], v[130:133]
	v_mfma_i32_16x16x64_i8 v[130:133], v[30:33], v[182:185], v[130:133]
	v_mfma_i32_16x16x64_i8 v[118:121], v[18:21], v[186:189], v[118:121]
	v_mfma_i32_16x16x64_i8 v[118:121], v[22:25], v[190:193], v[118:121]
	v_mfma_i32_16x16x64_i8 v[114:117], v[26:29], v[186:189], v[114:117]
	v_mfma_i32_16x16x64_i8 v[114:117], v[30:33], v[190:193], v[114:117]
	v_mfma_i32_16x16x64_i8 v[110:113], v[18:21], v[178:181], v[134:137]
	v_mfma_i32_16x16x64_i8 v[110:113], v[22:25], v[182:185], v[110:113]
	s_barrier
	s_add_i32 s81, s70, s41
	v_lshl_add_u64 v[226:227], s[6:7], 0, v[196:197]
	s_mov_b32 m0, s81
	ds_read_b128 v[134:137], v236 offset:16384
	ds_read_b128 v[146:149], v236 offset:17408
	ds_read_b128 v[150:153], v236 offset:18432
	ds_read_b128 v[162:165], v236 offset:19456
	ds_read_b128 v[178:181], v236 offset:20480
	ds_read_b128 v[182:185], v236 offset:21504
	ds_read_b128 v[186:189], v236 offset:22528
	ds_read_b128 v[190:193], v236 offset:23552
	global_load_lds_dwordx4 v[226:227], off
	s_add_i32 m0, s81, 0x2000
	s_add_u32 s82, s6, 0x80000
	v_lshl_add_u64 v[244:245], s[6:7], 0, v[198:199]
	s_addc_u32 s83, s7, 0
	s_add_i32 s81, s71, s41
	global_load_lds_dwordx4 v[244:245], off
	v_lshl_add_u64 v[214:215], s[82:83], 0, v[196:197]
	s_mov_b32 m0, s81
	v_lshl_add_u64 v[246:247], s[8:9], 0, v[196:197]
	global_load_lds_dwordx4 v[214:215], off
	v_lshl_add_u64 v[214:215], s[82:83], 0, v[198:199]
	s_add_i32 m0, s81, 0x2000
	v_lshl_add_u64 v[248:249], s[8:9], 0, v[198:199]
	global_load_lds_dwordx4 v[214:215], off
	s_mov_b32 m0, s43
	s_nop 0
	global_load_lds_dwordx4 v[246:247], off
	s_mov_b32 m0, s57
	s_nop 0
	global_load_lds_dwordx4 v[248:249], off
	s_waitcnt vmcnt(8)
	s_waitcnt lgkmcnt(0)
	s_barrier
	s_waitcnt lgkmcnt(0)
	v_mfma_i32_16x16x64_i8 v[94:97], v[2:5], v[134:137], v[94:97]
	v_mfma_i32_16x16x64_i8 v[94:97], v[6:9], v[146:149], v[94:97]
	v_mfma_i32_16x16x64_i8 v[90:93], v[10:13], v[134:137], v[90:93]
	v_mfma_i32_16x16x64_i8 v[90:93], v[14:17], v[146:149], v[90:93]
	v_mfma_i32_16x16x64_i8 v[78:81], v[2:5], v[150:153], v[78:81]
	v_mfma_i32_16x16x64_i8 v[78:81], v[6:9], v[162:165], v[78:81]
	v_mfma_i32_16x16x64_i8 v[74:77], v[10:13], v[150:153], v[74:77]
	v_mfma_i32_16x16x64_i8 v[74:77], v[14:17], v[162:165], v[74:77]
	v_mfma_i32_16x16x64_i8 v[62:65], v[2:5], v[178:181], v[62:65]
	v_mfma_i32_16x16x64_i8 v[62:65], v[6:9], v[182:185], v[62:65]
	v_mfma_i32_16x16x64_i8 v[58:61], v[10:13], v[178:181], v[58:61]
	v_mfma_i32_16x16x64_i8 v[58:61], v[14:17], v[182:185], v[58:61]
	v_mfma_i32_16x16x64_i8 v[2:5], v[2:5], v[186:189], v[46:49]
	v_mfma_i32_16x16x64_i8 v[2:5], v[6:9], v[190:193], v[2:5]
	v_mfma_i32_16x16x64_i8 v[6:9], v[10:13], v[186:189], v[42:45]
	v_mfma_i32_16x16x64_i8 v[6:9], v[14:17], v[190:193], v[6:9]
	v_mfma_i32_16x16x64_i8 v[42:45], v[18:21], v[150:153], v[70:73]
	v_mfma_i32_16x16x64_i8 v[70:73], v[22:25], v[162:165], v[42:45]
	v_mfma_i32_16x16x64_i8 v[42:45], v[26:29], v[150:153], v[66:69]
	v_mfma_i32_16x16x64_i8 v[66:69], v[30:33], v[162:165], v[42:45]
	v_mfma_i32_16x16x64_i8 v[42:45], v[18:21], v[178:181], v[54:57]
	v_mfma_i32_16x16x64_i8 v[54:57], v[22:25], v[182:185], v[42:45]
	v_mfma_i32_16x16x64_i8 v[10:13], v[18:21], v[134:137], v[86:89]
	v_mfma_i32_16x16x64_i8 v[10:13], v[22:25], v[146:149], v[10:13]
	v_mfma_i32_16x16x64_i8 v[42:45], v[26:29], v[178:181], v[50:53]
	v_mfma_i32_16x16x64_i8 v[50:53], v[30:33], v[182:185], v[42:45]
	v_mfma_i32_16x16x64_i8 v[18:21], v[18:21], v[186:189], v[38:41]
	v_mfma_i32_16x16x64_i8 v[18:21], v[22:25], v[190:193], v[18:21]
	v_mfma_i32_16x16x64_i8 v[14:17], v[26:29], v[134:137], v[82:85]
	v_mfma_i32_16x16x64_i8 v[14:17], v[30:33], v[146:149], v[14:17]
	v_mfma_i32_16x16x64_i8 v[22:25], v[26:29], v[186:189], v[34:37]
	v_mfma_i32_16x16x64_i8 v[22:25], v[30:33], v[190:193], v[22:25]
	s_barrier
	s_add_i32 s81, 0, 0x18000
	s_add_i32 s82, 0, 0x1c000
	v_add_u32_e32 v38, s81, v229
	v_add_u32_e32 v42, s82, v229
	ds_read_b128 v[26:29], v38
	ds_read_b128 v[30:33], v38 offset:1024
	ds_read_b128 v[34:37], v38 offset:2048
	ds_read_b128 v[38:41], v38 offset:3072
	ds_read_b128 v[178:181], v42
	ds_read_b128 v[182:185], v42 offset:1024
	ds_read_b128 v[186:189], v42 offset:2048
	ds_read_b128 v[190:193], v42 offset:3072
	s_add_u32 s8, s8, 0x80000
	s_addc_u32 s9, s9, 0
	s_mov_b32 m0, s60
	v_lshl_add_u64 v[134:135], s[8:9], 0, v[196:197]
	ds_read_b128 v[42:45], v236 offset:32768
	ds_read_b128 v[46:49], v236 offset:33792
	ds_read_b128 v[82:85], v236 offset:34816
	ds_read_b128 v[86:89], v236 offset:35840
	ds_read_b128 v[214:217], v236 offset:36864
	ds_read_b128 v[218:221], v236 offset:37888
	ds_read_b128 v[222:225], v236 offset:38912
	ds_read_b128 v[240:243], v236 offset:39936
	global_load_lds_dwordx4 v[134:135], off
	v_lshl_add_u64 v[134:135], s[8:9], 0, v[198:199]
	s_mov_b32 m0, s61
	s_nop 0
	global_load_lds_dwordx4 v[134:135], off
	s_waitcnt vmcnt(8)
	s_waitcnt lgkmcnt(0)
	s_barrier
	s_waitcnt lgkmcnt(0)
	v_mfma_i32_16x16x64_i8 v[134:137], v[26:29], v[42:45], v[174:177]
	v_mfma_i32_16x16x64_i8 v[174:177], v[30:33], v[46:49], v[134:137]
	v_mfma_i32_16x16x64_i8 v[134:137], v[34:37], v[42:45], v[170:173]
	v_mfma_i32_16x16x64_i8 v[170:173], v[38:41], v[46:49], v[134:137]
	v_mfma_i32_16x16x64_i8 v[134:137], v[26:29], v[82:85], v[158:161]
	v_mfma_i32_16x16x64_i8 v[158:161], v[30:33], v[86:89], v[134:137]
	v_mfma_i32_16x16x64_i8 v[134:137], v[34:37], v[82:85], v[154:157]
	v_mfma_i32_16x16x64_i8 v[154:157], v[38:41], v[86:89], v[134:137]
	v_mfma_i32_16x16x64_i8 v[134:137], v[26:29], v[214:217], v[142:145]
	v_mfma_i32_16x16x64_i8 v[142:145], v[30:33], v[218:221], v[134:137]
	v_mfma_i32_16x16x64_i8 v[134:137], v[34:37], v[214:217], v[138:141]
	v_mfma_i32_16x16x64_i8 v[138:141], v[38:41], v[218:221], v[134:137]
	v_mfma_i32_16x16x64_i8 v[126:129], v[26:29], v[222:225], v[126:129]
	v_mfma_i32_16x16x64_i8 v[126:129], v[30:33], v[240:243], v[126:129]
	v_mfma_i32_16x16x64_i8 v[122:125], v[34:37], v[222:225], v[122:125]
	v_mfma_i32_16x16x64_i8 v[122:125], v[38:41], v[240:243], v[122:125]
	v_mfma_i32_16x16x64_i8 v[134:137], v[178:181], v[42:45], v[166:169]
	v_mfma_i32_16x16x64_i8 v[166:169], v[182:185], v[46:49], v[134:137]
	v_mfma_i32_16x16x64_i8 v[42:45], v[186:189], v[42:45], v[98:101]
	v_mfma_i32_16x16x64_i8 v[162:165], v[190:193], v[46:49], v[42:45]
	v_mfma_i32_16x16x64_i8 v[42:45], v[178:181], v[82:85], v[102:105]
	v_mfma_i32_16x16x64_i8 v[150:153], v[182:185], v[86:89], v[42:45]
	v_mfma_i32_16x16x64_i8 v[42:45], v[186:189], v[82:85], v[106:109]
	v_mfma_i32_16x16x64_i8 v[146:149], v[190:193], v[86:89], v[42:45]
	v_mfma_i32_16x16x64_i8 v[42:45], v[178:181], v[214:217], v[110:113]
	v_mfma_i32_16x16x64_i8 v[134:137], v[182:185], v[218:221], v[42:45]
	v_mfma_i32_16x16x64_i8 v[42:45], v[186:189], v[214:217], v[130:133]
	v_mfma_i32_16x16x64_i8 v[130:133], v[190:193], v[218:221], v[42:45]
	v_mfma_i32_16x16x64_i8 v[42:45], v[178:181], v[222:225], v[118:121]
	v_mfma_i32_16x16x64_i8 v[118:121], v[182:185], v[240:243], v[42:45]
	v_mfma_i32_16x16x64_i8 v[42:45], v[186:189], v[222:225], v[114:117]
	v_mfma_i32_16x16x64_i8 v[114:117], v[190:193], v[240:243], v[42:45]
	s_barrier
	s_add_i32 s8, s81, s41
	s_nop 3
	v_lshl_add_u64 v[42:43], v[226:227], 0, s[24:25]
	s_mov_b32 m0, s8
	ds_read_b128 v[82:85], v236 offset:49152
	ds_read_b128 v[98:101], v236 offset:50176
	ds_read_b128 v[102:105], v236 offset:51200
	ds_read_b128 v[106:109], v236 offset:52224
	ds_read_b128 v[110:113], v236 offset:53248
	ds_read_b128 v[214:217], v236 offset:54272
	ds_read_b128 v[218:221], v236 offset:55296
	ds_read_b128 v[222:225], v236 offset:56320
	global_load_lds_dwordx4 v[42:43], off
	s_add_i32 m0, s8, 0x2000
	s_add_u32 s6, s6, 0x80080
	v_lshl_add_u64 v[42:43], v[244:245], 0, s[24:25]
	s_addc_u32 s7, s7, 0
	s_add_i32 s8, s82, s41
	global_load_lds_dwordx4 v[42:43], off
	v_lshl_add_u64 v[42:43], s[6:7], 0, v[196:197]
	s_mov_b32 m0, s8
	s_nop 0
	global_load_lds_dwordx4 v[42:43], off
	v_lshl_add_u64 v[42:43], s[6:7], 0, v[198:199]
	s_add_i32 m0, s8, 0x2000
	s_nop 0
	global_load_lds_dwordx4 v[42:43], off
	v_lshl_add_u64 v[42:43], v[246:247], 0, s[24:25]
	s_mov_b32 m0, s63
	s_nop 0
	global_load_lds_dwordx4 v[42:43], off
	v_lshl_add_u64 v[42:43], v[248:249], 0, s[24:25]
	s_mov_b32 m0, s64
	s_nop 0
	global_load_lds_dwordx4 v[42:43], off
	s_waitcnt vmcnt(8)
	s_waitcnt lgkmcnt(0)
	s_barrier
	s_waitcnt lgkmcnt(0)
	v_mfma_i32_16x16x64_i8 v[42:45], v[26:29], v[82:85], v[94:97]
	v_mfma_i32_16x16x64_i8 v[94:97], v[30:33], v[98:101], v[42:45]
	v_mfma_i32_16x16x64_i8 v[42:45], v[34:37], v[82:85], v[90:93]
	v_mfma_i32_16x16x64_i8 v[90:93], v[38:41], v[98:101], v[42:45]
	v_mfma_i32_16x16x64_i8 v[42:45], v[26:29], v[102:105], v[78:81]
	v_mfma_i32_16x16x64_i8 v[78:81], v[30:33], v[106:109], v[42:45]
	v_mfma_i32_16x16x64_i8 v[42:45], v[34:37], v[102:105], v[74:77]
	v_mfma_i32_16x16x64_i8 v[74:77], v[38:41], v[106:109], v[42:45]
	v_mfma_i32_16x16x64_i8 v[42:45], v[26:29], v[110:113], v[62:65]
	v_mfma_i32_16x16x64_i8 v[62:65], v[30:33], v[214:217], v[42:45]
	v_mfma_i32_16x16x64_i8 v[2:5], v[26:29], v[218:221], v[2:5]
	v_mfma_i32_16x16x64_i8 v[46:49], v[30:33], v[222:225], v[2:5]
	v_mfma_i32_16x16x64_i8 v[42:45], v[34:37], v[110:113], v[58:61]
	v_mfma_i32_16x16x64_i8 v[58:61], v[38:41], v[214:217], v[42:45]
	v_mfma_i32_16x16x64_i8 v[2:5], v[34:37], v[218:221], v[6:9]
	v_mfma_i32_16x16x64_i8 v[42:45], v[38:41], v[222:225], v[2:5]
	v_mfma_i32_16x16x64_i8 v[2:5], v[178:181], v[82:85], v[10:13]
	v_mfma_i32_16x16x64_i8 v[86:89], v[182:185], v[98:101], v[2:5]
	v_mfma_i32_16x16x64_i8 v[2:5], v[186:189], v[82:85], v[14:17]
	v_mfma_i32_16x16x64_i8 v[82:85], v[190:193], v[98:101], v[2:5]
	v_mfma_i32_16x16x64_i8 v[2:5], v[178:181], v[102:105], v[70:73]
	v_mfma_i32_16x16x64_i8 v[70:73], v[182:185], v[106:109], v[2:5]
	v_mfma_i32_16x16x64_i8 v[2:5], v[186:189], v[102:105], v[66:69]
	v_mfma_i32_16x16x64_i8 v[66:69], v[190:193], v[106:109], v[2:5]
	v_mfma_i32_16x16x64_i8 v[2:5], v[178:181], v[110:113], v[54:57]
	v_mfma_i32_16x16x64_i8 v[54:57], v[182:185], v[214:217], v[2:5]
	v_mfma_i32_16x16x64_i8 v[2:5], v[186:189], v[110:113], v[50:53]
	v_mfma_i32_16x16x64_i8 v[50:53], v[190:193], v[214:217], v[2:5]
	v_mfma_i32_16x16x64_i8 v[2:5], v[178:181], v[218:221], v[18:21]
	v_mfma_i32_16x16x64_i8 v[38:41], v[182:185], v[222:225], v[2:5]
	v_mfma_i32_16x16x64_i8 v[2:5], v[186:189], v[218:221], v[22:25]
	v_mfma_i32_16x16x64_i8 v[34:37], v[190:193], v[222:225], v[2:5]
	s_barrier
	s_add_i32 s80, s80, 2
	s_add_u32 s4, s4, 0x100
	s_addc_u32 s5, s5, 0
	s_add_u32 s78, s78, 0x100
	s_addc_u32 s79, s79, 0
	s_cmp_gt_u32 s80, 29
	s_cbranch_scc0 .LBB0_304
	s_and_b64 vcc, exec, s[12:13]
	s_cbranch_vccz .LBB0_307
	s_barrier

.LBB0_1231:
	s_ashr_i32 s23, s22, 31
	s_lshl_b64 s[24:25], s[22:23], 20
	s_add_u32 s24, s17, s24
	s_addc_u32 s25, s36, s25
	s_and_b64 s[26:27], s[0:1], exec
	s_cselect_b32 s23, s25, s29
	s_cselect_b32 s66, s24, s28
	s_ashr_i32 s15, s14, 31
	s_lshl_b64 s[26:27], s[14:15], 20
	s_add_u32 s26, s37, s26
	s_addc_u32 s27, s38, s27
	s_and_b64 s[34:35], s[0:1], exec
	s_cselect_b32 s15, s27, s31
	s_cselect_b32 s67, s26, s30
	s_add_u32 s28, s28, 0x80080
	s_addc_u32 s29, s29, 0
	s_add_u32 s68, s30, 0x100
	s_addc_u32 s69, s31, 0
	s_mov_b32 s70, -2
	ds_read_b128 v[106:109], v197
	ds_read_b128 v[114:117], v197 offset:1024
	ds_read_b128 v[122:125], v197 offset:2048
	ds_read_b128 v[130:133], v197 offset:3072
	ds_read_b128 v[146:149], v201
	ds_read_b128 v[150:153], v201 offset:1024
	ds_read_b128 v[154:157], v201 offset:2048
	ds_read_b128 v[158:161], v201 offset:3072
	s_add_u32 s30, s28, 0xfff80080
	s_addc_u32 s31, s29, -1
	s_cmp_eq_u32 s70, 28
	s_cselect_b32 s35, s23, s31
	s_cselect_b32 s34, s66, s30
	s_cselect_b32 s31, s15, s69
	s_cselect_b32 s30, s67, s68
	v_lshl_add_u64 v[194:195], s[28:29], 0, v[174:175]
	s_add_i32 m0, s19, 0xc000
	ds_read_b128 v[162:165], v204
	ds_read_b128 v[182:185], v204 offset:1024
	ds_read_b128 v[186:189], v204 offset:2048
	ds_read_b128 v[206:209], v204 offset:3072
	ds_read_b128 v[210:213], v204 offset:4096
	ds_read_b128 v[214:217], v204 offset:5120
	ds_read_b128 v[218:221], v204 offset:6144
	ds_read_b128 v[222:225], v204 offset:7168
	global_load_lds_dwordx4 v[194:195], off
	v_lshl_add_u64 v[194:195], s[28:29], 0, v[176:177]
	s_add_i32 m0, s19, 0xe000
	s_nop 0
	global_load_lds_dwordx4 v[194:195], off
	s_waitcnt vmcnt(8)
	s_waitcnt lgkmcnt(0)
	s_barrier
	s_waitcnt lgkmcnt(0)
	v_mfma_i32_16x16x64_i8 v[142:145], v[106:109], v[162:165], 0
	v_mfma_i32_16x16x64_i8 v[142:145], v[114:117], v[182:185], v[142:145]
	v_mfma_i32_16x16x64_i8 v[138:141], v[122:125], v[162:165], 0
	v_mfma_i32_16x16x64_i8 v[138:141], v[130:133], v[182:185], v[138:141]
	v_mfma_i32_16x16x64_i8 v[118:121], v[106:109], v[186:189], 0
	v_mfma_i32_16x16x64_i8 v[118:121], v[114:117], v[206:209], v[118:121]
	v_mfma_i32_16x16x64_i8 v[110:113], v[122:125], v[186:189], 0
	v_mfma_i32_16x16x64_i8 v[110:113], v[130:133], v[206:209], v[110:113]
	v_mfma_i32_16x16x64_i8 v[94:97], v[106:109], v[210:213], 0
	v_mfma_i32_16x16x64_i8 v[94:97], v[114:117], v[214:217], v[94:97]
	v_mfma_i32_16x16x64_i8 v[90:93], v[122:125], v[210:213], 0
	v_mfma_i32_16x16x64_i8 v[90:93], v[130:133], v[214:217], v[90:93]
	v_mfma_i32_16x16x64_i8 v[78:81], v[106:109], v[218:221], 0
	v_mfma_i32_16x16x64_i8 v[78:81], v[114:117], v[222:225], v[78:81]
	v_mfma_i32_16x16x64_i8 v[74:77], v[122:125], v[218:221], 0
	v_mfma_i32_16x16x64_i8 v[74:77], v[130:133], v[222:225], v[74:77]
	v_mfma_i32_16x16x64_i8 v[134:137], v[146:149], v[162:165], 0
	v_mfma_i32_16x16x64_i8 v[134:137], v[150:153], v[182:185], v[134:137]
	v_mfma_i32_16x16x64_i8 v[126:129], v[154:157], v[162:165], 0
	v_mfma_i32_16x16x64_i8 v[126:129], v[158:161], v[182:185], v[126:129]
	v_mfma_i32_16x16x64_i8 v[102:105], v[146:149], v[186:189], 0
	v_mfma_i32_16x16x64_i8 v[102:105], v[150:153], v[206:209], v[102:105]
	v_mfma_i32_16x16x64_i8 v[98:101], v[154:157], v[186:189], 0
	v_mfma_i32_16x16x64_i8 v[98:101], v[158:161], v[206:209], v[98:101]
	v_mfma_i32_16x16x64_i8 v[86:89], v[146:149], v[210:213], 0
	v_mfma_i32_16x16x64_i8 v[86:89], v[150:153], v[214:217], v[86:89]
	v_mfma_i32_16x16x64_i8 v[82:85], v[154:157], v[210:213], 0
	v_mfma_i32_16x16x64_i8 v[82:85], v[158:161], v[214:217], v[82:85]
	v_mfma_i32_16x16x64_i8 v[70:73], v[146:149], v[218:221], 0
	v_mfma_i32_16x16x64_i8 v[70:73], v[150:153], v[222:225], v[70:73]
	v_mfma_i32_16x16x64_i8 v[66:69], v[154:157], v[218:221], 0
	v_mfma_i32_16x16x64_i8 v[66:69], v[158:161], v[222:225], v[66:69]
	s_barrier
	s_add_i32 s71, s63, s39
	v_lshl_add_u64 v[194:195], s[30:31], 0, v[168:169]
	s_mov_b32 m0, s71
	ds_read_b128 v[162:165], v204 offset:16384
	ds_read_b128 v[182:185], v204 offset:17408
	ds_read_b128 v[186:189], v204 offset:18432
	ds_read_b128 v[206:209], v204 offset:19456
	ds_read_b128 v[210:213], v204 offset:20480
	ds_read_b128 v[214:217], v204 offset:21504
	ds_read_b128 v[218:221], v204 offset:22528
	ds_read_b128 v[222:225], v204 offset:23552
	global_load_lds_dwordx4 v[194:195], off
	s_add_i32 m0, s71, 0x2000
	s_add_u32 s72, s30, 0x80000
	v_lshl_add_u64 v[198:199], s[30:31], 0, v[172:173]
	s_addc_u32 s73, s31, 0
	s_add_i32 s71, s64, s39
	global_load_lds_dwordx4 v[198:199], off
	v_lshl_add_u64 v[202:203], s[72:73], 0, v[168:169]
	s_mov_b32 m0, s71
	v_lshl_add_u64 v[226:227], s[34:35], 0, v[170:171]
	global_load_lds_dwordx4 v[202:203], off
	v_lshl_add_u64 v[202:203], s[72:73], 0, v[172:173]
	s_add_i32 m0, s71, 0x2000
	s_nop 0
	global_load_lds_dwordx4 v[202:203], off
	v_lshl_add_u64 v[202:203], s[34:35], 0, v[166:167]
	s_mov_b32 m0, s19
	s_nop 0
	global_load_lds_dwordx4 v[202:203], off
	s_mov_b32 m0, s40
	s_nop 0
	global_load_lds_dwordx4 v[226:227], off
	s_waitcnt vmcnt(8)
	s_waitcnt lgkmcnt(0)
	s_barrier
	s_waitcnt lgkmcnt(0)
	v_mfma_i32_16x16x64_i8 v[62:65], v[106:109], v[162:165], 0
	v_mfma_i32_16x16x64_i8 v[62:65], v[114:117], v[182:185], v[62:65]
	v_mfma_i32_16x16x64_i8 v[58:61], v[122:125], v[162:165], 0
	v_mfma_i32_16x16x64_i8 v[58:61], v[130:133], v[182:185], v[58:61]
	v_mfma_i32_16x16x64_i8 v[46:49], v[106:109], v[186:189], 0
	v_mfma_i32_16x16x64_i8 v[46:49], v[114:117], v[206:209], v[46:49]
	v_mfma_i32_16x16x64_i8 v[42:45], v[122:125], v[186:189], 0
	v_mfma_i32_16x16x64_i8 v[42:45], v[130:133], v[206:209], v[42:45]
	v_mfma_i32_16x16x64_i8 v[30:33], v[106:109], v[210:213], 0
	v_mfma_i32_16x16x64_i8 v[30:33], v[114:117], v[214:217], v[30:33]
	v_mfma_i32_16x16x64_i8 v[26:29], v[122:125], v[210:213], 0
	v_mfma_i32_16x16x64_i8 v[26:29], v[130:133], v[214:217], v[26:29]
	v_mfma_i32_16x16x64_i8 v[14:17], v[106:109], v[218:221], 0
	v_mfma_i32_16x16x64_i8 v[14:17], v[114:117], v[222:225], v[14:17]
	v_mfma_i32_16x16x64_i8 v[10:13], v[122:125], v[218:221], 0
	v_mfma_i32_16x16x64_i8 v[10:13], v[130:133], v[222:225], v[10:13]
	v_mfma_i32_16x16x64_i8 v[54:57], v[146:149], v[162:165], 0
	v_mfma_i32_16x16x64_i8 v[54:57], v[150:153], v[182:185], v[54:57]
	v_mfma_i32_16x16x64_i8 v[50:53], v[154:157], v[162:165], 0
	v_mfma_i32_16x16x64_i8 v[50:53], v[158:161], v[182:185], v[50:53]
	v_mfma_i32_16x16x64_i8 v[38:41], v[146:149], v[186:189], 0
	v_mfma_i32_16x16x64_i8 v[38:41], v[150:153], v[206:209], v[38:41]
	v_mfma_i32_16x16x64_i8 v[34:37], v[154:157], v[186:189], 0
	v_mfma_i32_16x16x64_i8 v[34:37], v[158:161], v[206:209], v[34:37]
	v_mfma_i32_16x16x64_i8 v[22:25], v[146:149], v[210:213], 0
	v_mfma_i32_16x16x64_i8 v[22:25], v[150:153], v[214:217], v[22:25]
	v_mfma_i32_16x16x64_i8 v[18:21], v[154:157], v[210:213], 0
	v_mfma_i32_16x16x64_i8 v[18:21], v[158:161], v[214:217], v[18:21]
	v_mfma_i32_16x16x64_i8 v[6:9], v[146:149], v[218:221], 0
	v_mfma_i32_16x16x64_i8 v[6:9], v[150:153], v[222:225], v[6:9]
	v_mfma_i32_16x16x64_i8 v[2:5], v[154:157], v[218:221], 0
	v_mfma_i32_16x16x64_i8 v[2:5], v[158:161], v[222:225], v[2:5]
	s_barrier
	s_add_i32 s71, 0, 0x18000
	s_add_i32 s72, 0, 0x1c000
	v_add_u32_e32 v130, s71, v193
	v_add_u32_e32 v158, s72, v193
	ds_read_b128 v[106:109], v130
	ds_read_b128 v[114:117], v130 offset:1024
	ds_read_b128 v[122:125], v130 offset:2048
	ds_read_b128 v[130:133], v130 offset:3072
	ds_read_b128 v[146:149], v158
	ds_read_b128 v[150:153], v158 offset:1024
	ds_read_b128 v[154:157], v158 offset:2048
	ds_read_b128 v[158:161], v158 offset:3072
	s_add_u32 s34, s34, 0x80000
	s_addc_u32 s35, s35, 0
	s_mov_b32 m0, s41
	v_lshl_add_u64 v[228:229], s[34:35], 0, v[166:167]
	ds_read_b128 v[162:165], v204 offset:32768
	ds_read_b128 v[182:185], v204 offset:33792
	ds_read_b128 v[186:189], v204 offset:34816
	ds_read_b128 v[206:209], v204 offset:35840
	ds_read_b128 v[210:213], v204 offset:36864
	ds_read_b128 v[214:217], v204 offset:37888
	ds_read_b128 v[218:221], v204 offset:38912
	ds_read_b128 v[222:225], v204 offset:39936
	global_load_lds_dwordx4 v[228:229], off
	v_lshl_add_u64 v[228:229], s[34:35], 0, v[170:171]
	s_mov_b32 m0, s42
	s_nop 0
	global_load_lds_dwordx4 v[228:229], off
	s_waitcnt vmcnt(8)
	s_waitcnt lgkmcnt(0)
	s_barrier
	s_waitcnt lgkmcnt(0)
	v_mfma_i32_16x16x64_i8 v[142:145], v[106:109], v[162:165], v[142:145]
	v_mfma_i32_16x16x64_i8 v[142:145], v[114:117], v[182:185], v[142:145]
	v_mfma_i32_16x16x64_i8 v[138:141], v[122:125], v[162:165], v[138:141]
	v_mfma_i32_16x16x64_i8 v[138:141], v[130:133], v[182:185], v[138:141]
	v_mfma_i32_16x16x64_i8 v[118:121], v[106:109], v[186:189], v[118:121]
	v_mfma_i32_16x16x64_i8 v[118:121], v[114:117], v[206:209], v[118:121]
	v_mfma_i32_16x16x64_i8 v[110:113], v[122:125], v[186:189], v[110:113]
	v_mfma_i32_16x16x64_i8 v[110:113], v[130:133], v[206:209], v[110:113]
	v_mfma_i32_16x16x64_i8 v[94:97], v[106:109], v[210:213], v[94:97]
	v_mfma_i32_16x16x64_i8 v[94:97], v[114:117], v[214:217], v[94:97]
	v_mfma_i32_16x16x64_i8 v[90:93], v[122:125], v[210:213], v[90:93]
	v_mfma_i32_16x16x64_i8 v[90:93], v[130:133], v[214:217], v[90:93]
	v_mfma_i32_16x16x64_i8 v[78:81], v[106:109], v[218:221], v[78:81]
	v_mfma_i32_16x16x64_i8 v[78:81], v[114:117], v[222:225], v[78:81]
	v_mfma_i32_16x16x64_i8 v[74:77], v[122:125], v[218:221], v[74:77]
	v_mfma_i32_16x16x64_i8 v[74:77], v[130:133], v[222:225], v[74:77]
	v_mfma_i32_16x16x64_i8 v[134:137], v[146:149], v[162:165], v[134:137]
	v_mfma_i32_16x16x64_i8 v[134:137], v[150:153], v[182:185], v[134:137]
	v_mfma_i32_16x16x64_i8 v[126:129], v[154:157], v[162:165], v[126:129]
	v_mfma_i32_16x16x64_i8 v[126:129], v[158:161], v[182:185], v[126:129]
	v_mfma_i32_16x16x64_i8 v[102:105], v[146:149], v[186:189], v[102:105]
	v_mfma_i32_16x16x64_i8 v[102:105], v[150:153], v[206:209], v[102:105]
	v_mfma_i32_16x16x64_i8 v[98:101], v[154:157], v[186:189], v[98:101]
	v_mfma_i32_16x16x64_i8 v[98:101], v[158:161], v[206:209], v[98:101]
	v_mfma_i32_16x16x64_i8 v[86:89], v[146:149], v[210:213], v[86:89]
	v_mfma_i32_16x16x64_i8 v[86:89], v[150:153], v[214:217], v[86:89]
	v_mfma_i32_16x16x64_i8 v[82:85], v[154:157], v[210:213], v[82:85]
	v_mfma_i32_16x16x64_i8 v[82:85], v[158:161], v[214:217], v[82:85]
	v_mfma_i32_16x16x64_i8 v[70:73], v[146:149], v[218:221], v[70:73]
	v_mfma_i32_16x16x64_i8 v[70:73], v[150:153], v[222:225], v[70:73]
	v_mfma_i32_16x16x64_i8 v[66:69], v[154:157], v[218:221], v[66:69]
	v_mfma_i32_16x16x64_i8 v[66:69], v[158:161], v[222:225], v[66:69]
	s_barrier
	s_add_i32 s34, s71, s39
	v_lshl_add_u64 v[194:195], v[194:195], 0, s[10:11]
	s_mov_b32 m0, s34
	ds_read_b128 v[162:165], v204 offset:49152
	ds_read_b128 v[182:185], v204 offset:50176
	ds_read_b128 v[186:189], v204 offset:51200
	ds_read_b128 v[206:209], v204 offset:52224
	ds_read_b128 v[210:213], v204 offset:53248
	ds_read_b128 v[214:217], v204 offset:54272
	ds_read_b128 v[218:221], v204 offset:55296
	ds_read_b128 v[222:225], v204 offset:56320
	global_load_lds_dwordx4 v[194:195], off
	s_add_i32 m0, s34, 0x2000
	s_add_u32 s30, s30, 0x80080
	v_lshl_add_u64 v[194:195], v[198:199], 0, s[10:11]
	s_addc_u32 s31, s31, 0
	s_add_i32 s34, s72, s39
	global_load_lds_dwordx4 v[194:195], off
	v_lshl_add_u64 v[194:195], s[30:31], 0, v[168:169]
	s_mov_b32 m0, s34
	s_nop 0
	global_load_lds_dwordx4 v[194:195], off
	v_lshl_add_u64 v[194:195], s[30:31], 0, v[172:173]
	s_add_i32 m0, s34, 0x2000
	s_nop 0
	global_load_lds_dwordx4 v[194:195], off
	v_lshl_add_u64 v[194:195], v[202:203], 0, s[10:11]
	s_mov_b32 m0, s60
	s_nop 0
	global_load_lds_dwordx4 v[194:195], off
	v_lshl_add_u64 v[194:195], v[226:227], 0, s[10:11]
	s_mov_b32 m0, s61
	s_nop 0
	global_load_lds_dwordx4 v[194:195], off
	s_waitcnt vmcnt(8)
	s_waitcnt lgkmcnt(0)
	s_barrier
	s_waitcnt lgkmcnt(0)
	v_mfma_i32_16x16x64_i8 v[62:65], v[106:109], v[162:165], v[62:65]
	v_mfma_i32_16x16x64_i8 v[62:65], v[114:117], v[182:185], v[62:65]
	v_mfma_i32_16x16x64_i8 v[58:61], v[122:125], v[162:165], v[58:61]
	v_mfma_i32_16x16x64_i8 v[58:61], v[130:133], v[182:185], v[58:61]
	v_mfma_i32_16x16x64_i8 v[46:49], v[106:109], v[186:189], v[46:49]
	v_mfma_i32_16x16x64_i8 v[46:49], v[114:117], v[206:209], v[46:49]
	v_mfma_i32_16x16x64_i8 v[42:45], v[122:125], v[186:189], v[42:45]
	v_mfma_i32_16x16x64_i8 v[42:45], v[130:133], v[206:209], v[42:45]
	v_mfma_i32_16x16x64_i8 v[30:33], v[106:109], v[210:213], v[30:33]
	v_mfma_i32_16x16x64_i8 v[30:33], v[114:117], v[214:217], v[30:33]
	v_mfma_i32_16x16x64_i8 v[26:29], v[122:125], v[210:213], v[26:29]
	v_mfma_i32_16x16x64_i8 v[26:29], v[130:133], v[214:217], v[26:29]
	v_mfma_i32_16x16x64_i8 v[14:17], v[106:109], v[218:221], v[14:17]
	v_mfma_i32_16x16x64_i8 v[14:17], v[114:117], v[222:225], v[14:17]
	v_mfma_i32_16x16x64_i8 v[10:13], v[122:125], v[218:221], v[10:13]
	v_mfma_i32_16x16x64_i8 v[10:13], v[130:133], v[222:225], v[10:13]
	v_mfma_i32_16x16x64_i8 v[54:57], v[146:149], v[162:165], v[54:57]
	v_mfma_i32_16x16x64_i8 v[54:57], v[150:153], v[182:185], v[54:57]
	v_mfma_i32_16x16x64_i8 v[50:53], v[154:157], v[162:165], v[50:53]
	v_mfma_i32_16x16x64_i8 v[50:53], v[158:161], v[182:185], v[50:53]
	v_mfma_i32_16x16x64_i8 v[38:41], v[146:149], v[186:189], v[38:41]
	v_mfma_i32_16x16x64_i8 v[38:41], v[150:153], v[206:209], v[38:41]
	v_mfma_i32_16x16x64_i8 v[34:37], v[154:157], v[186:189], v[34:37]
	v_mfma_i32_16x16x64_i8 v[34:37], v[158:161], v[206:209], v[34:37]
	v_mfma_i32_16x16x64_i8 v[22:25], v[146:149], v[210:213], v[22:25]
	v_mfma_i32_16x16x64_i8 v[22:25], v[150:153], v[214:217], v[22:25]
	v_mfma_i32_16x16x64_i8 v[18:21], v[154:157], v[210:213], v[18:21]
	v_mfma_i32_16x16x64_i8 v[18:21], v[158:161], v[214:217], v[18:21]
	v_mfma_i32_16x16x64_i8 v[6:9], v[146:149], v[218:221], v[6:9]
	v_mfma_i32_16x16x64_i8 v[6:9], v[150:153], v[222:225], v[6:9]
	v_mfma_i32_16x16x64_i8 v[2:5], v[154:157], v[218:221], v[2:5]
	v_mfma_i32_16x16x64_i8 v[2:5], v[158:161], v[222:225], v[2:5]
	s_barrier
	s_add_i32 s70, s70, 2
	s_add_u32 s28, s28, 0x100
	s_addc_u32 s29, s29, 0
	s_add_u32 s68, s68, 0x100
	s_addc_u32 s69, s69, 0
	s_cmp_gt_u32 s70, 29

.LBB0_1366:
	s_ashr_i32 s35, s34, 31
	s_lshl_b64 s[18:19], s[34:35], 20
	s_add_u32 s36, s29, s18
	s_addc_u32 s37, s60, s19
	s_and_b64 s[18:19], s[2:3], exec
	s_cselect_b32 s35, s37, s5
	s_cselect_b32 s43, s36, s4
	s_ashr_i32 s31, s30, 31
	s_lshl_b64 s[18:19], s[30:31], 20
	s_add_u32 s38, s61, s18
	s_addc_u32 s39, s62, s19
	s_and_b64 s[18:19], s[2:3], exec
	s_cselect_b32 s31, s39, s7
	s_cselect_b32 vcc_lo, s38, s6
	s_add_u32 vcc_hi, s6, 0x100
	s_addc_u32 s79, s7, 0
	s_mov_b32 s80, -2
	ds_read_b128 v[130:133], v234
	ds_read_b128 v[134:137], v234 offset:1024
	ds_read_b128 v[162:165], v234 offset:2048
	ds_read_b128 v[166:169], v234 offset:3072
	ds_read_b128 v[170:173], v235
	ds_read_b128 v[174:177], v235 offset:1024
	ds_read_b128 v[178:181], v235 offset:2048
	ds_read_b128 v[182:185], v235 offset:3072
	s_add_u32 s6, s4, 0x100
	s_addc_u32 s7, s5, 0
	s_cmp_eq_u32 s80, 28
	s_cselect_b32 s57, s35, s7
	s_cselect_b32 s56, s43, s6
	s_cselect_b32 s19, s31, s79
	s_cselect_b32 s18, vcc_lo, vcc_hi
	v_lshl_add_u64 v[218:219], s[4:5], 0, v[154:155]
	s_add_i32 m0, s65, 0xc000
	ds_read_b128 v[186:189], v236
	ds_read_b128 v[190:193], v236 offset:1024
	ds_read_b128 v[194:197], v236 offset:2048
	ds_read_b128 v[198:201], v236 offset:3072
	ds_read_b128 v[202:205], v236 offset:4096
	ds_read_b128 v[206:209], v236 offset:5120
	ds_read_b128 v[210:213], v236 offset:6144
	ds_read_b128 v[214:217], v236 offset:7168
	global_load_lds_dwordx4 v[218:219], off
	v_lshl_add_u64 v[218:219], s[4:5], 0, v[156:157]
	s_add_i32 m0, s65, 0xe000
	s_nop 0
	global_load_lds_dwordx4 v[218:219], off
	s_waitcnt vmcnt(8)
	s_waitcnt lgkmcnt(0)
	s_barrier
	s_waitcnt lgkmcnt(0)
	v_mfma_i32_16x16x64_i8 v[118:121], v[130:133], v[186:189], 0
	v_mfma_i32_16x16x64_i8 v[118:121], v[134:137], v[190:193], v[118:121]
	v_mfma_i32_16x16x64_i8 v[102:105], v[162:165], v[186:189], 0
	v_mfma_i32_16x16x64_i8 v[102:105], v[166:169], v[190:193], v[102:105]
	v_mfma_i32_16x16x64_i8 v[114:117], v[130:133], v[194:197], 0
	v_mfma_i32_16x16x64_i8 v[114:117], v[134:137], v[198:201], v[114:117]
	v_mfma_i32_16x16x64_i8 v[98:101], v[162:165], v[194:197], 0
	v_mfma_i32_16x16x64_i8 v[98:101], v[166:169], v[198:201], v[98:101]
	v_mfma_i32_16x16x64_i8 v[126:129], v[130:133], v[202:205], 0
	v_mfma_i32_16x16x64_i8 v[126:129], v[134:137], v[206:209], v[126:129]
	v_mfma_i32_16x16x64_i8 v[110:113], v[162:165], v[202:205], 0
	v_mfma_i32_16x16x64_i8 v[110:113], v[166:169], v[206:209], v[110:113]
	v_mfma_i32_16x16x64_i8 v[122:125], v[130:133], v[210:213], 0
	v_mfma_i32_16x16x64_i8 v[122:125], v[134:137], v[214:217], v[122:125]
	v_mfma_i32_16x16x64_i8 v[106:109], v[162:165], v[210:213], 0
	v_mfma_i32_16x16x64_i8 v[106:109], v[166:169], v[214:217], v[106:109]
	v_mfma_i32_16x16x64_i8 v[86:89], v[170:173], v[186:189], 0
	v_mfma_i32_16x16x64_i8 v[86:89], v[174:177], v[190:193], v[86:89]
	v_mfma_i32_16x16x64_i8 v[70:73], v[178:181], v[186:189], 0
	v_mfma_i32_16x16x64_i8 v[70:73], v[182:185], v[190:193], v[70:73]
	v_mfma_i32_16x16x64_i8 v[82:85], v[170:173], v[194:197], 0
	v_mfma_i32_16x16x64_i8 v[82:85], v[174:177], v[198:201], v[82:85]
	v_mfma_i32_16x16x64_i8 v[66:69], v[178:181], v[194:197], 0
	v_mfma_i32_16x16x64_i8 v[66:69], v[182:185], v[198:201], v[66:69]
	v_mfma_i32_16x16x64_i8 v[94:97], v[170:173], v[202:205], 0
	v_mfma_i32_16x16x64_i8 v[94:97], v[174:177], v[206:209], v[94:97]
	v_mfma_i32_16x16x64_i8 v[78:81], v[178:181], v[202:205], 0
	v_mfma_i32_16x16x64_i8 v[78:81], v[182:185], v[206:209], v[78:81]
	v_mfma_i32_16x16x64_i8 v[90:93], v[170:173], v[210:213], 0
	v_mfma_i32_16x16x64_i8 v[90:93], v[174:177], v[214:217], v[90:93]
	v_mfma_i32_16x16x64_i8 v[74:77], v[178:181], v[210:213], 0
	v_mfma_i32_16x16x64_i8 v[74:77], v[182:185], v[214:217], v[74:77]
	s_barrier
	s_add_i32 s4, s97, s63
	v_lshl_add_u64 v[218:219], s[18:19], 0, v[144:145]
	s_mov_b32 m0, s4
	ds_read_b128 v[186:189], v236 offset:16384
	ds_read_b128 v[190:193], v236 offset:17408
	ds_read_b128 v[194:197], v236 offset:18432
	ds_read_b128 v[198:201], v236 offset:19456
	ds_read_b128 v[202:205], v236 offset:20480
	ds_read_b128 v[206:209], v236 offset:21504
	ds_read_b128 v[210:213], v236 offset:22528
	ds_read_b128 v[214:217], v236 offset:23552
	global_load_lds_dwordx4 v[218:219], off
	s_add_i32 m0, s4, 0x2000
	s_add_u32 s4, s18, 0x80000
	v_lshl_add_u64 v[220:221], s[18:19], 0, v[148:149]
	s_addc_u32 s5, s19, 0
	s_add_i32 s81, s0, s63
	global_load_lds_dwordx4 v[220:221], off
	v_lshl_add_u64 v[222:223], s[4:5], 0, v[144:145]
	s_mov_b32 m0, s81
	v_lshl_add_u64 v[224:225], s[56:57], 0, v[146:147]
	global_load_lds_dwordx4 v[222:223], off
	v_lshl_add_u64 v[222:223], s[4:5], 0, v[148:149]
	s_add_i32 m0, s81, 0x2000
	s_nop 0
	global_load_lds_dwordx4 v[222:223], off
	v_lshl_add_u64 v[222:223], s[56:57], 0, v[142:143]
	s_mov_b32 m0, s65
	s_nop 0
	global_load_lds_dwordx4 v[222:223], off
	s_mov_b32 m0, s66
	s_nop 0
	global_load_lds_dwordx4 v[224:225], off
	s_waitcnt vmcnt(8)
	s_waitcnt lgkmcnt(0)
	s_barrier
	s_waitcnt lgkmcnt(0)
	v_mfma_i32_16x16x64_i8 v[54:57], v[130:133], v[186:189], 0
	v_mfma_i32_16x16x64_i8 v[54:57], v[134:137], v[190:193], v[54:57]
	v_mfma_i32_16x16x64_i8 v[18:21], v[162:165], v[186:189], 0
	v_mfma_i32_16x16x64_i8 v[18:21], v[166:169], v[190:193], v[18:21]
	v_mfma_i32_16x16x64_i8 v[50:53], v[130:133], v[194:197], 0
	v_mfma_i32_16x16x64_i8 v[50:53], v[134:137], v[198:201], v[50:53]
	v_mfma_i32_16x16x64_i8 v[22:25], v[162:165], v[194:197], 0
	v_mfma_i32_16x16x64_i8 v[22:25], v[166:169], v[198:201], v[22:25]
	v_mfma_i32_16x16x64_i8 v[62:65], v[130:133], v[202:205], 0
	v_mfma_i32_16x16x64_i8 v[62:65], v[134:137], v[206:209], v[62:65]
	v_mfma_i32_16x16x64_i8 v[30:33], v[162:165], v[202:205], 0
	v_mfma_i32_16x16x64_i8 v[30:33], v[166:169], v[206:209], v[30:33]
	v_mfma_i32_16x16x64_i8 v[58:61], v[130:133], v[210:213], 0
	v_mfma_i32_16x16x64_i8 v[58:61], v[134:137], v[214:217], v[58:61]
	v_mfma_i32_16x16x64_i8 v[26:29], v[162:165], v[210:213], 0
	v_mfma_i32_16x16x64_i8 v[26:29], v[166:169], v[214:217], v[26:29]
	v_mfma_i32_16x16x64_i8 v[46:49], v[170:173], v[186:189], 0
	v_mfma_i32_16x16x64_i8 v[46:49], v[174:177], v[190:193], v[46:49]
	v_mfma_i32_16x16x64_i8 v[14:17], v[178:181], v[186:189], 0
	v_mfma_i32_16x16x64_i8 v[14:17], v[182:185], v[190:193], v[14:17]
	v_mfma_i32_16x16x64_i8 v[42:45], v[170:173], v[194:197], 0
	v_mfma_i32_16x16x64_i8 v[42:45], v[174:177], v[198:201], v[42:45]
	v_mfma_i32_16x16x64_i8 v[10:13], v[178:181], v[194:197], 0
	v_mfma_i32_16x16x64_i8 v[10:13], v[182:185], v[198:201], v[10:13]
	v_mfma_i32_16x16x64_i8 v[38:41], v[170:173], v[202:205], 0
	v_mfma_i32_16x16x64_i8 v[38:41], v[174:177], v[206:209], v[38:41]
	v_mfma_i32_16x16x64_i8 v[6:9], v[178:181], v[202:205], 0
	v_mfma_i32_16x16x64_i8 v[6:9], v[182:185], v[206:209], v[6:9]
	v_mfma_i32_16x16x64_i8 v[34:37], v[170:173], v[210:213], 0
	v_mfma_i32_16x16x64_i8 v[34:37], v[174:177], v[214:217], v[34:37]
	v_mfma_i32_16x16x64_i8 v[2:5], v[178:181], v[210:213], 0
	v_mfma_i32_16x16x64_i8 v[2:5], v[182:185], v[214:217], v[2:5]
	s_barrier
	s_add_i32 s81, 0, 0x18000
	s_add_i32 s82, 0, 0x1c000
	v_add_u32_e32 v166, s81, v232
	v_add_u32_e32 v182, s82, v232
	ds_read_b128 v[130:133], v166
	ds_read_b128 v[134:137], v166 offset:1024
	ds_read_b128 v[162:165], v166 offset:2048
	ds_read_b128 v[166:169], v166 offset:3072
	ds_read_b128 v[170:173], v182
	ds_read_b128 v[174:177], v182 offset:1024
	ds_read_b128 v[178:181], v182 offset:2048
	ds_read_b128 v[182:185], v182 offset:3072
	s_add_u32 s4, s56, 0x80000
	s_addc_u32 s5, s57, 0
	s_mov_b32 m0, s67
	v_lshl_add_u64 v[226:227], s[4:5], 0, v[142:143]
	ds_read_b128 v[186:189], v236 offset:32768
	ds_read_b128 v[190:193], v236 offset:33792
	ds_read_b128 v[194:197], v236 offset:34816
	ds_read_b128 v[198:201], v236 offset:35840
	ds_read_b128 v[202:205], v236 offset:36864
	ds_read_b128 v[206:209], v236 offset:37888
	ds_read_b128 v[210:213], v236 offset:38912
	ds_read_b128 v[214:217], v236 offset:39936
	global_load_lds_dwordx4 v[226:227], off
	v_lshl_add_u64 v[226:227], s[4:5], 0, v[146:147]
	s_mov_b32 m0, s68
	s_nop 0
	global_load_lds_dwordx4 v[226:227], off
	s_waitcnt vmcnt(8)
	s_waitcnt lgkmcnt(0)
	s_barrier
	s_waitcnt lgkmcnt(0)
	v_mfma_i32_16x16x64_i8 v[118:121], v[130:133], v[186:189], v[118:121]
	v_mfma_i32_16x16x64_i8 v[118:121], v[134:137], v[190:193], v[118:121]
	v_mfma_i32_16x16x64_i8 v[102:105], v[162:165], v[186:189], v[102:105]
	v_mfma_i32_16x16x64_i8 v[102:105], v[166:169], v[190:193], v[102:105]
	v_mfma_i32_16x16x64_i8 v[114:117], v[130:133], v[194:197], v[114:117]
	v_mfma_i32_16x16x64_i8 v[114:117], v[134:137], v[198:201], v[114:117]
	v_mfma_i32_16x16x64_i8 v[98:101], v[162:165], v[194:197], v[98:101]
	v_mfma_i32_16x16x64_i8 v[98:101], v[166:169], v[198:201], v[98:101]
	v_mfma_i32_16x16x64_i8 v[126:129], v[130:133], v[202:205], v[126:129]
	v_mfma_i32_16x16x64_i8 v[126:129], v[134:137], v[206:209], v[126:129]
	v_mfma_i32_16x16x64_i8 v[110:113], v[162:165], v[202:205], v[110:113]
	v_mfma_i32_16x16x64_i8 v[110:113], v[166:169], v[206:209], v[110:113]
	v_mfma_i32_16x16x64_i8 v[122:125], v[130:133], v[210:213], v[122:125]
	v_mfma_i32_16x16x64_i8 v[122:125], v[134:137], v[214:217], v[122:125]
	v_mfma_i32_16x16x64_i8 v[106:109], v[162:165], v[210:213], v[106:109]
	v_mfma_i32_16x16x64_i8 v[106:109], v[166:169], v[214:217], v[106:109]
	v_mfma_i32_16x16x64_i8 v[86:89], v[170:173], v[186:189], v[86:89]
	v_mfma_i32_16x16x64_i8 v[86:89], v[174:177], v[190:193], v[86:89]
	v_mfma_i32_16x16x64_i8 v[70:73], v[178:181], v[186:189], v[70:73]
	v_mfma_i32_16x16x64_i8 v[70:73], v[182:185], v[190:193], v[70:73]
	v_mfma_i32_16x16x64_i8 v[82:85], v[170:173], v[194:197], v[82:85]
	v_mfma_i32_16x16x64_i8 v[82:85], v[174:177], v[198:201], v[82:85]
	v_mfma_i32_16x16x64_i8 v[66:69], v[178:181], v[194:197], v[66:69]
	v_mfma_i32_16x16x64_i8 v[66:69], v[182:185], v[198:201], v[66:69]
	v_mfma_i32_16x16x64_i8 v[94:97], v[170:173], v[202:205], v[94:97]
	v_mfma_i32_16x16x64_i8 v[94:97], v[174:177], v[206:209], v[94:97]
	v_mfma_i32_16x16x64_i8 v[78:81], v[178:181], v[202:205], v[78:81]
	v_mfma_i32_16x16x64_i8 v[78:81], v[182:185], v[206:209], v[78:81]
	v_mfma_i32_16x16x64_i8 v[90:93], v[170:173], v[210:213], v[90:93]
	v_mfma_i32_16x16x64_i8 v[90:93], v[174:177], v[214:217], v[90:93]
	v_mfma_i32_16x16x64_i8 v[74:77], v[178:181], v[210:213], v[74:77]
	v_mfma_i32_16x16x64_i8 v[74:77], v[182:185], v[214:217], v[74:77]
	s_barrier
	s_add_i32 s4, s81, s63
	v_lshl_add_u64 v[218:219], v[218:219], 0, s[22:23]
	s_mov_b32 m0, s4
	ds_read_b128 v[186:189], v236 offset:49152
	ds_read_b128 v[190:193], v236 offset:50176
	ds_read_b128 v[194:197], v236 offset:51200
	ds_read_b128 v[198:201], v236 offset:52224
	ds_read_b128 v[202:205], v236 offset:53248
	ds_read_b128 v[206:209], v236 offset:54272
	ds_read_b128 v[210:213], v236 offset:55296
	ds_read_b128 v[214:217], v236 offset:56320
	global_load_lds_dwordx4 v[218:219], off
	s_add_i32 m0, s4, 0x2000
	s_add_u32 s4, s18, 0x80080
	v_lshl_add_u64 v[218:219], v[220:221], 0, s[22:23]
	s_addc_u32 s5, s19, 0
	s_add_i32 s18, s82, s63
	global_load_lds_dwordx4 v[218:219], off
	v_lshl_add_u64 v[218:219], s[4:5], 0, v[144:145]
	s_mov_b32 m0, s18
	s_nop 0
	global_load_lds_dwordx4 v[218:219], off
	v_lshl_add_u64 v[218:219], s[4:5], 0, v[148:149]
	s_add_i32 m0, s18, 0x2000
	s_nop 0
	global_load_lds_dwordx4 v[218:219], off
	v_lshl_add_u64 v[218:219], v[222:223], 0, s[22:23]
	s_mov_b32 m0, s77
	s_nop 0
	global_load_lds_dwordx4 v[218:219], off
	v_lshl_add_u64 v[218:219], v[224:225], 0, s[22:23]
	s_mov_b32 m0, s78
	s_nop 0
	global_load_lds_dwordx4 v[218:219], off
	s_waitcnt vmcnt(8)
	s_waitcnt lgkmcnt(0)
	s_barrier
	s_waitcnt lgkmcnt(0)
	v_mfma_i32_16x16x64_i8 v[54:57], v[130:133], v[186:189], v[54:57]
	v_mfma_i32_16x16x64_i8 v[54:57], v[134:137], v[190:193], v[54:57]
	v_mfma_i32_16x16x64_i8 v[18:21], v[162:165], v[186:189], v[18:21]
	v_mfma_i32_16x16x64_i8 v[18:21], v[166:169], v[190:193], v[18:21]
	v_mfma_i32_16x16x64_i8 v[50:53], v[130:133], v[194:197], v[50:53]
	v_mfma_i32_16x16x64_i8 v[50:53], v[134:137], v[198:201], v[50:53]
	v_mfma_i32_16x16x64_i8 v[22:25], v[162:165], v[194:197], v[22:25]
	v_mfma_i32_16x16x64_i8 v[22:25], v[166:169], v[198:201], v[22:25]
	v_mfma_i32_16x16x64_i8 v[62:65], v[130:133], v[202:205], v[62:65]
	v_mfma_i32_16x16x64_i8 v[62:65], v[134:137], v[206:209], v[62:65]
	v_mfma_i32_16x16x64_i8 v[30:33], v[162:165], v[202:205], v[30:33]
	v_mfma_i32_16x16x64_i8 v[30:33], v[166:169], v[206:209], v[30:33]
	v_mfma_i32_16x16x64_i8 v[58:61], v[130:133], v[210:213], v[58:61]
	v_mfma_i32_16x16x64_i8 v[58:61], v[134:137], v[214:217], v[58:61]
	v_mfma_i32_16x16x64_i8 v[26:29], v[162:165], v[210:213], v[26:29]
	v_mfma_i32_16x16x64_i8 v[26:29], v[166:169], v[214:217], v[26:29]
	v_mfma_i32_16x16x64_i8 v[46:49], v[170:173], v[186:189], v[46:49]
	v_mfma_i32_16x16x64_i8 v[46:49], v[174:177], v[190:193], v[46:49]
	v_mfma_i32_16x16x64_i8 v[14:17], v[178:181], v[186:189], v[14:17]
	v_mfma_i32_16x16x64_i8 v[14:17], v[182:185], v[190:193], v[14:17]
	v_mfma_i32_16x16x64_i8 v[42:45], v[170:173], v[194:197], v[42:45]
	v_mfma_i32_16x16x64_i8 v[42:45], v[174:177], v[198:201], v[42:45]
	v_mfma_i32_16x16x64_i8 v[10:13], v[178:181], v[194:197], v[10:13]
	v_mfma_i32_16x16x64_i8 v[10:13], v[182:185], v[198:201], v[10:13]
	v_mfma_i32_16x16x64_i8 v[38:41], v[170:173], v[202:205], v[38:41]
	v_mfma_i32_16x16x64_i8 v[38:41], v[174:177], v[206:209], v[38:41]
	v_mfma_i32_16x16x64_i8 v[6:9], v[178:181], v[202:205], v[6:9]
	v_mfma_i32_16x16x64_i8 v[6:9], v[182:185], v[206:209], v[6:9]
	v_mfma_i32_16x16x64_i8 v[34:37], v[170:173], v[210:213], v[34:37]
	v_mfma_i32_16x16x64_i8 v[34:37], v[174:177], v[214:217], v[34:37]
	v_mfma_i32_16x16x64_i8 v[2:5], v[178:181], v[210:213], v[2:5]
	v_mfma_i32_16x16x64_i8 v[2:5], v[182:185], v[214:217], v[2:5]
	s_barrier
	s_add_i32 s80, s80, 2
	s_add_u32 vcc_hi, vcc_hi, 0x100
	s_addc_u32 s79, s79, 0
	s_cmp_gt_u32 s80, 29
	s_mov_b64 s[4:5], s[6:7]

.LBB0_1553:
	s_add_u32 s64, s26, 0x100
	s_addc_u32 s65, s27, 0
	s_mov_b32 s66, -2
	s_waitcnt lgkmcnt(0)
	ds_read_b128 v[114:117], v247
	ds_read_b128 v[118:121], v247 offset:1024
	ds_read_b128 v[126:129], v247 offset:2048
	ds_read_b128 v[134:137], v247 offset:3072
	ds_read_b128 v[138:141], v248
	ds_read_b128 v[142:145], v248 offset:1024
	ds_read_b128 v[154:157], v248 offset:2048
	ds_read_b128 v[158:161], v248 offset:3072
	s_add_u32 s4, s18, 0x100
	s_addc_u32 s5, s19, 0
	s_cmpk_eq_i32 s66, 0xdc
	s_cselect_b32 s29, s23, s5
	s_cselect_b32 s28, s22, s4
	s_cselect_b32 s27, s25, s65
	s_cselect_b32 s26, s24, s64
	v_lshl_add_u64 v[210:211], s[18:19], 0, v[202:203]
	s_add_i32 m0, s17, 0xc000
	ds_read_b128 v[162:165], v249
	ds_read_b128 v[166:169], v249 offset:1024
	ds_read_b128 v[170:173], v249 offset:2048
	ds_read_b128 v[174:177], v249 offset:3072
	ds_read_b128 v[178:181], v249 offset:4096
	ds_read_b128 v[182:185], v249 offset:5120
	ds_read_b128 v[186:189], v249 offset:6144
	ds_read_b128 v[190:193], v249 offset:7168
	global_load_lds_dwordx4 v[210:211], off
	v_lshl_add_u64 v[210:211], s[18:19], 0, v[204:205]
	s_add_i32 m0, s17, 0xe000
	s_nop 0
	global_load_lds_dwordx4 v[210:211], off
	s_waitcnt vmcnt(8)
	s_waitcnt lgkmcnt(0)
	s_barrier
	s_waitcnt lgkmcnt(0)
	v_mfma_f32_16x16x32_bf16 v[150:153], v[114:117], v[162:165], 0
	v_mfma_f32_16x16x32_bf16 v[150:153], v[118:121], v[166:169], v[150:153]
	v_mfma_f32_16x16x32_bf16 v[146:149], v[126:129], v[162:165], 0
	v_mfma_f32_16x16x32_bf16 v[146:149], v[134:137], v[166:169], v[146:149]
	v_mfma_f32_16x16x32_bf16 v[110:113], v[114:117], v[170:173], 0
	v_mfma_f32_16x16x32_bf16 v[110:113], v[118:121], v[174:177], v[110:113]
	v_mfma_f32_16x16x32_bf16 v[106:109], v[126:129], v[170:173], 0
	v_mfma_f32_16x16x32_bf16 v[106:109], v[134:137], v[174:177], v[106:109]
	v_mfma_f32_16x16x32_bf16 v[94:97], v[114:117], v[178:181], 0
	v_mfma_f32_16x16x32_bf16 v[94:97], v[118:121], v[182:185], v[94:97]
	v_mfma_f32_16x16x32_bf16 v[90:93], v[126:129], v[178:181], 0
	v_mfma_f32_16x16x32_bf16 v[90:93], v[134:137], v[182:185], v[90:93]
	v_mfma_f32_16x16x32_bf16 v[78:81], v[114:117], v[186:189], 0
	v_mfma_f32_16x16x32_bf16 v[78:81], v[118:121], v[190:193], v[78:81]
	v_mfma_f32_16x16x32_bf16 v[74:77], v[126:129], v[186:189], 0
	v_mfma_f32_16x16x32_bf16 v[74:77], v[134:137], v[190:193], v[74:77]
	v_mfma_f32_16x16x32_bf16 v[130:133], v[138:141], v[162:165], 0
	v_mfma_f32_16x16x32_bf16 v[130:133], v[142:145], v[166:169], v[130:133]
	v_mfma_f32_16x16x32_bf16 v[122:125], v[154:157], v[162:165], 0
	v_mfma_f32_16x16x32_bf16 v[122:125], v[158:161], v[166:169], v[122:125]
	v_mfma_f32_16x16x32_bf16 v[102:105], v[138:141], v[170:173], 0
	v_mfma_f32_16x16x32_bf16 v[102:105], v[142:145], v[174:177], v[102:105]
	v_mfma_f32_16x16x32_bf16 v[98:101], v[154:157], v[170:173], 0
	v_mfma_f32_16x16x32_bf16 v[98:101], v[158:161], v[174:177], v[98:101]
	v_mfma_f32_16x16x32_bf16 v[86:89], v[138:141], v[178:181], 0
	v_mfma_f32_16x16x32_bf16 v[86:89], v[142:145], v[182:185], v[86:89]
	v_mfma_f32_16x16x32_bf16 v[82:85], v[154:157], v[178:181], 0
	v_mfma_f32_16x16x32_bf16 v[82:85], v[158:161], v[182:185], v[82:85]
	v_mfma_f32_16x16x32_bf16 v[70:73], v[138:141], v[186:189], 0
	v_mfma_f32_16x16x32_bf16 v[70:73], v[142:145], v[190:193], v[70:73]
	v_mfma_f32_16x16x32_bf16 v[66:69], v[154:157], v[186:189], 0
	v_mfma_f32_16x16x32_bf16 v[66:69], v[158:161], v[190:193], v[66:69]
	s_barrier
	s_add_i32 s18, s42, s16
	v_lshl_add_u64 v[210:211], s[26:27], 0, v[196:197]
	s_mov_b32 m0, s18
	ds_read_b128 v[162:165], v249 offset:16384
	ds_read_b128 v[166:169], v249 offset:17408
	ds_read_b128 v[170:173], v249 offset:18432
	ds_read_b128 v[174:177], v249 offset:19456
	ds_read_b128 v[178:181], v249 offset:20480
	ds_read_b128 v[182:185], v249 offset:21504
	ds_read_b128 v[186:189], v249 offset:22528
	ds_read_b128 v[190:193], v249 offset:23552
	global_load_lds_dwordx4 v[210:211], off
	s_add_i32 m0, s18, 0x2000
	s_add_u32 s18, s26, 0x380000
	v_lshl_add_u64 v[212:213], s[26:27], 0, v[200:201]
	s_addc_u32 s19, s27, 0
	s_add_i32 s67, s43, s16
	global_load_lds_dwordx4 v[212:213], off
	v_lshl_add_u64 v[214:215], s[18:19], 0, v[196:197]
	s_mov_b32 m0, s67
	v_lshl_add_u64 v[216:217], s[28:29], 0, v[198:199]
	global_load_lds_dwordx4 v[214:215], off
	v_lshl_add_u64 v[214:215], s[18:19], 0, v[200:201]
	s_add_i32 m0, s67, 0x2000
	s_nop 0
	global_load_lds_dwordx4 v[214:215], off
	v_lshl_add_u64 v[214:215], s[28:29], 0, v[194:195]
	s_mov_b32 m0, s17
	s_nop 0
	global_load_lds_dwordx4 v[214:215], off
	s_mov_b32 m0, s30
	s_nop 0
	global_load_lds_dwordx4 v[216:217], off
	s_waitcnt vmcnt(8)
	s_waitcnt lgkmcnt(0)
	s_barrier
	s_waitcnt lgkmcnt(0)
	v_mfma_f32_16x16x32_bf16 v[62:65], v[114:117], v[162:165], 0
	v_mfma_f32_16x16x32_bf16 v[62:65], v[118:121], v[166:169], v[62:65]
	v_mfma_f32_16x16x32_bf16 v[58:61], v[126:129], v[162:165], 0
	v_mfma_f32_16x16x32_bf16 v[58:61], v[134:137], v[166:169], v[58:61]
	v_mfma_f32_16x16x32_bf16 v[46:49], v[114:117], v[170:173], 0
	v_mfma_f32_16x16x32_bf16 v[46:49], v[118:121], v[174:177], v[46:49]
	v_mfma_f32_16x16x32_bf16 v[42:45], v[126:129], v[170:173], 0
	v_mfma_f32_16x16x32_bf16 v[42:45], v[134:137], v[174:177], v[42:45]
	v_mfma_f32_16x16x32_bf16 v[30:33], v[114:117], v[178:181], 0
	v_mfma_f32_16x16x32_bf16 v[30:33], v[118:121], v[182:185], v[30:33]
	v_mfma_f32_16x16x32_bf16 v[26:29], v[126:129], v[178:181], 0
	v_mfma_f32_16x16x32_bf16 v[26:29], v[134:137], v[182:185], v[26:29]
	v_mfma_f32_16x16x32_bf16 v[14:17], v[114:117], v[186:189], 0
	v_mfma_f32_16x16x32_bf16 v[14:17], v[118:121], v[190:193], v[14:17]
	v_mfma_f32_16x16x32_bf16 v[10:13], v[126:129], v[186:189], 0
	v_mfma_f32_16x16x32_bf16 v[10:13], v[134:137], v[190:193], v[10:13]
	v_mfma_f32_16x16x32_bf16 v[54:57], v[138:141], v[162:165], 0
	v_mfma_f32_16x16x32_bf16 v[54:57], v[142:145], v[166:169], v[54:57]
	v_mfma_f32_16x16x32_bf16 v[50:53], v[154:157], v[162:165], 0
	v_mfma_f32_16x16x32_bf16 v[50:53], v[158:161], v[166:169], v[50:53]
	v_mfma_f32_16x16x32_bf16 v[38:41], v[138:141], v[170:173], 0
	v_mfma_f32_16x16x32_bf16 v[38:41], v[142:145], v[174:177], v[38:41]
	v_mfma_f32_16x16x32_bf16 v[34:37], v[154:157], v[170:173], 0
	v_mfma_f32_16x16x32_bf16 v[34:37], v[158:161], v[174:177], v[34:37]
	v_mfma_f32_16x16x32_bf16 v[22:25], v[138:141], v[178:181], 0
	v_mfma_f32_16x16x32_bf16 v[22:25], v[142:145], v[182:185], v[22:25]
	v_mfma_f32_16x16x32_bf16 v[18:21], v[154:157], v[178:181], 0
	v_mfma_f32_16x16x32_bf16 v[18:21], v[158:161], v[182:185], v[18:21]
	v_mfma_f32_16x16x32_bf16 v[6:9], v[138:141], v[186:189], 0
	v_mfma_f32_16x16x32_bf16 v[6:9], v[142:145], v[190:193], v[6:9]
	v_mfma_f32_16x16x32_bf16 v[2:5], v[154:157], v[186:189], 0
	v_mfma_f32_16x16x32_bf16 v[2:5], v[158:161], v[190:193], v[2:5]
	s_barrier
	s_add_i32 s67, 0, 0x18000
	s_add_i32 s68, 0, 0x1c000
	v_add_u32_e32 v134, s67, v244
	v_add_u32_e32 v158, s68, v244
	ds_read_b128 v[114:117], v134
	ds_read_b128 v[118:121], v134 offset:1024
	ds_read_b128 v[126:129], v134 offset:2048
	ds_read_b128 v[134:137], v134 offset:3072
	ds_read_b128 v[138:141], v158
	ds_read_b128 v[142:145], v158 offset:1024
	ds_read_b128 v[154:157], v158 offset:2048
	ds_read_b128 v[158:161], v158 offset:3072
	s_add_u32 s18, s28, 0x380000
	s_addc_u32 s19, s29, 0
	s_mov_b32 m0, s31
	v_lshl_add_u64 v[218:219], s[18:19], 0, v[194:195]
	ds_read_b128 v[162:165], v249 offset:32768
	ds_read_b128 v[166:169], v249 offset:33792
	ds_read_b128 v[170:173], v249 offset:34816
	ds_read_b128 v[174:177], v249 offset:35840
	ds_read_b128 v[178:181], v249 offset:36864
	ds_read_b128 v[182:185], v249 offset:37888
	ds_read_b128 v[186:189], v249 offset:38912
	ds_read_b128 v[190:193], v249 offset:39936
	global_load_lds_dwordx4 v[218:219], off
	v_lshl_add_u64 v[218:219], s[18:19], 0, v[198:199]
	s_mov_b32 m0, s34
	s_nop 0
	global_load_lds_dwordx4 v[218:219], off
	s_waitcnt vmcnt(8)
	s_waitcnt lgkmcnt(0)
	s_barrier
	s_waitcnt lgkmcnt(0)
	v_mfma_f32_16x16x32_bf16 v[150:153], v[114:117], v[162:165], v[150:153]
	v_mfma_f32_16x16x32_bf16 v[150:153], v[118:121], v[166:169], v[150:153]
	v_mfma_f32_16x16x32_bf16 v[146:149], v[126:129], v[162:165], v[146:149]
	v_mfma_f32_16x16x32_bf16 v[146:149], v[134:137], v[166:169], v[146:149]
	v_mfma_f32_16x16x32_bf16 v[110:113], v[114:117], v[170:173], v[110:113]
	v_mfma_f32_16x16x32_bf16 v[110:113], v[118:121], v[174:177], v[110:113]
	v_mfma_f32_16x16x32_bf16 v[106:109], v[126:129], v[170:173], v[106:109]
	v_mfma_f32_16x16x32_bf16 v[106:109], v[134:137], v[174:177], v[106:109]
	v_mfma_f32_16x16x32_bf16 v[94:97], v[114:117], v[178:181], v[94:97]
	v_mfma_f32_16x16x32_bf16 v[94:97], v[118:121], v[182:185], v[94:97]
	v_mfma_f32_16x16x32_bf16 v[90:93], v[126:129], v[178:181], v[90:93]
	v_mfma_f32_16x16x32_bf16 v[90:93], v[134:137], v[182:185], v[90:93]
	v_mfma_f32_16x16x32_bf16 v[78:81], v[114:117], v[186:189], v[78:81]
	v_mfma_f32_16x16x32_bf16 v[78:81], v[118:121], v[190:193], v[78:81]
	v_mfma_f32_16x16x32_bf16 v[74:77], v[126:129], v[186:189], v[74:77]
	v_mfma_f32_16x16x32_bf16 v[74:77], v[134:137], v[190:193], v[74:77]
	v_mfma_f32_16x16x32_bf16 v[130:133], v[138:141], v[162:165], v[130:133]
	v_mfma_f32_16x16x32_bf16 v[130:133], v[142:145], v[166:169], v[130:133]
	v_mfma_f32_16x16x32_bf16 v[122:125], v[154:157], v[162:165], v[122:125]
	v_mfma_f32_16x16x32_bf16 v[122:125], v[158:161], v[166:169], v[122:125]
	v_mfma_f32_16x16x32_bf16 v[102:105], v[138:141], v[170:173], v[102:105]
	v_mfma_f32_16x16x32_bf16 v[102:105], v[142:145], v[174:177], v[102:105]
	v_mfma_f32_16x16x32_bf16 v[98:101], v[154:157], v[170:173], v[98:101]
	v_mfma_f32_16x16x32_bf16 v[98:101], v[158:161], v[174:177], v[98:101]
	v_mfma_f32_16x16x32_bf16 v[86:89], v[138:141], v[178:181], v[86:89]
	v_mfma_f32_16x16x32_bf16 v[86:89], v[142:145], v[182:185], v[86:89]
	v_mfma_f32_16x16x32_bf16 v[82:85], v[154:157], v[178:181], v[82:85]
	v_mfma_f32_16x16x32_bf16 v[82:85], v[158:161], v[182:185], v[82:85]
	v_mfma_f32_16x16x32_bf16 v[70:73], v[138:141], v[186:189], v[70:73]
	v_mfma_f32_16x16x32_bf16 v[70:73], v[142:145], v[190:193], v[70:73]
	v_mfma_f32_16x16x32_bf16 v[66:69], v[154:157], v[186:189], v[66:69]
	v_mfma_f32_16x16x32_bf16 v[66:69], v[158:161], v[190:193], v[66:69]
	s_barrier
	s_add_i32 s18, s67, s16
	v_lshl_add_u64 v[210:211], v[210:211], 0, s[12:13]
	s_mov_b32 m0, s18
	ds_read_b128 v[162:165], v249 offset:49152
	ds_read_b128 v[166:169], v249 offset:50176
	ds_read_b128 v[170:173], v249 offset:51200
	ds_read_b128 v[174:177], v249 offset:52224
	ds_read_b128 v[178:181], v249 offset:53248
	ds_read_b128 v[182:185], v249 offset:54272
	ds_read_b128 v[186:189], v249 offset:55296
	ds_read_b128 v[190:193], v249 offset:56320
	global_load_lds_dwordx4 v[210:211], off
	s_add_i32 m0, s18, 0x2000
	s_add_u32 s18, s26, 0x380080
	v_lshl_add_u64 v[210:211], v[212:213], 0, s[12:13]
	s_addc_u32 s19, s27, 0
	s_add_i32 s26, s68, s16
	global_load_lds_dwordx4 v[210:211], off
	v_lshl_add_u64 v[210:211], s[18:19], 0, v[196:197]
	s_mov_b32 m0, s26
	s_nop 0
	global_load_lds_dwordx4 v[210:211], off
	v_lshl_add_u64 v[210:211], s[18:19], 0, v[200:201]
	s_add_i32 m0, s26, 0x2000
	s_nop 0
	global_load_lds_dwordx4 v[210:211], off
	v_lshl_add_u64 v[210:211], v[214:215], 0, s[12:13]
	s_mov_b32 m0, s38
	s_nop 0
	global_load_lds_dwordx4 v[210:211], off
	v_lshl_add_u64 v[210:211], v[216:217], 0, s[12:13]
	s_mov_b32 m0, s39
	s_nop 0
	global_load_lds_dwordx4 v[210:211], off
	s_waitcnt vmcnt(8)
	s_waitcnt lgkmcnt(0)
	s_barrier
	s_waitcnt lgkmcnt(0)
	v_mfma_f32_16x16x32_bf16 v[62:65], v[114:117], v[162:165], v[62:65]
	v_mfma_f32_16x16x32_bf16 v[62:65], v[118:121], v[166:169], v[62:65]
	v_mfma_f32_16x16x32_bf16 v[58:61], v[126:129], v[162:165], v[58:61]
	v_mfma_f32_16x16x32_bf16 v[58:61], v[134:137], v[166:169], v[58:61]
	v_mfma_f32_16x16x32_bf16 v[46:49], v[114:117], v[170:173], v[46:49]
	v_mfma_f32_16x16x32_bf16 v[46:49], v[118:121], v[174:177], v[46:49]
	v_mfma_f32_16x16x32_bf16 v[42:45], v[126:129], v[170:173], v[42:45]
	v_mfma_f32_16x16x32_bf16 v[42:45], v[134:137], v[174:177], v[42:45]
	v_mfma_f32_16x16x32_bf16 v[30:33], v[114:117], v[178:181], v[30:33]
	v_mfma_f32_16x16x32_bf16 v[30:33], v[118:121], v[182:185], v[30:33]
	v_mfma_f32_16x16x32_bf16 v[26:29], v[126:129], v[178:181], v[26:29]
	v_mfma_f32_16x16x32_bf16 v[26:29], v[134:137], v[182:185], v[26:29]
	v_mfma_f32_16x16x32_bf16 v[14:17], v[114:117], v[186:189], v[14:17]
	v_mfma_f32_16x16x32_bf16 v[14:17], v[118:121], v[190:193], v[14:17]
	v_mfma_f32_16x16x32_bf16 v[10:13], v[126:129], v[186:189], v[10:13]
	v_mfma_f32_16x16x32_bf16 v[10:13], v[134:137], v[190:193], v[10:13]
	v_mfma_f32_16x16x32_bf16 v[54:57], v[138:141], v[162:165], v[54:57]
	v_mfma_f32_16x16x32_bf16 v[54:57], v[142:145], v[166:169], v[54:57]
	v_mfma_f32_16x16x32_bf16 v[50:53], v[154:157], v[162:165], v[50:53]
	v_mfma_f32_16x16x32_bf16 v[50:53], v[158:161], v[166:169], v[50:53]
	v_mfma_f32_16x16x32_bf16 v[38:41], v[138:141], v[170:173], v[38:41]
	v_mfma_f32_16x16x32_bf16 v[38:41], v[142:145], v[174:177], v[38:41]
	v_mfma_f32_16x16x32_bf16 v[34:37], v[154:157], v[170:173], v[34:37]
	v_mfma_f32_16x16x32_bf16 v[34:37], v[158:161], v[174:177], v[34:37]
	v_mfma_f32_16x16x32_bf16 v[22:25], v[138:141], v[178:181], v[22:25]
	v_mfma_f32_16x16x32_bf16 v[22:25], v[142:145], v[182:185], v[22:25]
	v_mfma_f32_16x16x32_bf16 v[18:21], v[154:157], v[178:181], v[18:21]
	v_mfma_f32_16x16x32_bf16 v[18:21], v[158:161], v[182:185], v[18:21]
	v_mfma_f32_16x16x32_bf16 v[6:9], v[138:141], v[186:189], v[6:9]
	v_mfma_f32_16x16x32_bf16 v[6:9], v[142:145], v[190:193], v[6:9]
	v_mfma_f32_16x16x32_bf16 v[2:5], v[154:157], v[186:189], v[2:5]
	v_mfma_f32_16x16x32_bf16 v[2:5], v[158:161], v[190:193], v[2:5]
	s_barrier
	s_add_i32 s66, s66, 2
	s_add_u32 s64, s64, 0x100
	s_addc_u32 s65, s65, 0
	s_cmpk_gt_u32 s66, 0xdd
	s_mov_b64 s[18:19], s[4:5]

.LBB0_1646:
	s_ashr_i32 s63, s62, 31
	s_lshl_b64 s[0:1], s[62:63], 21
	s_add_u32 s64, s52, s0
	s_addc_u32 s65, s53, s1
	s_and_b64 s[0:1], s[4:5], exec
	s_cselect_b32 s0, s65, s11
	s_cselect_b32 s1, s64, s10
	s_ashr_i32 s61, s60, 31
	s_lshl_b64 s[16:17], s[60:61], 21
	s_add_u32 s66, s31, s16
	s_addc_u32 s67, s35, s17
	s_and_b64 s[16:17], s[4:5], exec
	s_cselect_b32 s7, s67, s19
	s_cselect_b32 s9, s66, s18
	s_add_u32 s10, s10, 0x100080
	s_addc_u32 s11, s11, 0
	s_add_u32 s16, s18, 0x100
	s_addc_u32 s17, s19, 0
	s_mov_b32 s61, -2
	s_waitcnt lgkmcnt(0)
	ds_read_b128 v[30:33], v200
	ds_read_b128 v[38:41], v200 offset:1024
	ds_read_b128 v[42:45], v200 offset:2048
	ds_read_b128 v[50:53], v200 offset:3072
	ds_read_b128 v[164:167], v201
	ds_read_b128 v[168:171], v201 offset:1024
	ds_read_b128 v[172:175], v201 offset:2048
	ds_read_b128 v[176:179], v201 offset:3072
	s_add_u32 s18, s10, 0xfff00080
	s_addc_u32 s19, s11, -1
	s_cmp_eq_u32 s61, 60
	s_cselect_b32 s69, s0, s19
	s_cselect_b32 s68, s1, s18
	s_cselect_b32 s19, s7, s17
	s_cselect_b32 s18, s9, s16
	v_lshl_add_u64 v[222:223], s[10:11], 0, v[156:157]
	s_add_i32 m0, s39, 0xc000
	ds_read_b128 v[180:183], v202
	ds_read_b128 v[184:187], v202 offset:1024
	ds_read_b128 v[188:191], v202 offset:2048
	ds_read_b128 v[192:195], v202 offset:3072
	ds_read_b128 v[206:209], v202 offset:4096
	ds_read_b128 v[210:213], v202 offset:5120
	ds_read_b128 v[214:217], v202 offset:6144
	ds_read_b128 v[218:221], v202 offset:7168
	global_load_lds_dwordx4 v[222:223], off
	v_lshl_add_u64 v[222:223], s[10:11], 0, v[158:159]
	s_add_i32 m0, s39, 0xe000
	s_nop 0
	global_load_lds_dwordx4 v[222:223], off
	s_waitcnt vmcnt(8)
	s_waitcnt lgkmcnt(0)
	s_barrier
	s_waitcnt lgkmcnt(0)
	v_mfma_f32_16x16x32_bf16 v[138:141], v[30:33], v[180:183], 0
	v_mfma_f32_16x16x32_bf16 v[138:141], v[38:41], v[184:187], v[138:141]
	v_mfma_f32_16x16x32_bf16 v[142:145], v[42:45], v[180:183], 0
	v_mfma_f32_16x16x32_bf16 v[142:145], v[50:53], v[184:187], v[142:145]
	v_mfma_f32_16x16x32_bf16 v[122:125], v[30:33], v[188:191], 0
	v_mfma_f32_16x16x32_bf16 v[122:125], v[38:41], v[192:195], v[122:125]
	v_mfma_f32_16x16x32_bf16 v[126:129], v[42:45], v[188:191], 0
	v_mfma_f32_16x16x32_bf16 v[126:129], v[50:53], v[192:195], v[126:129]
	v_mfma_f32_16x16x32_bf16 v[106:109], v[30:33], v[206:209], 0
	v_mfma_f32_16x16x32_bf16 v[106:109], v[38:41], v[210:213], v[106:109]
	v_mfma_f32_16x16x32_bf16 v[110:113], v[42:45], v[206:209], 0
	v_mfma_f32_16x16x32_bf16 v[110:113], v[50:53], v[210:213], v[110:113]
	v_mfma_f32_16x16x32_bf16 v[90:93], v[30:33], v[214:217], 0
	v_mfma_f32_16x16x32_bf16 v[90:93], v[38:41], v[218:221], v[90:93]
	v_mfma_f32_16x16x32_bf16 v[94:97], v[42:45], v[214:217], 0
	v_mfma_f32_16x16x32_bf16 v[94:97], v[50:53], v[218:221], v[94:97]
	v_mfma_f32_16x16x32_bf16 v[130:133], v[164:167], v[180:183], 0
	v_mfma_f32_16x16x32_bf16 v[130:133], v[168:171], v[184:187], v[130:133]
	v_mfma_f32_16x16x32_bf16 v[134:137], v[172:175], v[180:183], 0
	v_mfma_f32_16x16x32_bf16 v[134:137], v[176:179], v[184:187], v[134:137]
	v_mfma_f32_16x16x32_bf16 v[114:117], v[164:167], v[188:191], 0
	v_mfma_f32_16x16x32_bf16 v[114:117], v[168:171], v[192:195], v[114:117]
	v_mfma_f32_16x16x32_bf16 v[118:121], v[172:175], v[188:191], 0
	v_mfma_f32_16x16x32_bf16 v[118:121], v[176:179], v[192:195], v[118:121]
	v_mfma_f32_16x16x32_bf16 v[98:101], v[164:167], v[206:209], 0
	v_mfma_f32_16x16x32_bf16 v[98:101], v[168:171], v[210:213], v[98:101]
	v_mfma_f32_16x16x32_bf16 v[102:105], v[172:175], v[206:209], 0
	v_mfma_f32_16x16x32_bf16 v[102:105], v[176:179], v[210:213], v[102:105]
	v_mfma_f32_16x16x32_bf16 v[82:85], v[164:167], v[214:217], 0
	v_mfma_f32_16x16x32_bf16 v[82:85], v[168:171], v[218:221], v[82:85]
	v_mfma_f32_16x16x32_bf16 v[86:89], v[172:175], v[214:217], 0
	v_mfma_f32_16x16x32_bf16 v[86:89], v[176:179], v[218:221], v[86:89]
	s_barrier
	s_add_i32 s63, s77, s37
	v_lshl_add_u64 v[222:223], s[18:19], 0, v[148:149]
	s_mov_b32 m0, s63
	ds_read_b128 v[180:183], v202 offset:16384
	ds_read_b128 v[184:187], v202 offset:17408
	ds_read_b128 v[188:191], v202 offset:18432
	ds_read_b128 v[192:195], v202 offset:19456
	ds_read_b128 v[206:209], v202 offset:20480
	ds_read_b128 v[210:213], v202 offset:21504
	ds_read_b128 v[214:217], v202 offset:22528
	ds_read_b128 v[218:221], v202 offset:23552
	global_load_lds_dwordx4 v[222:223], off
	s_add_i32 m0, s63, 0x2000
	s_add_u32 s82, s18, 0x100000
	v_lshl_add_u64 v[224:225], s[18:19], 0, v[152:153]
	s_addc_u32 s83, s19, 0
	s_add_i32 s63, s78, s37
	global_load_lds_dwordx4 v[224:225], off
	v_lshl_add_u64 v[226:227], s[82:83], 0, v[148:149]
	s_mov_b32 m0, s63
	v_lshl_add_u64 v[228:229], s[68:69], 0, v[150:151]
	global_load_lds_dwordx4 v[226:227], off
	v_lshl_add_u64 v[226:227], s[82:83], 0, v[152:153]
	s_add_i32 m0, s63, 0x2000
	s_nop 0
	global_load_lds_dwordx4 v[226:227], off
	v_lshl_add_u64 v[226:227], s[68:69], 0, v[146:147]
	s_mov_b32 m0, s39
	s_nop 0
	global_load_lds_dwordx4 v[226:227], off
	s_mov_b32 m0, s41
	s_nop 0
	global_load_lds_dwordx4 v[228:229], off
	s_waitcnt vmcnt(8)
	s_waitcnt lgkmcnt(0)
	s_barrier
	s_waitcnt lgkmcnt(0)
	v_mfma_f32_16x16x32_bf16 v[74:77], v[30:33], v[180:183], 0
	v_mfma_f32_16x16x32_bf16 v[74:77], v[38:41], v[184:187], v[74:77]
	v_mfma_f32_16x16x32_bf16 v[78:81], v[42:45], v[180:183], 0
	v_mfma_f32_16x16x32_bf16 v[78:81], v[50:53], v[184:187], v[78:81]
	v_mfma_f32_16x16x32_bf16 v[58:61], v[30:33], v[188:191], 0
	v_mfma_f32_16x16x32_bf16 v[58:61], v[38:41], v[192:195], v[58:61]
	v_mfma_f32_16x16x32_bf16 v[62:65], v[42:45], v[188:191], 0
	v_mfma_f32_16x16x32_bf16 v[62:65], v[50:53], v[192:195], v[62:65]
	v_mfma_f32_16x16x32_bf16 v[26:29], v[30:33], v[206:209], 0
	v_mfma_f32_16x16x32_bf16 v[26:29], v[38:41], v[210:213], v[26:29]
	v_mfma_f32_16x16x32_bf16 v[34:37], v[42:45], v[206:209], 0
	v_mfma_f32_16x16x32_bf16 v[34:37], v[50:53], v[210:213], v[34:37]
	v_mfma_f32_16x16x32_bf16 v[10:13], v[30:33], v[214:217], 0
	v_mfma_f32_16x16x32_bf16 v[10:13], v[38:41], v[218:221], v[10:13]
	v_mfma_f32_16x16x32_bf16 v[14:17], v[42:45], v[214:217], 0
	v_mfma_f32_16x16x32_bf16 v[14:17], v[50:53], v[218:221], v[14:17]
	v_mfma_f32_16x16x32_bf16 v[18:21], v[164:167], v[206:209], 0
	v_mfma_f32_16x16x32_bf16 v[18:21], v[168:171], v[210:213], v[18:21]
	v_mfma_f32_16x16x32_bf16 v[22:25], v[172:175], v[206:209], 0
	v_mfma_f32_16x16x32_bf16 v[22:25], v[176:179], v[210:213], v[22:25]
	v_mfma_f32_16x16x32_bf16 v[2:5], v[164:167], v[214:217], 0
	v_mfma_f32_16x16x32_bf16 v[2:5], v[168:171], v[218:221], v[2:5]
	v_mfma_f32_16x16x32_bf16 v[6:9], v[172:175], v[214:217], 0
	v_mfma_f32_16x16x32_bf16 v[6:9], v[176:179], v[218:221], v[6:9]
	v_mfma_f32_16x16x32_bf16 v[30:33], v[164:167], v[180:183], 0
	v_mfma_f32_16x16x32_bf16 v[30:33], v[168:171], v[184:187], v[30:33]
	v_mfma_f32_16x16x32_bf16 v[38:41], v[172:175], v[180:183], 0
	v_mfma_f32_16x16x32_bf16 v[38:41], v[176:179], v[184:187], v[38:41]
	v_mfma_f32_16x16x32_bf16 v[42:45], v[164:167], v[188:191], 0
	v_mfma_f32_16x16x32_bf16 v[42:45], v[168:171], v[192:195], v[42:45]
	v_mfma_f32_16x16x32_bf16 v[46:49], v[172:175], v[188:191], 0
	v_mfma_f32_16x16x32_bf16 v[50:53], v[176:179], v[192:195], v[46:49]
	s_barrier
	s_add_i32 s63, 0, 0x18000
	s_add_i32 s82, 0, 0x1c000
	v_add_u32_e32 v70, s63, v196
	v_add_u32_e32 v155, s82, v196
	ds_read_b128 v[46:49], v70
	ds_read_b128 v[54:57], v70 offset:1024
	ds_read_b128 v[66:69], v70 offset:2048
	ds_read_b128 v[70:73], v70 offset:3072
	ds_read_b128 v[164:167], v155
	ds_read_b128 v[168:171], v155 offset:1024
	ds_read_b128 v[172:175], v155 offset:2048
	ds_read_b128 v[176:179], v155 offset:3072
	s_add_u32 s68, s68, 0x100000
	s_addc_u32 s69, s69, 0
	s_mov_b32 m0, s43
	v_lshl_add_u64 v[230:231], s[68:69], 0, v[146:147]
	ds_read_b128 v[180:183], v202 offset:32768
	ds_read_b128 v[184:187], v202 offset:33792
	ds_read_b128 v[188:191], v202 offset:34816
	ds_read_b128 v[192:195], v202 offset:35840
	ds_read_b128 v[206:209], v202 offset:36864
	ds_read_b128 v[210:213], v202 offset:37888
	ds_read_b128 v[214:217], v202 offset:38912
	ds_read_b128 v[218:221], v202 offset:39936
	global_load_lds_dwordx4 v[230:231], off
	v_lshl_add_u64 v[230:231], s[68:69], 0, v[150:151]
	s_mov_b32 m0, s57
	s_nop 0
	global_load_lds_dwordx4 v[230:231], off
	s_waitcnt vmcnt(8)
	s_waitcnt lgkmcnt(0)
	s_barrier
	s_waitcnt lgkmcnt(0)
	v_mfma_f32_16x16x32_bf16 v[138:141], v[46:49], v[180:183], v[138:141]
	v_mfma_f32_16x16x32_bf16 v[138:141], v[54:57], v[184:187], v[138:141]
	v_mfma_f32_16x16x32_bf16 v[142:145], v[66:69], v[180:183], v[142:145]
	v_mfma_f32_16x16x32_bf16 v[142:145], v[70:73], v[184:187], v[142:145]
	v_mfma_f32_16x16x32_bf16 v[122:125], v[46:49], v[188:191], v[122:125]
	v_mfma_f32_16x16x32_bf16 v[122:125], v[54:57], v[192:195], v[122:125]
	v_mfma_f32_16x16x32_bf16 v[126:129], v[66:69], v[188:191], v[126:129]
	v_mfma_f32_16x16x32_bf16 v[126:129], v[70:73], v[192:195], v[126:129]
	v_mfma_f32_16x16x32_bf16 v[106:109], v[46:49], v[206:209], v[106:109]
	v_mfma_f32_16x16x32_bf16 v[106:109], v[54:57], v[210:213], v[106:109]
	v_mfma_f32_16x16x32_bf16 v[110:113], v[66:69], v[206:209], v[110:113]
	v_mfma_f32_16x16x32_bf16 v[110:113], v[70:73], v[210:213], v[110:113]
	v_mfma_f32_16x16x32_bf16 v[90:93], v[46:49], v[214:217], v[90:93]
	v_mfma_f32_16x16x32_bf16 v[90:93], v[54:57], v[218:221], v[90:93]
	v_mfma_f32_16x16x32_bf16 v[94:97], v[66:69], v[214:217], v[94:97]
	v_mfma_f32_16x16x32_bf16 v[94:97], v[70:73], v[218:221], v[94:97]
	v_mfma_f32_16x16x32_bf16 v[130:133], v[164:167], v[180:183], v[130:133]
	v_mfma_f32_16x16x32_bf16 v[130:133], v[168:171], v[184:187], v[130:133]
	v_mfma_f32_16x16x32_bf16 v[134:137], v[172:175], v[180:183], v[134:137]
	v_mfma_f32_16x16x32_bf16 v[134:137], v[176:179], v[184:187], v[134:137]
	v_mfma_f32_16x16x32_bf16 v[114:117], v[164:167], v[188:191], v[114:117]
	v_mfma_f32_16x16x32_bf16 v[114:117], v[168:171], v[192:195], v[114:117]
	v_mfma_f32_16x16x32_bf16 v[118:121], v[172:175], v[188:191], v[118:121]
	v_mfma_f32_16x16x32_bf16 v[118:121], v[176:179], v[192:195], v[118:121]
	v_mfma_f32_16x16x32_bf16 v[98:101], v[164:167], v[206:209], v[98:101]
	v_mfma_f32_16x16x32_bf16 v[98:101], v[168:171], v[210:213], v[98:101]
	v_mfma_f32_16x16x32_bf16 v[102:105], v[172:175], v[206:209], v[102:105]
	v_mfma_f32_16x16x32_bf16 v[102:105], v[176:179], v[210:213], v[102:105]
	v_mfma_f32_16x16x32_bf16 v[82:85], v[164:167], v[214:217], v[82:85]
	v_mfma_f32_16x16x32_bf16 v[82:85], v[168:171], v[218:221], v[82:85]
	v_mfma_f32_16x16x32_bf16 v[86:89], v[172:175], v[214:217], v[86:89]
	v_mfma_f32_16x16x32_bf16 v[86:89], v[176:179], v[218:221], v[86:89]
	s_barrier
	s_add_i32 s63, s63, s37
	v_lshl_add_u64 v[222:223], v[222:223], 0, s[26:27]
	s_mov_b32 m0, s63
	ds_read_b128 v[180:183], v202 offset:49152
	ds_read_b128 v[184:187], v202 offset:50176
	ds_read_b128 v[188:191], v202 offset:51200
	ds_read_b128 v[192:195], v202 offset:52224
	ds_read_b128 v[206:209], v202 offset:53248
	ds_read_b128 v[210:213], v202 offset:54272
	ds_read_b128 v[214:217], v202 offset:55296
	ds_read_b128 v[218:221], v202 offset:56320
	global_load_lds_dwordx4 v[222:223], off
	s_add_i32 m0, s63, 0x2000
	s_add_u32 s18, s18, 0x100080
	v_lshl_add_u64 v[222:223], v[224:225], 0, s[26:27]
	s_addc_u32 s19, s19, 0
	s_add_i32 s63, s82, s37
	global_load_lds_dwordx4 v[222:223], off
	v_lshl_add_u64 v[222:223], s[18:19], 0, v[148:149]
	s_mov_b32 m0, s63
	s_nop 0
	global_load_lds_dwordx4 v[222:223], off
	v_lshl_add_u64 v[222:223], s[18:19], 0, v[152:153]
	s_add_i32 m0, s63, 0x2000
	s_nop 0
	global_load_lds_dwordx4 v[222:223], off
	v_lshl_add_u64 v[222:223], v[226:227], 0, s[26:27]
	s_mov_b32 m0, s71
	s_nop 0
	global_load_lds_dwordx4 v[222:223], off
	v_lshl_add_u64 v[222:223], v[228:229], 0, s[26:27]
	s_mov_b32 m0, s72
	s_nop 0
	global_load_lds_dwordx4 v[222:223], off
	s_waitcnt vmcnt(8)
	s_waitcnt lgkmcnt(0)
	s_barrier
	s_waitcnt lgkmcnt(0)
	v_mfma_f32_16x16x32_bf16 v[74:77], v[46:49], v[180:183], v[74:77]
	v_mfma_f32_16x16x32_bf16 v[74:77], v[54:57], v[184:187], v[74:77]
	v_mfma_f32_16x16x32_bf16 v[78:81], v[66:69], v[180:183], v[78:81]
	v_mfma_f32_16x16x32_bf16 v[78:81], v[70:73], v[184:187], v[78:81]
	v_mfma_f32_16x16x32_bf16 v[58:61], v[46:49], v[188:191], v[58:61]
	v_mfma_f32_16x16x32_bf16 v[58:61], v[54:57], v[192:195], v[58:61]
	v_mfma_f32_16x16x32_bf16 v[62:65], v[66:69], v[188:191], v[62:65]
	v_mfma_f32_16x16x32_bf16 v[62:65], v[70:73], v[192:195], v[62:65]
	v_mfma_f32_16x16x32_bf16 v[26:29], v[46:49], v[206:209], v[26:29]
	v_mfma_f32_16x16x32_bf16 v[26:29], v[54:57], v[210:213], v[26:29]
	v_mfma_f32_16x16x32_bf16 v[34:37], v[66:69], v[206:209], v[34:37]
	v_mfma_f32_16x16x32_bf16 v[34:37], v[70:73], v[210:213], v[34:37]
	v_mfma_f32_16x16x32_bf16 v[10:13], v[46:49], v[214:217], v[10:13]
	v_mfma_f32_16x16x32_bf16 v[10:13], v[54:57], v[218:221], v[10:13]
	v_mfma_f32_16x16x32_bf16 v[14:17], v[66:69], v[214:217], v[14:17]
	v_mfma_f32_16x16x32_bf16 v[14:17], v[70:73], v[218:221], v[14:17]
	v_mfma_f32_16x16x32_bf16 v[30:33], v[164:167], v[180:183], v[30:33]
	v_mfma_f32_16x16x32_bf16 v[66:69], v[168:171], v[184:187], v[30:33]
	v_mfma_f32_16x16x32_bf16 v[30:33], v[172:175], v[180:183], v[38:41]
	v_mfma_f32_16x16x32_bf16 v[70:73], v[176:179], v[184:187], v[30:33]
	v_mfma_f32_16x16x32_bf16 v[30:33], v[164:167], v[188:191], v[42:45]
	v_mfma_f32_16x16x32_bf16 v[46:49], v[168:171], v[192:195], v[30:33]
	v_mfma_f32_16x16x32_bf16 v[30:33], v[172:175], v[188:191], v[50:53]
	v_mfma_f32_16x16x32_bf16 v[54:57], v[176:179], v[192:195], v[30:33]
	v_mfma_f32_16x16x32_bf16 v[18:21], v[164:167], v[206:209], v[18:21]
	v_mfma_f32_16x16x32_bf16 v[18:21], v[168:171], v[210:213], v[18:21]
	v_mfma_f32_16x16x32_bf16 v[22:25], v[172:175], v[206:209], v[22:25]
	v_mfma_f32_16x16x32_bf16 v[22:25], v[176:179], v[210:213], v[22:25]
	v_mfma_f32_16x16x32_bf16 v[2:5], v[164:167], v[214:217], v[2:5]
	v_mfma_f32_16x16x32_bf16 v[2:5], v[168:171], v[218:221], v[2:5]
	v_mfma_f32_16x16x32_bf16 v[6:9], v[172:175], v[214:217], v[6:9]
	v_mfma_f32_16x16x32_bf16 v[6:9], v[176:179], v[218:221], v[6:9]
	s_barrier
	s_add_i32 s61, s61, 2
	s_add_u32 s10, s10, 0x100
	s_addc_u32 s11, s11, 0
	s_add_u32 s16, s16, 0x100
	s_addc_u32 s17, s17, 0
	s_cmp_gt_u32 s61, 61
.LBB0_1647:
	ds_read_b128 v[30:33], v200
	ds_read_b128 v[38:41], v200 offset:1024
	ds_read_b128 v[42:45], v200 offset:2048
	ds_read_b128 v[50:53], v200 offset:3072
	ds_read_b128 v[164:167], v201
	ds_read_b128 v[168:171], v201 offset:1024
	ds_read_b128 v[172:175], v201 offset:2048
	ds_read_b128 v[176:179], v201 offset:3072
	s_add_u32 s18, s10, 0xfff00080
	s_addc_u32 s19, s11, -1
	s_cmp_eq_u32 s61, 60
	s_cselect_b32 s69, s0, s19
	s_cselect_b32 s68, s1, s18
	s_cselect_b32 s19, s7, s17
	s_cselect_b32 s18, s9, s16
	v_lshl_add_u64 v[222:223], s[10:11], 0, v[156:157]
	s_add_i32 m0, s39, 0xc000
	ds_read_b128 v[180:183], v202
	ds_read_b128 v[184:187], v202 offset:1024
	ds_read_b128 v[188:191], v202 offset:2048
	ds_read_b128 v[192:195], v202 offset:3072
	ds_read_b128 v[206:209], v202 offset:4096
	ds_read_b128 v[210:213], v202 offset:5120
	ds_read_b128 v[214:217], v202 offset:6144
	ds_read_b128 v[218:221], v202 offset:7168
	global_load_lds_dwordx4 v[222:223], off
	v_lshl_add_u64 v[222:223], s[10:11], 0, v[158:159]
	s_add_i32 m0, s39, 0xe000
	s_nop 0
	global_load_lds_dwordx4 v[222:223], off
	s_waitcnt vmcnt(8)
	s_waitcnt lgkmcnt(0)
	s_barrier
	s_waitcnt lgkmcnt(0)
	v_mfma_f32_16x16x32_bf16 v[138:141], v[30:33], v[180:183], v[138:141]
	v_mfma_f32_16x16x32_bf16 v[138:141], v[38:41], v[184:187], v[138:141]
	v_mfma_f32_16x16x32_bf16 v[142:145], v[42:45], v[180:183], v[142:145]
	v_mfma_f32_16x16x32_bf16 v[142:145], v[50:53], v[184:187], v[142:145]
	v_mfma_f32_16x16x32_bf16 v[122:125], v[30:33], v[188:191], v[122:125]
	v_mfma_f32_16x16x32_bf16 v[122:125], v[38:41], v[192:195], v[122:125]
	v_mfma_f32_16x16x32_bf16 v[126:129], v[42:45], v[188:191], v[126:129]
	v_mfma_f32_16x16x32_bf16 v[126:129], v[50:53], v[192:195], v[126:129]
	v_mfma_f32_16x16x32_bf16 v[106:109], v[30:33], v[206:209], v[106:109]
	v_mfma_f32_16x16x32_bf16 v[106:109], v[38:41], v[210:213], v[106:109]
	v_mfma_f32_16x16x32_bf16 v[110:113], v[42:45], v[206:209], v[110:113]
	v_mfma_f32_16x16x32_bf16 v[110:113], v[50:53], v[210:213], v[110:113]
	v_mfma_f32_16x16x32_bf16 v[90:93], v[30:33], v[214:217], v[90:93]
	v_mfma_f32_16x16x32_bf16 v[90:93], v[38:41], v[218:221], v[90:93]
	v_mfma_f32_16x16x32_bf16 v[94:97], v[42:45], v[214:217], v[94:97]
	v_mfma_f32_16x16x32_bf16 v[94:97], v[50:53], v[218:221], v[94:97]
	v_mfma_f32_16x16x32_bf16 v[130:133], v[164:167], v[180:183], v[130:133]
	v_mfma_f32_16x16x32_bf16 v[130:133], v[168:171], v[184:187], v[130:133]
	v_mfma_f32_16x16x32_bf16 v[134:137], v[172:175], v[180:183], v[134:137]
	v_mfma_f32_16x16x32_bf16 v[134:137], v[176:179], v[184:187], v[134:137]
	v_mfma_f32_16x16x32_bf16 v[114:117], v[164:167], v[188:191], v[114:117]
	v_mfma_f32_16x16x32_bf16 v[114:117], v[168:171], v[192:195], v[114:117]
	v_mfma_f32_16x16x32_bf16 v[118:121], v[172:175], v[188:191], v[118:121]
	v_mfma_f32_16x16x32_bf16 v[118:121], v[176:179], v[192:195], v[118:121]
	v_mfma_f32_16x16x32_bf16 v[98:101], v[164:167], v[206:209], v[98:101]
	v_mfma_f32_16x16x32_bf16 v[98:101], v[168:171], v[210:213], v[98:101]
	v_mfma_f32_16x16x32_bf16 v[102:105], v[172:175], v[206:209], v[102:105]
	v_mfma_f32_16x16x32_bf16 v[102:105], v[176:179], v[210:213], v[102:105]
	v_mfma_f32_16x16x32_bf16 v[82:85], v[164:167], v[214:217], v[82:85]
	v_mfma_f32_16x16x32_bf16 v[82:85], v[168:171], v[218:221], v[82:85]
	v_mfma_f32_16x16x32_bf16 v[86:89], v[172:175], v[214:217], v[86:89]
	v_mfma_f32_16x16x32_bf16 v[86:89], v[176:179], v[218:221], v[86:89]
	s_barrier
	s_add_i32 s63, s77, s37
	v_lshl_add_u64 v[222:223], s[18:19], 0, v[148:149]
	s_mov_b32 m0, s63
	ds_read_b128 v[180:183], v202 offset:16384
	ds_read_b128 v[184:187], v202 offset:17408
	ds_read_b128 v[188:191], v202 offset:18432
	ds_read_b128 v[192:195], v202 offset:19456
	ds_read_b128 v[206:209], v202 offset:20480
	ds_read_b128 v[210:213], v202 offset:21504
	ds_read_b128 v[214:217], v202 offset:22528
	ds_read_b128 v[218:221], v202 offset:23552
	global_load_lds_dwordx4 v[222:223], off
	s_add_i32 m0, s63, 0x2000
	s_add_u32 s82, s18, 0x100000
	v_lshl_add_u64 v[224:225], s[18:19], 0, v[152:153]
	s_addc_u32 s83, s19, 0
	s_add_i32 s63, s78, s37
	global_load_lds_dwordx4 v[224:225], off
	v_lshl_add_u64 v[226:227], s[82:83], 0, v[148:149]
	s_mov_b32 m0, s63
	v_lshl_add_u64 v[228:229], s[68:69], 0, v[150:151]
	global_load_lds_dwordx4 v[226:227], off
	v_lshl_add_u64 v[226:227], s[82:83], 0, v[152:153]
	s_add_i32 m0, s63, 0x2000
	s_nop 0
	global_load_lds_dwordx4 v[226:227], off
	v_lshl_add_u64 v[226:227], s[68:69], 0, v[146:147]
	s_mov_b32 m0, s39
	s_nop 0
	global_load_lds_dwordx4 v[226:227], off
	s_mov_b32 m0, s41
	s_nop 0
	global_load_lds_dwordx4 v[228:229], off
	s_waitcnt vmcnt(8)
	s_waitcnt lgkmcnt(0)
	s_barrier
	s_waitcnt lgkmcnt(0)
	v_mfma_f32_16x16x32_bf16 v[74:77], v[30:33], v[180:183], v[74:77]
	v_mfma_f32_16x16x32_bf16 v[74:77], v[38:41], v[184:187], v[74:77]
	v_mfma_f32_16x16x32_bf16 v[78:81], v[42:45], v[180:183], v[78:81]
	v_mfma_f32_16x16x32_bf16 v[78:81], v[50:53], v[184:187], v[78:81]
	v_mfma_f32_16x16x32_bf16 v[58:61], v[30:33], v[188:191], v[58:61]
	v_mfma_f32_16x16x32_bf16 v[58:61], v[38:41], v[192:195], v[58:61]
	v_mfma_f32_16x16x32_bf16 v[62:65], v[42:45], v[188:191], v[62:65]
	v_mfma_f32_16x16x32_bf16 v[62:65], v[50:53], v[192:195], v[62:65]
	v_mfma_f32_16x16x32_bf16 v[26:29], v[30:33], v[206:209], v[26:29]
	v_mfma_f32_16x16x32_bf16 v[26:29], v[38:41], v[210:213], v[26:29]
	v_mfma_f32_16x16x32_bf16 v[34:37], v[42:45], v[206:209], v[34:37]
	v_mfma_f32_16x16x32_bf16 v[34:37], v[50:53], v[210:213], v[34:37]
	v_mfma_f32_16x16x32_bf16 v[10:13], v[30:33], v[214:217], v[10:13]
	v_mfma_f32_16x16x32_bf16 v[10:13], v[38:41], v[218:221], v[10:13]
	v_mfma_f32_16x16x32_bf16 v[14:17], v[42:45], v[214:217], v[14:17]
	v_mfma_f32_16x16x32_bf16 v[14:17], v[50:53], v[218:221], v[14:17]
	v_mfma_f32_16x16x32_bf16 v[18:21], v[164:167], v[206:209], v[18:21]
	v_mfma_f32_16x16x32_bf16 v[18:21], v[168:171], v[210:213], v[18:21]
	v_mfma_f32_16x16x32_bf16 v[22:25], v[172:175], v[206:209], v[22:25]
	v_mfma_f32_16x16x32_bf16 v[22:25], v[176:179], v[210:213], v[22:25]
	v_mfma_f32_16x16x32_bf16 v[2:5], v[164:167], v[214:217], v[2:5]
	v_mfma_f32_16x16x32_bf16 v[2:5], v[168:171], v[218:221], v[2:5]
	v_mfma_f32_16x16x32_bf16 v[6:9], v[172:175], v[214:217], v[6:9]
	v_mfma_f32_16x16x32_bf16 v[6:9], v[176:179], v[218:221], v[6:9]
	v_mfma_f32_16x16x32_bf16 v[30:33], v[164:167], v[180:183], v[66:69]
	v_mfma_f32_16x16x32_bf16 v[30:33], v[168:171], v[184:187], v[30:33]
	v_mfma_f32_16x16x32_bf16 v[38:41], v[172:175], v[180:183], v[70:73]
	v_mfma_f32_16x16x32_bf16 v[38:41], v[176:179], v[184:187], v[38:41]
	v_mfma_f32_16x16x32_bf16 v[42:45], v[164:167], v[188:191], v[46:49]
	v_mfma_f32_16x16x32_bf16 v[42:45], v[168:171], v[192:195], v[42:45]
	v_mfma_f32_16x16x32_bf16 v[46:49], v[172:175], v[188:191], v[54:57]
	v_mfma_f32_16x16x32_bf16 v[50:53], v[176:179], v[192:195], v[46:49]
	s_barrier
	s_add_i32 s63, 0, 0x18000
	s_add_i32 s82, 0, 0x1c000
	v_add_u32_e32 v70, s63, v196
	v_add_u32_e32 v155, s82, v196
	ds_read_b128 v[46:49], v70
	ds_read_b128 v[54:57], v70 offset:1024
	ds_read_b128 v[66:69], v70 offset:2048
	ds_read_b128 v[70:73], v70 offset:3072
	ds_read_b128 v[164:167], v155
	ds_read_b128 v[168:171], v155 offset:1024
	ds_read_b128 v[172:175], v155 offset:2048
	ds_read_b128 v[176:179], v155 offset:3072
	s_add_u32 s68, s68, 0x100000
	s_addc_u32 s69, s69, 0
	s_mov_b32 m0, s43
	v_lshl_add_u64 v[230:231], s[68:69], 0, v[146:147]
	ds_read_b128 v[180:183], v202 offset:32768
	ds_read_b128 v[184:187], v202 offset:33792
	ds_read_b128 v[188:191], v202 offset:34816
	ds_read_b128 v[192:195], v202 offset:35840
	ds_read_b128 v[206:209], v202 offset:36864
	ds_read_b128 v[210:213], v202 offset:37888
	ds_read_b128 v[214:217], v202 offset:38912
	ds_read_b128 v[218:221], v202 offset:39936
	global_load_lds_dwordx4 v[230:231], off
	v_lshl_add_u64 v[230:231], s[68:69], 0, v[150:151]
	s_mov_b32 m0, s57
	s_nop 0
	global_load_lds_dwordx4 v[230:231], off
	s_waitcnt vmcnt(8)
	s_waitcnt lgkmcnt(0)
	s_barrier
	s_waitcnt lgkmcnt(0)
	v_mfma_f32_16x16x32_bf16 v[138:141], v[46:49], v[180:183], v[138:141]
	v_mfma_f32_16x16x32_bf16 v[138:141], v[54:57], v[184:187], v[138:141]
	v_mfma_f32_16x16x32_bf16 v[142:145], v[66:69], v[180:183], v[142:145]
	v_mfma_f32_16x16x32_bf16 v[142:145], v[70:73], v[184:187], v[142:145]
	v_mfma_f32_16x16x32_bf16 v[122:125], v[46:49], v[188:191], v[122:125]
	v_mfma_f32_16x16x32_bf16 v[122:125], v[54:57], v[192:195], v[122:125]
	v_mfma_f32_16x16x32_bf16 v[126:129], v[66:69], v[188:191], v[126:129]
	v_mfma_f32_16x16x32_bf16 v[126:129], v[70:73], v[192:195], v[126:129]
	v_mfma_f32_16x16x32_bf16 v[106:109], v[46:49], v[206:209], v[106:109]
	v_mfma_f32_16x16x32_bf16 v[106:109], v[54:57], v[210:213], v[106:109]
	v_mfma_f32_16x16x32_bf16 v[110:113], v[66:69], v[206:209], v[110:113]
	v_mfma_f32_16x16x32_bf16 v[110:113], v[70:73], v[210:213], v[110:113]
	v_mfma_f32_16x16x32_bf16 v[90:93], v[46:49], v[214:217], v[90:93]
	v_mfma_f32_16x16x32_bf16 v[90:93], v[54:57], v[218:221], v[90:93]
	v_mfma_f32_16x16x32_bf16 v[94:97], v[66:69], v[214:217], v[94:97]
	v_mfma_f32_16x16x32_bf16 v[94:97], v[70:73], v[218:221], v[94:97]
	v_mfma_f32_16x16x32_bf16 v[130:133], v[164:167], v[180:183], v[130:133]
	v_mfma_f32_16x16x32_bf16 v[130:133], v[168:171], v[184:187], v[130:133]
	v_mfma_f32_16x16x32_bf16 v[134:137], v[172:175], v[180:183], v[134:137]
	v_mfma_f32_16x16x32_bf16 v[134:137], v[176:179], v[184:187], v[134:137]
	v_mfma_f32_16x16x32_bf16 v[114:117], v[164:167], v[188:191], v[114:117]
	v_mfma_f32_16x16x32_bf16 v[114:117], v[168:171], v[192:195], v[114:117]
	v_mfma_f32_16x16x32_bf16 v[118:121], v[172:175], v[188:191], v[118:121]
	v_mfma_f32_16x16x32_bf16 v[118:121], v[176:179], v[192:195], v[118:121]
	v_mfma_f32_16x16x32_bf16 v[98:101], v[164:167], v[206:209], v[98:101]
	v_mfma_f32_16x16x32_bf16 v[98:101], v[168:171], v[210:213], v[98:101]
	v_mfma_f32_16x16x32_bf16 v[102:105], v[172:175], v[206:209], v[102:105]
	v_mfma_f32_16x16x32_bf16 v[102:105], v[176:179], v[210:213], v[102:105]
	v_mfma_f32_16x16x32_bf16 v[82:85], v[164:167], v[214:217], v[82:85]
	v_mfma_f32_16x16x32_bf16 v[82:85], v[168:171], v[218:221], v[82:85]
	v_mfma_f32_16x16x32_bf16 v[86:89], v[172:175], v[214:217], v[86:89]
	v_mfma_f32_16x16x32_bf16 v[86:89], v[176:179], v[218:221], v[86:89]
	s_barrier
	s_add_i32 s63, s63, s37
	v_lshl_add_u64 v[222:223], v[222:223], 0, s[26:27]
	s_mov_b32 m0, s63
	ds_read_b128 v[180:183], v202 offset:49152
	ds_read_b128 v[184:187], v202 offset:50176
	ds_read_b128 v[188:191], v202 offset:51200
	ds_read_b128 v[192:195], v202 offset:52224
	ds_read_b128 v[206:209], v202 offset:53248
	ds_read_b128 v[210:213], v202 offset:54272
	ds_read_b128 v[214:217], v202 offset:55296
	ds_read_b128 v[218:221], v202 offset:56320
	global_load_lds_dwordx4 v[222:223], off
	s_add_i32 m0, s63, 0x2000
	s_add_u32 s18, s18, 0x100080
	v_lshl_add_u64 v[222:223], v[224:225], 0, s[26:27]
	s_addc_u32 s19, s19, 0
	s_add_i32 s63, s82, s37
	global_load_lds_dwordx4 v[222:223], off
	v_lshl_add_u64 v[222:223], s[18:19], 0, v[148:149]
	s_mov_b32 m0, s63
	s_nop 0
	global_load_lds_dwordx4 v[222:223], off
	v_lshl_add_u64 v[222:223], s[18:19], 0, v[152:153]
	s_add_i32 m0, s63, 0x2000
	s_nop 0
	global_load_lds_dwordx4 v[222:223], off
	v_lshl_add_u64 v[222:223], v[226:227], 0, s[26:27]
	s_mov_b32 m0, s71
	s_nop 0
	global_load_lds_dwordx4 v[222:223], off
	v_lshl_add_u64 v[222:223], v[228:229], 0, s[26:27]
	s_mov_b32 m0, s72
	s_nop 0
	global_load_lds_dwordx4 v[222:223], off
	s_waitcnt vmcnt(8)
	s_waitcnt lgkmcnt(0)
	s_barrier
	s_waitcnt lgkmcnt(0)
	v_mfma_f32_16x16x32_bf16 v[74:77], v[46:49], v[180:183], v[74:77]
	v_mfma_f32_16x16x32_bf16 v[74:77], v[54:57], v[184:187], v[74:77]
	v_mfma_f32_16x16x32_bf16 v[78:81], v[66:69], v[180:183], v[78:81]
	v_mfma_f32_16x16x32_bf16 v[78:81], v[70:73], v[184:187], v[78:81]
	v_mfma_f32_16x16x32_bf16 v[58:61], v[46:49], v[188:191], v[58:61]
	v_mfma_f32_16x16x32_bf16 v[58:61], v[54:57], v[192:195], v[58:61]
	v_mfma_f32_16x16x32_bf16 v[62:65], v[66:69], v[188:191], v[62:65]
	v_mfma_f32_16x16x32_bf16 v[62:65], v[70:73], v[192:195], v[62:65]
	v_mfma_f32_16x16x32_bf16 v[26:29], v[46:49], v[206:209], v[26:29]
	v_mfma_f32_16x16x32_bf16 v[26:29], v[54:57], v[210:213], v[26:29]
	v_mfma_f32_16x16x32_bf16 v[34:37], v[66:69], v[206:209], v[34:37]
	v_mfma_f32_16x16x32_bf16 v[34:37], v[70:73], v[210:213], v[34:37]
	v_mfma_f32_16x16x32_bf16 v[10:13], v[46:49], v[214:217], v[10:13]
	v_mfma_f32_16x16x32_bf16 v[10:13], v[54:57], v[218:221], v[10:13]
	v_mfma_f32_16x16x32_bf16 v[14:17], v[66:69], v[214:217], v[14:17]
	v_mfma_f32_16x16x32_bf16 v[14:17], v[70:73], v[218:221], v[14:17]
	v_mfma_f32_16x16x32_bf16 v[30:33], v[164:167], v[180:183], v[30:33]
	v_mfma_f32_16x16x32_bf16 v[66:69], v[168:171], v[184:187], v[30:33]
	v_mfma_f32_16x16x32_bf16 v[30:33], v[172:175], v[180:183], v[38:41]
	v_mfma_f32_16x16x32_bf16 v[70:73], v[176:179], v[184:187], v[30:33]
	v_mfma_f32_16x16x32_bf16 v[30:33], v[164:167], v[188:191], v[42:45]
	v_mfma_f32_16x16x32_bf16 v[46:49], v[168:171], v[192:195], v[30:33]
	v_mfma_f32_16x16x32_bf16 v[30:33], v[172:175], v[188:191], v[50:53]
	v_mfma_f32_16x16x32_bf16 v[54:57], v[176:179], v[192:195], v[30:33]
	v_mfma_f32_16x16x32_bf16 v[18:21], v[164:167], v[206:209], v[18:21]
	v_mfma_f32_16x16x32_bf16 v[18:21], v[168:171], v[210:213], v[18:21]
	v_mfma_f32_16x16x32_bf16 v[22:25], v[172:175], v[206:209], v[22:25]
	v_mfma_f32_16x16x32_bf16 v[22:25], v[176:179], v[210:213], v[22:25]
	v_mfma_f32_16x16x32_bf16 v[2:5], v[164:167], v[214:217], v[2:5]
	v_mfma_f32_16x16x32_bf16 v[2:5], v[168:171], v[218:221], v[2:5]
	v_mfma_f32_16x16x32_bf16 v[6:9], v[172:175], v[214:217], v[6:9]
	v_mfma_f32_16x16x32_bf16 v[6:9], v[176:179], v[218:221], v[6:9]
	s_barrier
	s_add_i32 s61, s61, 2
	s_add_u32 s10, s10, 0x100
	s_addc_u32 s11, s11, 0
	s_add_u32 s16, s16, 0x100
	s_addc_u32 s17, s17, 0
	s_cmp_gt_u32 s61, 61
	s_cbranch_scc0 .LBB0_1647
	s_and_b64 vcc, exec, s[28:29]
	s_cbranch_vccz .LBB0_1650
	s_barrier

.LBB0_1920:
	s_ashr_i32 s31, s30, 31
	s_lshl_b64 s[34:35], s[30:31], 21
	s_add_u32 s34, s54, s34
	s_addc_u32 s35, s55, s35
	s_and_b64 s[36:37], s[2:3], exec
	s_cselect_b32 s31, s35, s39
	s_cselect_b32 s69, s34, s38
	s_ashr_i32 s29, s28, 31
	s_lshl_b64 s[36:37], s[28:29], 21
	s_add_u32 s36, s1, s36
	s_addc_u32 s37, s16, s37
	s_and_b64 s[42:43], s[2:3], exec
	s_cselect_b32 s29, s37, s41
	s_cselect_b32 s70, s36, s40
	s_add_u32 s38, s38, 0x100080
	s_addc_u32 s39, s39, 0
	s_add_u32 s71, s40, 0x100
	s_addc_u32 s72, s41, 0
	s_mov_b32 s73, -2
	ds_read_b128 v[130:133], v212
	ds_read_b128 v[134:137], v212 offset:1024
	ds_read_b128 v[138:141], v212 offset:2048
	ds_read_b128 v[142:145], v212 offset:3072
	ds_read_b128 v[146:149], v213
	ds_read_b128 v[150:153], v213 offset:1024
	ds_read_b128 v[154:157], v213 offset:2048
	ds_read_b128 v[158:161], v213 offset:3072
	s_add_u32 s40, s38, 0xfff00080
	s_addc_u32 s41, s39, -1
	s_cmp_eq_u32 s73, 60
	s_cselect_b32 s43, s31, s41
	s_cselect_b32 s42, s69, s40
	s_cselect_b32 s41, s29, s72
	s_cselect_b32 s40, s70, s71
	v_lshl_add_u64 v[216:217], s[38:39], 0, v[178:179]
	s_add_i32 m0, s19, 0xc000
	ds_read_b128 v[162:165], v214
	ds_read_b128 v[166:169], v214 offset:1024
	ds_read_b128 v[186:189], v214 offset:2048
	ds_read_b128 v[190:193], v214 offset:3072
	ds_read_b128 v[194:197], v214 offset:4096
	ds_read_b128 v[198:201], v214 offset:5120
	ds_read_b128 v[202:205], v214 offset:6144
	ds_read_b128 v[206:209], v214 offset:7168
	global_load_lds_dwordx4 v[216:217], off
	v_lshl_add_u64 v[216:217], s[38:39], 0, v[180:181]
	s_add_i32 m0, s19, 0xe000
	s_nop 0
	global_load_lds_dwordx4 v[216:217], off
	s_waitcnt vmcnt(8)
	s_waitcnt lgkmcnt(0)
	s_barrier
	s_waitcnt lgkmcnt(0)
	v_mfma_f32_16x16x32_bf16 v[126:129], v[130:133], v[162:165], 0
	v_mfma_f32_16x16x32_bf16 v[126:129], v[134:137], v[166:169], v[126:129]
	v_mfma_f32_16x16x32_bf16 v[122:125], v[138:141], v[162:165], 0
	v_mfma_f32_16x16x32_bf16 v[122:125], v[142:145], v[166:169], v[122:125]
	v_mfma_f32_16x16x32_bf16 v[110:113], v[130:133], v[186:189], 0
	v_mfma_f32_16x16x32_bf16 v[110:113], v[134:137], v[190:193], v[110:113]
	v_mfma_f32_16x16x32_bf16 v[106:109], v[138:141], v[186:189], 0
	v_mfma_f32_16x16x32_bf16 v[106:109], v[142:145], v[190:193], v[106:109]
	v_mfma_f32_16x16x32_bf16 v[94:97], v[130:133], v[194:197], 0
	v_mfma_f32_16x16x32_bf16 v[94:97], v[134:137], v[198:201], v[94:97]
	v_mfma_f32_16x16x32_bf16 v[90:93], v[138:141], v[194:197], 0
	v_mfma_f32_16x16x32_bf16 v[90:93], v[142:145], v[198:201], v[90:93]
	v_mfma_f32_16x16x32_bf16 v[78:81], v[130:133], v[202:205], 0
	v_mfma_f32_16x16x32_bf16 v[78:81], v[134:137], v[206:209], v[78:81]
	v_mfma_f32_16x16x32_bf16 v[74:77], v[138:141], v[202:205], 0
	v_mfma_f32_16x16x32_bf16 v[74:77], v[142:145], v[206:209], v[74:77]
	v_mfma_f32_16x16x32_bf16 v[118:121], v[146:149], v[162:165], 0
	v_mfma_f32_16x16x32_bf16 v[118:121], v[150:153], v[166:169], v[118:121]
	v_mfma_f32_16x16x32_bf16 v[114:117], v[154:157], v[162:165], 0
	v_mfma_f32_16x16x32_bf16 v[114:117], v[158:161], v[166:169], v[114:117]
	v_mfma_f32_16x16x32_bf16 v[102:105], v[146:149], v[186:189], 0
	v_mfma_f32_16x16x32_bf16 v[102:105], v[150:153], v[190:193], v[102:105]
	v_mfma_f32_16x16x32_bf16 v[98:101], v[154:157], v[186:189], 0
	v_mfma_f32_16x16x32_bf16 v[98:101], v[158:161], v[190:193], v[98:101]
	v_mfma_f32_16x16x32_bf16 v[86:89], v[146:149], v[194:197], 0
	v_mfma_f32_16x16x32_bf16 v[86:89], v[150:153], v[198:201], v[86:89]
	v_mfma_f32_16x16x32_bf16 v[82:85], v[154:157], v[194:197], 0
	v_mfma_f32_16x16x32_bf16 v[82:85], v[158:161], v[198:201], v[82:85]
	v_mfma_f32_16x16x32_bf16 v[70:73], v[146:149], v[202:205], 0
	v_mfma_f32_16x16x32_bf16 v[70:73], v[150:153], v[206:209], v[70:73]
	v_mfma_f32_16x16x32_bf16 v[66:69], v[154:157], v[202:205], 0
	v_mfma_f32_16x16x32_bf16 v[66:69], v[158:161], v[206:209], v[66:69]
	s_barrier
	s_add_i32 s76, s57, s17
	v_lshl_add_u64 v[216:217], s[40:41], 0, v[172:173]
	s_mov_b32 m0, s76
	ds_read_b128 v[162:165], v214 offset:16384
	ds_read_b128 v[166:169], v214 offset:17408
	ds_read_b128 v[186:189], v214 offset:18432
	ds_read_b128 v[190:193], v214 offset:19456
	ds_read_b128 v[194:197], v214 offset:20480
	ds_read_b128 v[198:201], v214 offset:21504
	ds_read_b128 v[202:205], v214 offset:22528
	ds_read_b128 v[206:209], v214 offset:23552
	global_load_lds_dwordx4 v[216:217], off
	s_add_i32 m0, s76, 0x2000
	s_add_u32 s76, s40, 0x100000
	v_lshl_add_u64 v[218:219], s[40:41], 0, v[176:177]
	s_addc_u32 s77, s41, 0
	s_add_i32 s78, s60, s17
	global_load_lds_dwordx4 v[218:219], off
	v_lshl_add_u64 v[220:221], s[76:77], 0, v[172:173]
	s_mov_b32 m0, s78
	v_lshl_add_u64 v[222:223], s[42:43], 0, v[174:175]
	global_load_lds_dwordx4 v[220:221], off
	v_lshl_add_u64 v[220:221], s[76:77], 0, v[176:177]
	s_add_i32 m0, s78, 0x2000
	s_nop 0
	global_load_lds_dwordx4 v[220:221], off
	v_lshl_add_u64 v[220:221], s[42:43], 0, v[170:171]
	s_mov_b32 m0, s19
	s_nop 0
	global_load_lds_dwordx4 v[220:221], off
	s_mov_b32 m0, s44
	s_nop 0
	global_load_lds_dwordx4 v[222:223], off
	s_waitcnt vmcnt(8)
	s_waitcnt lgkmcnt(0)
	s_barrier
	s_waitcnt lgkmcnt(0)
	v_mfma_f32_16x16x32_bf16 v[62:65], v[130:133], v[162:165], 0
	v_mfma_f32_16x16x32_bf16 v[62:65], v[134:137], v[166:169], v[62:65]
	v_mfma_f32_16x16x32_bf16 v[58:61], v[138:141], v[162:165], 0
	v_mfma_f32_16x16x32_bf16 v[58:61], v[142:145], v[166:169], v[58:61]
	v_mfma_f32_16x16x32_bf16 v[46:49], v[130:133], v[186:189], 0
	v_mfma_f32_16x16x32_bf16 v[46:49], v[134:137], v[190:193], v[46:49]
	v_mfma_f32_16x16x32_bf16 v[42:45], v[138:141], v[186:189], 0
	v_mfma_f32_16x16x32_bf16 v[42:45], v[142:145], v[190:193], v[42:45]
	v_mfma_f32_16x16x32_bf16 v[30:33], v[130:133], v[194:197], 0
	v_mfma_f32_16x16x32_bf16 v[30:33], v[134:137], v[198:201], v[30:33]
	v_mfma_f32_16x16x32_bf16 v[26:29], v[138:141], v[194:197], 0
	v_mfma_f32_16x16x32_bf16 v[26:29], v[142:145], v[198:201], v[26:29]
	v_mfma_f32_16x16x32_bf16 v[14:17], v[130:133], v[202:205], 0
	v_mfma_f32_16x16x32_bf16 v[14:17], v[134:137], v[206:209], v[14:17]
	v_mfma_f32_16x16x32_bf16 v[10:13], v[138:141], v[202:205], 0
	v_mfma_f32_16x16x32_bf16 v[10:13], v[142:145], v[206:209], v[10:13]
	v_mfma_f32_16x16x32_bf16 v[54:57], v[146:149], v[162:165], 0
	v_mfma_f32_16x16x32_bf16 v[54:57], v[150:153], v[166:169], v[54:57]
	v_mfma_f32_16x16x32_bf16 v[50:53], v[154:157], v[162:165], 0
	v_mfma_f32_16x16x32_bf16 v[50:53], v[158:161], v[166:169], v[50:53]
	v_mfma_f32_16x16x32_bf16 v[38:41], v[146:149], v[186:189], 0
	v_mfma_f32_16x16x32_bf16 v[38:41], v[150:153], v[190:193], v[38:41]
	v_mfma_f32_16x16x32_bf16 v[34:37], v[154:157], v[186:189], 0
	v_mfma_f32_16x16x32_bf16 v[34:37], v[158:161], v[190:193], v[34:37]
	v_mfma_f32_16x16x32_bf16 v[22:25], v[146:149], v[194:197], 0
	v_mfma_f32_16x16x32_bf16 v[22:25], v[150:153], v[198:201], v[22:25]
	v_mfma_f32_16x16x32_bf16 v[18:21], v[154:157], v[194:197], 0
	v_mfma_f32_16x16x32_bf16 v[18:21], v[158:161], v[198:201], v[18:21]
	v_mfma_f32_16x16x32_bf16 v[6:9], v[146:149], v[202:205], 0
	v_mfma_f32_16x16x32_bf16 v[6:9], v[150:153], v[206:209], v[6:9]
	v_mfma_f32_16x16x32_bf16 v[2:5], v[154:157], v[202:205], 0
	v_mfma_f32_16x16x32_bf16 v[2:5], v[158:161], v[206:209], v[2:5]
	s_barrier
	s_add_i32 s76, 0, 0x18000
	s_add_i32 s77, 0, 0x1c000
	v_add_u32_e32 v142, s76, v211
	v_add_u32_e32 v158, s77, v211
	ds_read_b128 v[130:133], v142
	ds_read_b128 v[134:137], v142 offset:1024
	ds_read_b128 v[138:141], v142 offset:2048
	ds_read_b128 v[142:145], v142 offset:3072
	ds_read_b128 v[146:149], v158
	ds_read_b128 v[150:153], v158 offset:1024
	ds_read_b128 v[154:157], v158 offset:2048
	ds_read_b128 v[158:161], v158 offset:3072
	s_add_u32 s42, s42, 0x100000
	s_addc_u32 s43, s43, 0
	s_mov_b32 m0, s45
	v_lshl_add_u64 v[224:225], s[42:43], 0, v[170:171]
	ds_read_b128 v[162:165], v214 offset:32768
	ds_read_b128 v[166:169], v214 offset:33792
	ds_read_b128 v[186:189], v214 offset:34816
	ds_read_b128 v[190:193], v214 offset:35840
	ds_read_b128 v[194:197], v214 offset:36864
	ds_read_b128 v[198:201], v214 offset:37888
	ds_read_b128 v[202:205], v214 offset:38912
	ds_read_b128 v[206:209], v214 offset:39936
	global_load_lds_dwordx4 v[224:225], off
	v_lshl_add_u64 v[224:225], s[42:43], 0, v[174:175]
	s_mov_b32 m0, s46
	s_nop 0
	global_load_lds_dwordx4 v[224:225], off
	s_waitcnt vmcnt(8)
	s_waitcnt lgkmcnt(0)
	s_barrier
	s_waitcnt lgkmcnt(0)
	v_mfma_f32_16x16x32_bf16 v[126:129], v[130:133], v[162:165], v[126:129]
	v_mfma_f32_16x16x32_bf16 v[126:129], v[134:137], v[166:169], v[126:129]
	v_mfma_f32_16x16x32_bf16 v[122:125], v[138:141], v[162:165], v[122:125]
	v_mfma_f32_16x16x32_bf16 v[122:125], v[142:145], v[166:169], v[122:125]
	v_mfma_f32_16x16x32_bf16 v[110:113], v[130:133], v[186:189], v[110:113]
	v_mfma_f32_16x16x32_bf16 v[110:113], v[134:137], v[190:193], v[110:113]
	v_mfma_f32_16x16x32_bf16 v[106:109], v[138:141], v[186:189], v[106:109]
	v_mfma_f32_16x16x32_bf16 v[106:109], v[142:145], v[190:193], v[106:109]
	v_mfma_f32_16x16x32_bf16 v[94:97], v[130:133], v[194:197], v[94:97]
	v_mfma_f32_16x16x32_bf16 v[94:97], v[134:137], v[198:201], v[94:97]
	v_mfma_f32_16x16x32_bf16 v[90:93], v[138:141], v[194:197], v[90:93]
	v_mfma_f32_16x16x32_bf16 v[90:93], v[142:145], v[198:201], v[90:93]
	v_mfma_f32_16x16x32_bf16 v[78:81], v[130:133], v[202:205], v[78:81]
	v_mfma_f32_16x16x32_bf16 v[78:81], v[134:137], v[206:209], v[78:81]
	v_mfma_f32_16x16x32_bf16 v[74:77], v[138:141], v[202:205], v[74:77]
	v_mfma_f32_16x16x32_bf16 v[74:77], v[142:145], v[206:209], v[74:77]
	v_mfma_f32_16x16x32_bf16 v[118:121], v[146:149], v[162:165], v[118:121]
	v_mfma_f32_16x16x32_bf16 v[118:121], v[150:153], v[166:169], v[118:121]
	v_mfma_f32_16x16x32_bf16 v[114:117], v[154:157], v[162:165], v[114:117]
	v_mfma_f32_16x16x32_bf16 v[114:117], v[158:161], v[166:169], v[114:117]
	v_mfma_f32_16x16x32_bf16 v[102:105], v[146:149], v[186:189], v[102:105]
	v_mfma_f32_16x16x32_bf16 v[102:105], v[150:153], v[190:193], v[102:105]
	v_mfma_f32_16x16x32_bf16 v[98:101], v[154:157], v[186:189], v[98:101]
	v_mfma_f32_16x16x32_bf16 v[98:101], v[158:161], v[190:193], v[98:101]
	v_mfma_f32_16x16x32_bf16 v[86:89], v[146:149], v[194:197], v[86:89]
	v_mfma_f32_16x16x32_bf16 v[86:89], v[150:153], v[198:201], v[86:89]
	v_mfma_f32_16x16x32_bf16 v[82:85], v[154:157], v[194:197], v[82:85]
	v_mfma_f32_16x16x32_bf16 v[82:85], v[158:161], v[198:201], v[82:85]
	v_mfma_f32_16x16x32_bf16 v[70:73], v[146:149], v[202:205], v[70:73]
	v_mfma_f32_16x16x32_bf16 v[70:73], v[150:153], v[206:209], v[70:73]
	v_mfma_f32_16x16x32_bf16 v[66:69], v[154:157], v[202:205], v[66:69]
	v_mfma_f32_16x16x32_bf16 v[66:69], v[158:161], v[206:209], v[66:69]
	s_barrier
	s_add_i32 s42, s76, s17
	v_lshl_add_u64 v[216:217], v[216:217], 0, s[8:9]
	s_mov_b32 m0, s42
	ds_read_b128 v[162:165], v214 offset:49152
	ds_read_b128 v[166:169], v214 offset:50176
	ds_read_b128 v[186:189], v214 offset:51200
	ds_read_b128 v[190:193], v214 offset:52224
	ds_read_b128 v[194:197], v214 offset:53248
	ds_read_b128 v[198:201], v214 offset:54272
	ds_read_b128 v[202:205], v214 offset:55296
	ds_read_b128 v[206:209], v214 offset:56320
	global_load_lds_dwordx4 v[216:217], off
	s_add_i32 m0, s42, 0x2000
	s_add_u32 s40, s40, 0x100080
	v_lshl_add_u64 v[216:217], v[218:219], 0, s[8:9]
	s_addc_u32 s41, s41, 0
	s_add_i32 s42, s77, s17
	global_load_lds_dwordx4 v[216:217], off
	v_lshl_add_u64 v[216:217], s[40:41], 0, v[172:173]
	s_mov_b32 m0, s42
	s_nop 0
	global_load_lds_dwordx4 v[216:217], off
	v_lshl_add_u64 v[216:217], s[40:41], 0, v[176:177]
	s_add_i32 m0, s42, 0x2000
	s_nop 0
	global_load_lds_dwordx4 v[216:217], off
	v_lshl_add_u64 v[216:217], v[220:221], 0, s[8:9]
	s_mov_b32 m0, s50
	s_nop 0
	global_load_lds_dwordx4 v[216:217], off
	v_lshl_add_u64 v[216:217], v[222:223], 0, s[8:9]
	s_mov_b32 m0, s51
	s_nop 0
	global_load_lds_dwordx4 v[216:217], off
	s_waitcnt vmcnt(8)
	s_waitcnt lgkmcnt(0)
	s_barrier
	s_waitcnt lgkmcnt(0)
	v_mfma_f32_16x16x32_bf16 v[62:65], v[130:133], v[162:165], v[62:65]
	v_mfma_f32_16x16x32_bf16 v[62:65], v[134:137], v[166:169], v[62:65]
	v_mfma_f32_16x16x32_bf16 v[58:61], v[138:141], v[162:165], v[58:61]
	v_mfma_f32_16x16x32_bf16 v[58:61], v[142:145], v[166:169], v[58:61]
	v_mfma_f32_16x16x32_bf16 v[46:49], v[130:133], v[186:189], v[46:49]
	v_mfma_f32_16x16x32_bf16 v[46:49], v[134:137], v[190:193], v[46:49]
	v_mfma_f32_16x16x32_bf16 v[42:45], v[138:141], v[186:189], v[42:45]
	v_mfma_f32_16x16x32_bf16 v[42:45], v[142:145], v[190:193], v[42:45]
	v_mfma_f32_16x16x32_bf16 v[30:33], v[130:133], v[194:197], v[30:33]
	v_mfma_f32_16x16x32_bf16 v[30:33], v[134:137], v[198:201], v[30:33]
	v_mfma_f32_16x16x32_bf16 v[26:29], v[138:141], v[194:197], v[26:29]
	v_mfma_f32_16x16x32_bf16 v[26:29], v[142:145], v[198:201], v[26:29]
	v_mfma_f32_16x16x32_bf16 v[14:17], v[130:133], v[202:205], v[14:17]
	v_mfma_f32_16x16x32_bf16 v[14:17], v[134:137], v[206:209], v[14:17]
	v_mfma_f32_16x16x32_bf16 v[10:13], v[138:141], v[202:205], v[10:13]
	v_mfma_f32_16x16x32_bf16 v[10:13], v[142:145], v[206:209], v[10:13]
	v_mfma_f32_16x16x32_bf16 v[54:57], v[146:149], v[162:165], v[54:57]
	v_mfma_f32_16x16x32_bf16 v[54:57], v[150:153], v[166:169], v[54:57]
	v_mfma_f32_16x16x32_bf16 v[50:53], v[154:157], v[162:165], v[50:53]
	v_mfma_f32_16x16x32_bf16 v[50:53], v[158:161], v[166:169], v[50:53]
	v_mfma_f32_16x16x32_bf16 v[38:41], v[146:149], v[186:189], v[38:41]
	v_mfma_f32_16x16x32_bf16 v[38:41], v[150:153], v[190:193], v[38:41]
	v_mfma_f32_16x16x32_bf16 v[34:37], v[154:157], v[186:189], v[34:37]
	v_mfma_f32_16x16x32_bf16 v[34:37], v[158:161], v[190:193], v[34:37]
	v_mfma_f32_16x16x32_bf16 v[22:25], v[146:149], v[194:197], v[22:25]
	v_mfma_f32_16x16x32_bf16 v[22:25], v[150:153], v[198:201], v[22:25]
	v_mfma_f32_16x16x32_bf16 v[18:21], v[154:157], v[194:197], v[18:21]
	v_mfma_f32_16x16x32_bf16 v[18:21], v[158:161], v[198:201], v[18:21]
	v_mfma_f32_16x16x32_bf16 v[6:9], v[146:149], v[202:205], v[6:9]
	v_mfma_f32_16x16x32_bf16 v[6:9], v[150:153], v[206:209], v[6:9]
	v_mfma_f32_16x16x32_bf16 v[2:5], v[154:157], v[202:205], v[2:5]
	v_mfma_f32_16x16x32_bf16 v[2:5], v[158:161], v[206:209], v[2:5]
	s_barrier
	s_add_i32 s73, s73, 2
	s_add_u32 s38, s38, 0x100
	s_addc_u32 s39, s39, 0
	s_add_u32 s71, s71, 0x100
	s_addc_u32 s72, s72, 0
	s_cmp_gt_u32 s73, 61

.LBB0_2055:
	s_ashr_i32 s31, s30, 31
	s_lshl_b64 s[18:19], s[30:31], 20
	s_add_u32 s34, s27, s18
	s_addc_u32 s35, s44, s19
	s_and_b64 s[18:19], s[0:1], exec
	s_cselect_b32 s31, s35, s3
	s_cselect_b32 s87, s34, s2
	s_ashr_i32 s29, s28, 31
	s_lshl_b64 s[18:19], s[28:29], 20
	s_add_u32 s36, s45, s18
	s_addc_u32 s37, s46, s19
	s_and_b64 s[18:19], s[0:1], exec
	s_cselect_b32 s29, s37, s5
	s_cselect_b32 s90, s36, s4
	s_add_u32 s91, s4, 0x100
	s_addc_u32 s92, s5, 0
	s_mov_b32 s93, -2
	ds_read_b128 v[130:133], v234
	ds_read_b128 v[134:137], v234 offset:1024
	ds_read_b128 v[162:165], v234 offset:2048
	ds_read_b128 v[166:169], v234 offset:3072
	ds_read_b128 v[170:173], v235
	ds_read_b128 v[174:177], v235 offset:1024
	ds_read_b128 v[178:181], v235 offset:2048
	ds_read_b128 v[182:185], v235 offset:3072
	s_add_u32 s4, s2, 0x100
	s_addc_u32 s5, s3, 0
	s_cmp_eq_u32 s93, 28
	s_cselect_b32 s43, s31, s5
	s_cselect_b32 s42, s87, s4
	s_cselect_b32 s19, s29, s92
	s_cselect_b32 s18, s90, s91
	v_lshl_add_u64 v[218:219], s[2:3], 0, v[154:155]
	s_add_i32 m0, s49, 0xc000
	ds_read_b128 v[186:189], v236
	ds_read_b128 v[190:193], v236 offset:1024
	ds_read_b128 v[194:197], v236 offset:2048
	ds_read_b128 v[198:201], v236 offset:3072
	ds_read_b128 v[202:205], v236 offset:4096
	ds_read_b128 v[206:209], v236 offset:5120
	ds_read_b128 v[210:213], v236 offset:6144
	ds_read_b128 v[214:217], v236 offset:7168
	global_load_lds_dwordx4 v[218:219], off
	v_lshl_add_u64 v[218:219], s[2:3], 0, v[156:157]
	s_add_i32 m0, s49, 0xe000
	s_nop 0
	global_load_lds_dwordx4 v[218:219], off
	s_waitcnt vmcnt(8)
	s_waitcnt lgkmcnt(0)
	s_barrier
	s_waitcnt lgkmcnt(0)
	v_mfma_i32_16x16x64_i8 v[118:121], v[130:133], v[186:189], 0
	v_mfma_i32_16x16x64_i8 v[118:121], v[134:137], v[190:193], v[118:121]
	v_mfma_i32_16x16x64_i8 v[102:105], v[162:165], v[186:189], 0
	v_mfma_i32_16x16x64_i8 v[102:105], v[166:169], v[190:193], v[102:105]
	v_mfma_i32_16x16x64_i8 v[114:117], v[130:133], v[194:197], 0
	v_mfma_i32_16x16x64_i8 v[114:117], v[134:137], v[198:201], v[114:117]
	v_mfma_i32_16x16x64_i8 v[98:101], v[162:165], v[194:197], 0
	v_mfma_i32_16x16x64_i8 v[98:101], v[166:169], v[198:201], v[98:101]
	v_mfma_i32_16x16x64_i8 v[126:129], v[130:133], v[202:205], 0
	v_mfma_i32_16x16x64_i8 v[126:129], v[134:137], v[206:209], v[126:129]
	v_mfma_i32_16x16x64_i8 v[110:113], v[162:165], v[202:205], 0
	v_mfma_i32_16x16x64_i8 v[110:113], v[166:169], v[206:209], v[110:113]
	v_mfma_i32_16x16x64_i8 v[122:125], v[130:133], v[210:213], 0
	v_mfma_i32_16x16x64_i8 v[122:125], v[134:137], v[214:217], v[122:125]
	v_mfma_i32_16x16x64_i8 v[106:109], v[162:165], v[210:213], 0
	v_mfma_i32_16x16x64_i8 v[106:109], v[166:169], v[214:217], v[106:109]
	v_mfma_i32_16x16x64_i8 v[86:89], v[170:173], v[186:189], 0
	v_mfma_i32_16x16x64_i8 v[86:89], v[174:177], v[190:193], v[86:89]
	v_mfma_i32_16x16x64_i8 v[70:73], v[178:181], v[186:189], 0
	v_mfma_i32_16x16x64_i8 v[70:73], v[182:185], v[190:193], v[70:73]
	v_mfma_i32_16x16x64_i8 v[82:85], v[170:173], v[194:197], 0
	v_mfma_i32_16x16x64_i8 v[82:85], v[174:177], v[198:201], v[82:85]
	v_mfma_i32_16x16x64_i8 v[66:69], v[178:181], v[194:197], 0
	v_mfma_i32_16x16x64_i8 v[66:69], v[182:185], v[198:201], v[66:69]
	v_mfma_i32_16x16x64_i8 v[94:97], v[170:173], v[202:205], 0
	v_mfma_i32_16x16x64_i8 v[94:97], v[174:177], v[206:209], v[94:97]
	v_mfma_i32_16x16x64_i8 v[78:81], v[178:181], v[202:205], 0
	v_mfma_i32_16x16x64_i8 v[78:81], v[182:185], v[206:209], v[78:81]
	v_mfma_i32_16x16x64_i8 v[90:93], v[170:173], v[210:213], 0
	v_mfma_i32_16x16x64_i8 v[90:93], v[174:177], v[214:217], v[90:93]
	v_mfma_i32_16x16x64_i8 v[74:77], v[178:181], v[210:213], 0
	v_mfma_i32_16x16x64_i8 v[74:77], v[182:185], v[214:217], v[74:77]
	s_barrier
	s_add_i32 s2, s82, s47
	v_lshl_add_u64 v[218:219], s[18:19], 0, v[144:145]
	s_mov_b32 m0, s2
	ds_read_b128 v[186:189], v236 offset:16384
	ds_read_b128 v[190:193], v236 offset:17408
	ds_read_b128 v[194:197], v236 offset:18432
	ds_read_b128 v[198:201], v236 offset:19456
	ds_read_b128 v[202:205], v236 offset:20480
	ds_read_b128 v[206:209], v236 offset:21504
	ds_read_b128 v[210:213], v236 offset:22528
	ds_read_b128 v[214:217], v236 offset:23552
	global_load_lds_dwordx4 v[218:219], off
	s_add_i32 m0, s2, 0x2000
	s_add_u32 s2, s18, 0x80000
	v_lshl_add_u64 v[220:221], s[18:19], 0, v[148:149]
	s_addc_u32 s3, s19, 0
	s_add_i32 s94, s16, s47
	global_load_lds_dwordx4 v[220:221], off
	v_lshl_add_u64 v[222:223], s[2:3], 0, v[144:145]
	s_mov_b32 m0, s94
	v_lshl_add_u64 v[224:225], s[42:43], 0, v[146:147]
	global_load_lds_dwordx4 v[222:223], off
	v_lshl_add_u64 v[222:223], s[2:3], 0, v[148:149]
	s_add_i32 m0, s94, 0x2000
	s_nop 0
	global_load_lds_dwordx4 v[222:223], off
	v_lshl_add_u64 v[222:223], s[42:43], 0, v[142:143]
	s_mov_b32 m0, s49
	s_nop 0
	global_load_lds_dwordx4 v[222:223], off
	s_mov_b32 m0, s50
	s_nop 0
	global_load_lds_dwordx4 v[224:225], off
	s_waitcnt vmcnt(8)
	s_waitcnt lgkmcnt(0)
	s_barrier
	s_waitcnt lgkmcnt(0)
	v_mfma_i32_16x16x64_i8 v[54:57], v[130:133], v[186:189], 0
	v_mfma_i32_16x16x64_i8 v[54:57], v[134:137], v[190:193], v[54:57]
	v_mfma_i32_16x16x64_i8 v[18:21], v[162:165], v[186:189], 0
	v_mfma_i32_16x16x64_i8 v[18:21], v[166:169], v[190:193], v[18:21]
	v_mfma_i32_16x16x64_i8 v[50:53], v[130:133], v[194:197], 0
	v_mfma_i32_16x16x64_i8 v[50:53], v[134:137], v[198:201], v[50:53]
	v_mfma_i32_16x16x64_i8 v[22:25], v[162:165], v[194:197], 0
	v_mfma_i32_16x16x64_i8 v[22:25], v[166:169], v[198:201], v[22:25]
	v_mfma_i32_16x16x64_i8 v[62:65], v[130:133], v[202:205], 0
	v_mfma_i32_16x16x64_i8 v[62:65], v[134:137], v[206:209], v[62:65]
	v_mfma_i32_16x16x64_i8 v[30:33], v[162:165], v[202:205], 0
	v_mfma_i32_16x16x64_i8 v[30:33], v[166:169], v[206:209], v[30:33]
	v_mfma_i32_16x16x64_i8 v[58:61], v[130:133], v[210:213], 0
	v_mfma_i32_16x16x64_i8 v[58:61], v[134:137], v[214:217], v[58:61]
	v_mfma_i32_16x16x64_i8 v[26:29], v[162:165], v[210:213], 0
	v_mfma_i32_16x16x64_i8 v[26:29], v[166:169], v[214:217], v[26:29]
	v_mfma_i32_16x16x64_i8 v[46:49], v[170:173], v[186:189], 0
	v_mfma_i32_16x16x64_i8 v[46:49], v[174:177], v[190:193], v[46:49]
	v_mfma_i32_16x16x64_i8 v[14:17], v[178:181], v[186:189], 0
	v_mfma_i32_16x16x64_i8 v[14:17], v[182:185], v[190:193], v[14:17]
	v_mfma_i32_16x16x64_i8 v[42:45], v[170:173], v[194:197], 0
	v_mfma_i32_16x16x64_i8 v[42:45], v[174:177], v[198:201], v[42:45]
	v_mfma_i32_16x16x64_i8 v[10:13], v[178:181], v[194:197], 0
	v_mfma_i32_16x16x64_i8 v[10:13], v[182:185], v[198:201], v[10:13]
	v_mfma_i32_16x16x64_i8 v[38:41], v[170:173], v[202:205], 0
	v_mfma_i32_16x16x64_i8 v[38:41], v[174:177], v[206:209], v[38:41]
	v_mfma_i32_16x16x64_i8 v[6:9], v[178:181], v[202:205], 0
	v_mfma_i32_16x16x64_i8 v[6:9], v[182:185], v[206:209], v[6:9]
	v_mfma_i32_16x16x64_i8 v[34:37], v[170:173], v[210:213], 0
	v_mfma_i32_16x16x64_i8 v[34:37], v[174:177], v[214:217], v[34:37]
	v_mfma_i32_16x16x64_i8 v[2:5], v[178:181], v[210:213], 0
	v_mfma_i32_16x16x64_i8 v[2:5], v[182:185], v[214:217], v[2:5]
	s_barrier
	s_add_i32 s94, 0, 0x18000
	s_add_i32 s95, 0, 0x1c000
	v_add_u32_e32 v166, s94, v232
	v_add_u32_e32 v182, s95, v232
	ds_read_b128 v[130:133], v166
	ds_read_b128 v[134:137], v166 offset:1024
	ds_read_b128 v[162:165], v166 offset:2048
	ds_read_b128 v[166:169], v166 offset:3072
	ds_read_b128 v[170:173], v182
	ds_read_b128 v[174:177], v182 offset:1024
	ds_read_b128 v[178:181], v182 offset:2048
	ds_read_b128 v[182:185], v182 offset:3072
	s_add_u32 s2, s42, 0x80000
	s_addc_u32 s3, s43, 0
	s_mov_b32 m0, s51
	v_lshl_add_u64 v[226:227], s[2:3], 0, v[142:143]
	ds_read_b128 v[186:189], v236 offset:32768
	ds_read_b128 v[190:193], v236 offset:33792
	ds_read_b128 v[194:197], v236 offset:34816
	ds_read_b128 v[198:201], v236 offset:35840
	ds_read_b128 v[202:205], v236 offset:36864
	ds_read_b128 v[206:209], v236 offset:37888
	ds_read_b128 v[210:213], v236 offset:38912
	ds_read_b128 v[214:217], v236 offset:39936
	global_load_lds_dwordx4 v[226:227], off
	v_lshl_add_u64 v[226:227], s[2:3], 0, v[146:147]
	s_mov_b32 m0, s54
	s_nop 0
	global_load_lds_dwordx4 v[226:227], off
	s_waitcnt vmcnt(8)
	s_waitcnt lgkmcnt(0)
	s_barrier
	s_waitcnt lgkmcnt(0)
	v_mfma_i32_16x16x64_i8 v[118:121], v[130:133], v[186:189], v[118:121]
	v_mfma_i32_16x16x64_i8 v[118:121], v[134:137], v[190:193], v[118:121]
	v_mfma_i32_16x16x64_i8 v[102:105], v[162:165], v[186:189], v[102:105]
	v_mfma_i32_16x16x64_i8 v[102:105], v[166:169], v[190:193], v[102:105]
	v_mfma_i32_16x16x64_i8 v[114:117], v[130:133], v[194:197], v[114:117]
	v_mfma_i32_16x16x64_i8 v[114:117], v[134:137], v[198:201], v[114:117]
	v_mfma_i32_16x16x64_i8 v[98:101], v[162:165], v[194:197], v[98:101]
	v_mfma_i32_16x16x64_i8 v[98:101], v[166:169], v[198:201], v[98:101]
	v_mfma_i32_16x16x64_i8 v[126:129], v[130:133], v[202:205], v[126:129]
	v_mfma_i32_16x16x64_i8 v[126:129], v[134:137], v[206:209], v[126:129]
	v_mfma_i32_16x16x64_i8 v[110:113], v[162:165], v[202:205], v[110:113]
	v_mfma_i32_16x16x64_i8 v[110:113], v[166:169], v[206:209], v[110:113]
	v_mfma_i32_16x16x64_i8 v[122:125], v[130:133], v[210:213], v[122:125]
	v_mfma_i32_16x16x64_i8 v[122:125], v[134:137], v[214:217], v[122:125]
	v_mfma_i32_16x16x64_i8 v[106:109], v[162:165], v[210:213], v[106:109]
	v_mfma_i32_16x16x64_i8 v[106:109], v[166:169], v[214:217], v[106:109]
	v_mfma_i32_16x16x64_i8 v[86:89], v[170:173], v[186:189], v[86:89]
	v_mfma_i32_16x16x64_i8 v[86:89], v[174:177], v[190:193], v[86:89]
	v_mfma_i32_16x16x64_i8 v[70:73], v[178:181], v[186:189], v[70:73]
	v_mfma_i32_16x16x64_i8 v[70:73], v[182:185], v[190:193], v[70:73]
	v_mfma_i32_16x16x64_i8 v[82:85], v[170:173], v[194:197], v[82:85]
	v_mfma_i32_16x16x64_i8 v[82:85], v[174:177], v[198:201], v[82:85]
	v_mfma_i32_16x16x64_i8 v[66:69], v[178:181], v[194:197], v[66:69]
	v_mfma_i32_16x16x64_i8 v[66:69], v[182:185], v[198:201], v[66:69]
	v_mfma_i32_16x16x64_i8 v[94:97], v[170:173], v[202:205], v[94:97]
	v_mfma_i32_16x16x64_i8 v[94:97], v[174:177], v[206:209], v[94:97]
	v_mfma_i32_16x16x64_i8 v[78:81], v[178:181], v[202:205], v[78:81]
	v_mfma_i32_16x16x64_i8 v[78:81], v[182:185], v[206:209], v[78:81]
	v_mfma_i32_16x16x64_i8 v[90:93], v[170:173], v[210:213], v[90:93]
	v_mfma_i32_16x16x64_i8 v[90:93], v[174:177], v[214:217], v[90:93]
	v_mfma_i32_16x16x64_i8 v[74:77], v[178:181], v[210:213], v[74:77]
	v_mfma_i32_16x16x64_i8 v[74:77], v[182:185], v[214:217], v[74:77]
	s_barrier
	s_add_i32 s2, s94, s47
	v_lshl_add_u64 v[218:219], v[218:219], 0, s[14:15]
	s_mov_b32 m0, s2
	ds_read_b128 v[186:189], v236 offset:49152
	ds_read_b128 v[190:193], v236 offset:50176
	ds_read_b128 v[194:197], v236 offset:51200
	ds_read_b128 v[198:201], v236 offset:52224
	ds_read_b128 v[202:205], v236 offset:53248
	ds_read_b128 v[206:209], v236 offset:54272
	ds_read_b128 v[210:213], v236 offset:55296
	ds_read_b128 v[214:217], v236 offset:56320
	global_load_lds_dwordx4 v[218:219], off
	s_add_i32 m0, s2, 0x2000
	s_add_u32 s2, s18, 0x80080
	v_lshl_add_u64 v[218:219], v[220:221], 0, s[14:15]
	s_addc_u32 s3, s19, 0
	s_add_i32 s18, s95, s47
	global_load_lds_dwordx4 v[218:219], off
	v_lshl_add_u64 v[218:219], s[2:3], 0, v[144:145]
	s_mov_b32 m0, s18
	s_nop 0
	global_load_lds_dwordx4 v[218:219], off
	v_lshl_add_u64 v[218:219], s[2:3], 0, v[148:149]
	s_add_i32 m0, s18, 0x2000
	s_nop 0
	global_load_lds_dwordx4 v[218:219], off
	v_lshl_add_u64 v[218:219], v[222:223], 0, s[14:15]
	s_mov_b32 m0, s63
	s_nop 0
	global_load_lds_dwordx4 v[218:219], off
	v_lshl_add_u64 v[218:219], v[224:225], 0, s[14:15]
	s_mov_b32 m0, s64
	s_nop 0
	global_load_lds_dwordx4 v[218:219], off
	s_waitcnt vmcnt(8)
	s_waitcnt lgkmcnt(0)
	s_barrier
	s_waitcnt lgkmcnt(0)
	v_mfma_i32_16x16x64_i8 v[54:57], v[130:133], v[186:189], v[54:57]
	v_mfma_i32_16x16x64_i8 v[54:57], v[134:137], v[190:193], v[54:57]
	v_mfma_i32_16x16x64_i8 v[18:21], v[162:165], v[186:189], v[18:21]
	v_mfma_i32_16x16x64_i8 v[18:21], v[166:169], v[190:193], v[18:21]
	v_mfma_i32_16x16x64_i8 v[50:53], v[130:133], v[194:197], v[50:53]
	v_mfma_i32_16x16x64_i8 v[50:53], v[134:137], v[198:201], v[50:53]
	v_mfma_i32_16x16x64_i8 v[22:25], v[162:165], v[194:197], v[22:25]
	v_mfma_i32_16x16x64_i8 v[22:25], v[166:169], v[198:201], v[22:25]
	v_mfma_i32_16x16x64_i8 v[62:65], v[130:133], v[202:205], v[62:65]
	v_mfma_i32_16x16x64_i8 v[62:65], v[134:137], v[206:209], v[62:65]
	v_mfma_i32_16x16x64_i8 v[30:33], v[162:165], v[202:205], v[30:33]
	v_mfma_i32_16x16x64_i8 v[30:33], v[166:169], v[206:209], v[30:33]
	v_mfma_i32_16x16x64_i8 v[58:61], v[130:133], v[210:213], v[58:61]
	v_mfma_i32_16x16x64_i8 v[58:61], v[134:137], v[214:217], v[58:61]
	v_mfma_i32_16x16x64_i8 v[26:29], v[162:165], v[210:213], v[26:29]
	v_mfma_i32_16x16x64_i8 v[26:29], v[166:169], v[214:217], v[26:29]
	v_mfma_i32_16x16x64_i8 v[46:49], v[170:173], v[186:189], v[46:49]
	v_mfma_i32_16x16x64_i8 v[46:49], v[174:177], v[190:193], v[46:49]
	v_mfma_i32_16x16x64_i8 v[14:17], v[178:181], v[186:189], v[14:17]
	v_mfma_i32_16x16x64_i8 v[14:17], v[182:185], v[190:193], v[14:17]
	v_mfma_i32_16x16x64_i8 v[42:45], v[170:173], v[194:197], v[42:45]
	v_mfma_i32_16x16x64_i8 v[42:45], v[174:177], v[198:201], v[42:45]
	v_mfma_i32_16x16x64_i8 v[10:13], v[178:181], v[194:197], v[10:13]
	v_mfma_i32_16x16x64_i8 v[10:13], v[182:185], v[198:201], v[10:13]
	v_mfma_i32_16x16x64_i8 v[38:41], v[170:173], v[202:205], v[38:41]
	v_mfma_i32_16x16x64_i8 v[38:41], v[174:177], v[206:209], v[38:41]
	v_mfma_i32_16x16x64_i8 v[6:9], v[178:181], v[202:205], v[6:9]
	v_mfma_i32_16x16x64_i8 v[6:9], v[182:185], v[206:209], v[6:9]
	v_mfma_i32_16x16x64_i8 v[34:37], v[170:173], v[210:213], v[34:37]
	v_mfma_i32_16x16x64_i8 v[34:37], v[174:177], v[214:217], v[34:37]
	v_mfma_i32_16x16x64_i8 v[2:5], v[178:181], v[210:213], v[2:5]
	v_mfma_i32_16x16x64_i8 v[2:5], v[182:185], v[214:217], v[2:5]
	s_barrier
	s_add_i32 s93, s93, 2
	s_add_u32 s91, s91, 0x100
	s_addc_u32 s92, s92, 0
	s_cmp_gt_u32 s93, 29
	s_mov_b64 s[2:3], s[4:5]

.LBB0_2240:
	s_add_u32 s69, s36, 0x100
	s_addc_u32 s70, s37, 0
	s_mov_b32 s71, -2
	ds_read_b128 v[130:133], v212
	ds_read_b128 v[134:137], v212 offset:1024
	ds_read_b128 v[138:141], v212 offset:2048
	ds_read_b128 v[142:145], v212 offset:3072
	ds_read_b128 v[146:149], v213
	ds_read_b128 v[150:153], v213 offset:1024
	ds_read_b128 v[154:157], v213 offset:2048
	ds_read_b128 v[158:161], v213 offset:3072
	s_add_u32 s36, s18, 0x100
	s_addc_u32 s37, s19, 0
	s_cmpk_eq_i32 s71, 0xdc
	s_cselect_b32 s41, s3, s37
	s_cselect_b32 s40, s2, s36
	s_cselect_b32 s39, s35, s70
	s_cselect_b32 s38, s34, s69
	v_lshl_add_u64 v[216:217], s[18:19], 0, v[178:179]
	s_add_i32 m0, s44, 0xc000
	ds_read_b128 v[162:165], v214
	ds_read_b128 v[166:169], v214 offset:1024
	ds_read_b128 v[186:189], v214 offset:2048
	ds_read_b128 v[190:193], v214 offset:3072
	ds_read_b128 v[194:197], v214 offset:4096
	ds_read_b128 v[198:201], v214 offset:5120
	ds_read_b128 v[202:205], v214 offset:6144
	ds_read_b128 v[206:209], v214 offset:7168
	global_load_lds_dwordx4 v[216:217], off
	v_lshl_add_u64 v[216:217], s[18:19], 0, v[180:181]
	s_add_i32 m0, s44, 0xe000
	s_nop 0
	global_load_lds_dwordx4 v[216:217], off
	s_waitcnt vmcnt(8)
	s_waitcnt lgkmcnt(0)
	s_barrier
	s_waitcnt lgkmcnt(0)
	v_mfma_f32_16x16x32_bf16 v[126:129], v[130:133], v[162:165], 0
	v_mfma_f32_16x16x32_bf16 v[126:129], v[134:137], v[166:169], v[126:129]
	v_mfma_f32_16x16x32_bf16 v[122:125], v[138:141], v[162:165], 0
	v_mfma_f32_16x16x32_bf16 v[122:125], v[142:145], v[166:169], v[122:125]
	v_mfma_f32_16x16x32_bf16 v[110:113], v[130:133], v[186:189], 0
	v_mfma_f32_16x16x32_bf16 v[110:113], v[134:137], v[190:193], v[110:113]
	v_mfma_f32_16x16x32_bf16 v[106:109], v[138:141], v[186:189], 0
	v_mfma_f32_16x16x32_bf16 v[106:109], v[142:145], v[190:193], v[106:109]
	v_mfma_f32_16x16x32_bf16 v[94:97], v[130:133], v[194:197], 0
	v_mfma_f32_16x16x32_bf16 v[94:97], v[134:137], v[198:201], v[94:97]
	v_mfma_f32_16x16x32_bf16 v[90:93], v[138:141], v[194:197], 0
	v_mfma_f32_16x16x32_bf16 v[90:93], v[142:145], v[198:201], v[90:93]
	v_mfma_f32_16x16x32_bf16 v[78:81], v[130:133], v[202:205], 0
	v_mfma_f32_16x16x32_bf16 v[78:81], v[134:137], v[206:209], v[78:81]
	v_mfma_f32_16x16x32_bf16 v[74:77], v[138:141], v[202:205], 0
	v_mfma_f32_16x16x32_bf16 v[74:77], v[142:145], v[206:209], v[74:77]
	v_mfma_f32_16x16x32_bf16 v[118:121], v[146:149], v[162:165], 0
	v_mfma_f32_16x16x32_bf16 v[118:121], v[150:153], v[166:169], v[118:121]
	v_mfma_f32_16x16x32_bf16 v[114:117], v[154:157], v[162:165], 0
	v_mfma_f32_16x16x32_bf16 v[114:117], v[158:161], v[166:169], v[114:117]
	v_mfma_f32_16x16x32_bf16 v[102:105], v[146:149], v[186:189], 0
	v_mfma_f32_16x16x32_bf16 v[102:105], v[150:153], v[190:193], v[102:105]
	v_mfma_f32_16x16x32_bf16 v[98:101], v[154:157], v[186:189], 0
	v_mfma_f32_16x16x32_bf16 v[98:101], v[158:161], v[190:193], v[98:101]
	v_mfma_f32_16x16x32_bf16 v[86:89], v[146:149], v[194:197], 0
	v_mfma_f32_16x16x32_bf16 v[86:89], v[150:153], v[198:201], v[86:89]
	v_mfma_f32_16x16x32_bf16 v[82:85], v[154:157], v[194:197], 0
	v_mfma_f32_16x16x32_bf16 v[82:85], v[158:161], v[198:201], v[82:85]
	v_mfma_f32_16x16x32_bf16 v[70:73], v[146:149], v[202:205], 0
	v_mfma_f32_16x16x32_bf16 v[70:73], v[150:153], v[206:209], v[70:73]
	v_mfma_f32_16x16x32_bf16 v[66:69], v[154:157], v[202:205], 0
	v_mfma_f32_16x16x32_bf16 v[66:69], v[158:161], v[206:209], v[66:69]
	s_barrier
	s_add_i32 s18, s56, s43
	v_lshl_add_u64 v[216:217], s[38:39], 0, v[172:173]
	s_mov_b32 m0, s18
	ds_read_b128 v[162:165], v214 offset:16384
	ds_read_b128 v[166:169], v214 offset:17408
	ds_read_b128 v[186:189], v214 offset:18432
	ds_read_b128 v[190:193], v214 offset:19456
	ds_read_b128 v[194:197], v214 offset:20480
	ds_read_b128 v[198:201], v214 offset:21504
	ds_read_b128 v[202:205], v214 offset:22528
	ds_read_b128 v[206:209], v214 offset:23552
	global_load_lds_dwordx4 v[216:217], off
	s_add_i32 m0, s18, 0x2000
	s_add_u32 s18, s38, 0x380000
	v_lshl_add_u64 v[218:219], s[38:39], 0, v[176:177]
	s_addc_u32 s19, s39, 0
	s_add_i32 s72, s57, s43
	global_load_lds_dwordx4 v[218:219], off
	v_lshl_add_u64 v[220:221], s[18:19], 0, v[172:173]
	s_mov_b32 m0, s72
	v_lshl_add_u64 v[222:223], s[40:41], 0, v[174:175]
	global_load_lds_dwordx4 v[220:221], off
	v_lshl_add_u64 v[220:221], s[18:19], 0, v[176:177]
	s_add_i32 m0, s72, 0x2000
	s_nop 0
	global_load_lds_dwordx4 v[220:221], off
	v_lshl_add_u64 v[220:221], s[40:41], 0, v[170:171]
	s_mov_b32 m0, s44
	s_nop 0
	global_load_lds_dwordx4 v[220:221], off
	s_mov_b32 m0, s45
	s_nop 0
	global_load_lds_dwordx4 v[222:223], off
	s_waitcnt vmcnt(8)
	s_waitcnt lgkmcnt(0)
	s_barrier
	s_waitcnt lgkmcnt(0)
	v_mfma_f32_16x16x32_bf16 v[62:65], v[130:133], v[162:165], 0
	v_mfma_f32_16x16x32_bf16 v[62:65], v[134:137], v[166:169], v[62:65]
	v_mfma_f32_16x16x32_bf16 v[58:61], v[138:141], v[162:165], 0
	v_mfma_f32_16x16x32_bf16 v[58:61], v[142:145], v[166:169], v[58:61]
	v_mfma_f32_16x16x32_bf16 v[46:49], v[130:133], v[186:189], 0
	v_mfma_f32_16x16x32_bf16 v[46:49], v[134:137], v[190:193], v[46:49]
	v_mfma_f32_16x16x32_bf16 v[42:45], v[138:141], v[186:189], 0
	v_mfma_f32_16x16x32_bf16 v[42:45], v[142:145], v[190:193], v[42:45]
	v_mfma_f32_16x16x32_bf16 v[30:33], v[130:133], v[194:197], 0
	v_mfma_f32_16x16x32_bf16 v[30:33], v[134:137], v[198:201], v[30:33]
	v_mfma_f32_16x16x32_bf16 v[26:29], v[138:141], v[194:197], 0
	v_mfma_f32_16x16x32_bf16 v[26:29], v[142:145], v[198:201], v[26:29]
	v_mfma_f32_16x16x32_bf16 v[14:17], v[130:133], v[202:205], 0
	v_mfma_f32_16x16x32_bf16 v[14:17], v[134:137], v[206:209], v[14:17]
	v_mfma_f32_16x16x32_bf16 v[10:13], v[138:141], v[202:205], 0
	v_mfma_f32_16x16x32_bf16 v[10:13], v[142:145], v[206:209], v[10:13]
	v_mfma_f32_16x16x32_bf16 v[54:57], v[146:149], v[162:165], 0
	v_mfma_f32_16x16x32_bf16 v[54:57], v[150:153], v[166:169], v[54:57]
	v_mfma_f32_16x16x32_bf16 v[50:53], v[154:157], v[162:165], 0
	v_mfma_f32_16x16x32_bf16 v[50:53], v[158:161], v[166:169], v[50:53]
	v_mfma_f32_16x16x32_bf16 v[38:41], v[146:149], v[186:189], 0
	v_mfma_f32_16x16x32_bf16 v[38:41], v[150:153], v[190:193], v[38:41]
	v_mfma_f32_16x16x32_bf16 v[34:37], v[154:157], v[186:189], 0
	v_mfma_f32_16x16x32_bf16 v[34:37], v[158:161], v[190:193], v[34:37]
	v_mfma_f32_16x16x32_bf16 v[22:25], v[146:149], v[194:197], 0
	v_mfma_f32_16x16x32_bf16 v[22:25], v[150:153], v[198:201], v[22:25]
	v_mfma_f32_16x16x32_bf16 v[18:21], v[154:157], v[194:197], 0
	v_mfma_f32_16x16x32_bf16 v[18:21], v[158:161], v[198:201], v[18:21]
	v_mfma_f32_16x16x32_bf16 v[6:9], v[146:149], v[202:205], 0
	v_mfma_f32_16x16x32_bf16 v[6:9], v[150:153], v[206:209], v[6:9]
	v_mfma_f32_16x16x32_bf16 v[2:5], v[154:157], v[202:205], 0
	v_mfma_f32_16x16x32_bf16 v[2:5], v[158:161], v[206:209], v[2:5]
	s_barrier
	s_add_i32 s72, 0, 0x18000
	s_add_i32 s73, 0, 0x1c000
	v_add_u32_e32 v142, s72, v211
	v_add_u32_e32 v158, s73, v211
	ds_read_b128 v[130:133], v142
	ds_read_b128 v[134:137], v142 offset:1024
	ds_read_b128 v[138:141], v142 offset:2048
	ds_read_b128 v[142:145], v142 offset:3072
	ds_read_b128 v[146:149], v158
	ds_read_b128 v[150:153], v158 offset:1024
	ds_read_b128 v[154:157], v158 offset:2048
	ds_read_b128 v[158:161], v158 offset:3072
	s_add_u32 s18, s40, 0x380000
	s_addc_u32 s19, s41, 0
	s_mov_b32 m0, s46
	v_lshl_add_u64 v[224:225], s[18:19], 0, v[170:171]
	ds_read_b128 v[162:165], v214 offset:32768
	ds_read_b128 v[166:169], v214 offset:33792
	ds_read_b128 v[186:189], v214 offset:34816
	ds_read_b128 v[190:193], v214 offset:35840
	ds_read_b128 v[194:197], v214 offset:36864
	ds_read_b128 v[198:201], v214 offset:37888
	ds_read_b128 v[202:205], v214 offset:38912
	ds_read_b128 v[206:209], v214 offset:39936
	global_load_lds_dwordx4 v[224:225], off
	v_lshl_add_u64 v[224:225], s[18:19], 0, v[174:175]
	s_mov_b32 m0, s47
	s_nop 0
	global_load_lds_dwordx4 v[224:225], off
	s_waitcnt vmcnt(8)
	s_waitcnt lgkmcnt(0)
	s_barrier
	s_waitcnt lgkmcnt(0)
	v_mfma_f32_16x16x32_bf16 v[126:129], v[130:133], v[162:165], v[126:129]
	v_mfma_f32_16x16x32_bf16 v[126:129], v[134:137], v[166:169], v[126:129]
	v_mfma_f32_16x16x32_bf16 v[122:125], v[138:141], v[162:165], v[122:125]
	v_mfma_f32_16x16x32_bf16 v[122:125], v[142:145], v[166:169], v[122:125]
	v_mfma_f32_16x16x32_bf16 v[110:113], v[130:133], v[186:189], v[110:113]
	v_mfma_f32_16x16x32_bf16 v[110:113], v[134:137], v[190:193], v[110:113]
	v_mfma_f32_16x16x32_bf16 v[106:109], v[138:141], v[186:189], v[106:109]
	v_mfma_f32_16x16x32_bf16 v[106:109], v[142:145], v[190:193], v[106:109]
	v_mfma_f32_16x16x32_bf16 v[94:97], v[130:133], v[194:197], v[94:97]
	v_mfma_f32_16x16x32_bf16 v[94:97], v[134:137], v[198:201], v[94:97]
	v_mfma_f32_16x16x32_bf16 v[90:93], v[138:141], v[194:197], v[90:93]
	v_mfma_f32_16x16x32_bf16 v[90:93], v[142:145], v[198:201], v[90:93]
	v_mfma_f32_16x16x32_bf16 v[78:81], v[130:133], v[202:205], v[78:81]
	v_mfma_f32_16x16x32_bf16 v[78:81], v[134:137], v[206:209], v[78:81]
	v_mfma_f32_16x16x32_bf16 v[74:77], v[138:141], v[202:205], v[74:77]
	v_mfma_f32_16x16x32_bf16 v[74:77], v[142:145], v[206:209], v[74:77]
	v_mfma_f32_16x16x32_bf16 v[118:121], v[146:149], v[162:165], v[118:121]
	v_mfma_f32_16x16x32_bf16 v[118:121], v[150:153], v[166:169], v[118:121]
	v_mfma_f32_16x16x32_bf16 v[114:117], v[154:157], v[162:165], v[114:117]
	v_mfma_f32_16x16x32_bf16 v[114:117], v[158:161], v[166:169], v[114:117]
	v_mfma_f32_16x16x32_bf16 v[102:105], v[146:149], v[186:189], v[102:105]
	v_mfma_f32_16x16x32_bf16 v[102:105], v[150:153], v[190:193], v[102:105]
	v_mfma_f32_16x16x32_bf16 v[98:101], v[154:157], v[186:189], v[98:101]
	v_mfma_f32_16x16x32_bf16 v[98:101], v[158:161], v[190:193], v[98:101]
	v_mfma_f32_16x16x32_bf16 v[86:89], v[146:149], v[194:197], v[86:89]
	v_mfma_f32_16x16x32_bf16 v[86:89], v[150:153], v[198:201], v[86:89]
	v_mfma_f32_16x16x32_bf16 v[82:85], v[154:157], v[194:197], v[82:85]
	v_mfma_f32_16x16x32_bf16 v[82:85], v[158:161], v[198:201], v[82:85]
	v_mfma_f32_16x16x32_bf16 v[70:73], v[146:149], v[202:205], v[70:73]
	v_mfma_f32_16x16x32_bf16 v[70:73], v[150:153], v[206:209], v[70:73]
	v_mfma_f32_16x16x32_bf16 v[66:69], v[154:157], v[202:205], v[66:69]
	v_mfma_f32_16x16x32_bf16 v[66:69], v[158:161], v[206:209], v[66:69]
	s_barrier
	s_add_i32 s18, s72, s43
	v_lshl_add_u64 v[216:217], v[216:217], 0, s[8:9]
	s_mov_b32 m0, s18
	ds_read_b128 v[162:165], v214 offset:49152
	ds_read_b128 v[166:169], v214 offset:50176
	ds_read_b128 v[186:189], v214 offset:51200
	ds_read_b128 v[190:193], v214 offset:52224
	ds_read_b128 v[194:197], v214 offset:53248
	ds_read_b128 v[198:201], v214 offset:54272
	ds_read_b128 v[202:205], v214 offset:55296
	ds_read_b128 v[206:209], v214 offset:56320
	global_load_lds_dwordx4 v[216:217], off
	s_add_i32 m0, s18, 0x2000
	s_add_u32 s18, s38, 0x380080
	v_lshl_add_u64 v[216:217], v[218:219], 0, s[8:9]
	s_addc_u32 s19, s39, 0
	s_add_i32 s38, s73, s43
	global_load_lds_dwordx4 v[216:217], off
	v_lshl_add_u64 v[216:217], s[18:19], 0, v[172:173]
	s_mov_b32 m0, s38
	s_nop 0
	global_load_lds_dwordx4 v[216:217], off
	v_lshl_add_u64 v[216:217], s[18:19], 0, v[176:177]
	s_add_i32 m0, s38, 0x2000
	s_nop 0
	global_load_lds_dwordx4 v[216:217], off
	v_lshl_add_u64 v[216:217], v[220:221], 0, s[8:9]
	s_mov_b32 m0, s51
	s_nop 0
	global_load_lds_dwordx4 v[216:217], off
	v_lshl_add_u64 v[216:217], v[222:223], 0, s[8:9]
	s_mov_b32 m0, s54
	s_nop 0
	global_load_lds_dwordx4 v[216:217], off
	s_waitcnt vmcnt(8)
	s_waitcnt lgkmcnt(0)
	s_barrier
	s_waitcnt lgkmcnt(0)
	v_mfma_f32_16x16x32_bf16 v[62:65], v[130:133], v[162:165], v[62:65]
	v_mfma_f32_16x16x32_bf16 v[62:65], v[134:137], v[166:169], v[62:65]
	v_mfma_f32_16x16x32_bf16 v[58:61], v[138:141], v[162:165], v[58:61]
	v_mfma_f32_16x16x32_bf16 v[58:61], v[142:145], v[166:169], v[58:61]
	v_mfma_f32_16x16x32_bf16 v[46:49], v[130:133], v[186:189], v[46:49]
	v_mfma_f32_16x16x32_bf16 v[46:49], v[134:137], v[190:193], v[46:49]
	v_mfma_f32_16x16x32_bf16 v[42:45], v[138:141], v[186:189], v[42:45]
	v_mfma_f32_16x16x32_bf16 v[42:45], v[142:145], v[190:193], v[42:45]
	v_mfma_f32_16x16x32_bf16 v[30:33], v[130:133], v[194:197], v[30:33]
	v_mfma_f32_16x16x32_bf16 v[30:33], v[134:137], v[198:201], v[30:33]
	v_mfma_f32_16x16x32_bf16 v[26:29], v[138:141], v[194:197], v[26:29]
	v_mfma_f32_16x16x32_bf16 v[26:29], v[142:145], v[198:201], v[26:29]
	v_mfma_f32_16x16x32_bf16 v[14:17], v[130:133], v[202:205], v[14:17]
	v_mfma_f32_16x16x32_bf16 v[14:17], v[134:137], v[206:209], v[14:17]
	v_mfma_f32_16x16x32_bf16 v[10:13], v[138:141], v[202:205], v[10:13]
	v_mfma_f32_16x16x32_bf16 v[10:13], v[142:145], v[206:209], v[10:13]
	v_mfma_f32_16x16x32_bf16 v[54:57], v[146:149], v[162:165], v[54:57]
	v_mfma_f32_16x16x32_bf16 v[54:57], v[150:153], v[166:169], v[54:57]
	v_mfma_f32_16x16x32_bf16 v[50:53], v[154:157], v[162:165], v[50:53]
	v_mfma_f32_16x16x32_bf16 v[50:53], v[158:161], v[166:169], v[50:53]
	v_mfma_f32_16x16x32_bf16 v[38:41], v[146:149], v[186:189], v[38:41]
	v_mfma_f32_16x16x32_bf16 v[38:41], v[150:153], v[190:193], v[38:41]
	v_mfma_f32_16x16x32_bf16 v[34:37], v[154:157], v[186:189], v[34:37]
	v_mfma_f32_16x16x32_bf16 v[34:37], v[158:161], v[190:193], v[34:37]
	v_mfma_f32_16x16x32_bf16 v[22:25], v[146:149], v[194:197], v[22:25]
	v_mfma_f32_16x16x32_bf16 v[22:25], v[150:153], v[198:201], v[22:25]
	v_mfma_f32_16x16x32_bf16 v[18:21], v[154:157], v[194:197], v[18:21]
	v_mfma_f32_16x16x32_bf16 v[18:21], v[158:161], v[198:201], v[18:21]
	v_mfma_f32_16x16x32_bf16 v[6:9], v[146:149], v[202:205], v[6:9]
	v_mfma_f32_16x16x32_bf16 v[6:9], v[150:153], v[206:209], v[6:9]
	v_mfma_f32_16x16x32_bf16 v[2:5], v[154:157], v[202:205], v[2:5]
	v_mfma_f32_16x16x32_bf16 v[2:5], v[158:161], v[206:209], v[2:5]
	s_barrier
	s_add_i32 s71, s71, 2
	s_add_u32 s69, s69, 0x100
	s_addc_u32 s70, s70, 0
	s_cmpk_gt_u32 s71, 0xdd
	s_mov_b64 s[18:19], s[36:37]
